# static s_setprio 1 for waves 4-7 at kernel entry, per-cluster priority flips in the GEMM phases removed
# speedup vs baseline: 1.0190x; 1.0055x over previous
; #define LAS __attribute__((address_space(3)))
; __device__ __forceinline__ unsigned xb_add(unsigned* p, unsigned v) { return __hip_atomic_fetch_add(p, v, __ATOMIC_RELAXED, __HIP_MEMORY_SCOPE_AGENT); }
; __device__ __forceinline__ unsigned xb_xcc_id() { return (unsigned)__builtin_amdgcn_s_getreg((3 << 11) | 20) & 0xFu; }
; __device__ __forceinline__ void convert_layer(const Ctx& C, int l) {
;     LAS float* scr = (LAS float*)(C.lds + C.wave * 8448);
;     gu8* ws = C.ws; const int lane = C.lane;
;     constexpr int NITEMS = 2816 + 1408 + 1792 + 1536 + 768 + 512 + 2816 + 1408 + 256 + 256 + 512;
;     for (int it = C.gw; it < NITEMS; it += C.NGW) {
;         int r = it;
;         if (r < 2816) { const int kb = r / 176, nb = r % 176, tile = nb >> 3, w = nb & 7, src = (w >> 2) * FF + tile * 128 + (w & 3) * 32;
; __global__ void __launch_bounds__(NWAVES * 64, 2) fwd_kernel(Args args) {
;     ...
;     const int wave0 = __builtin_amdgcn_readfirstlane((int)threadIdx.x >> 6);
;     {
;         volatile LAS unsigned* st = (volatile LAS unsigned*)(lds_raw + XB_LDS_OFF);
;         if (threadIdx.x == 0) { st[0] = 0u; st[1] = 0u; (void)xb_add((unsigned*)(args.ws + WS_BAR) + XB_XCNT(xb_xcc_id()), 1u); }
;         __syncthreads();
;     }
.LBB0_17:
	s_or_b64 exec, exec, s[0:1]
	v_readlane_b32 s20, v253, 0
	v_readlane_b32 s21, v253, 1
	s_cmp_ge_u32 s88, 0x100
	s_cbranch_scc0 .Lprio_skip
	s_setprio 1
.Lprio_skip:
	s_and_b32 s0, s88, 0xffffffc0
	s_waitcnt lgkmcnt(0)
	s_barrier
	v_mbcnt_lo_u32_b32 v66, -1, 0
	v_mbcnt_hi_u32_b32 v66, -1, v66
	s_mov_b32 s1, s35
	v_add_u32_e32 v0, s0, v66
	v_writelane_b32 v253, s0, 46
	v_readfirstlane_b32 s0, v0
	s_ashr_i32 s0, s0, 6
	s_lshl_b32 s1, s1, 3
	v_and_b32_e32 v67, 63, v66
	s_add_i32 s22, s1, s0
	s_lshl_b32 s70, s68, 3
	s_cmpk_gt_i32 s22, 0x36ff
	v_lshlrev_b32_e32 v0, 3, v67
	s_cbranch_scc1 .LBB0_106
	v_and_b32_e32 v46, 56, v0
	v_mov_b32_e32 v9, 0
	v_lshlrev_b32_e32 v8, 1, v46
	s_mul_i32 s4, s0, 0x2100
	v_lshl_add_u64 v[10:11], s[20:21], 0, v[8:9]
	s_mov_b64 s[0:1], 0x3500000
	v_lshl_add_u64 v[12:13], v[10:11], 0, s[0:1]
	s_mov_b64 s[0:1], 0x3400000
	v_lshl_add_u64 v[14:15], v[10:11], 0, s[0:1]
	s_mov_b64 s[0:1], 0x3300000
	v_lshl_add_u64 v[16:17], v[10:11], 0, s[0:1]
	s_mov_b64 s[0:1], 0x2d80000
	v_and_b32_e32 v4, 31, v66
	v_lshrrev_b32_e32 v3, 3, v67
	v_lshl_add_u64 v[18:19], v[10:11], 0, s[0:1]
	s_mov_b64 s[0:1], 0x2280000
	v_readlane_b32 s36, v253, 30
	v_readlane_b32 s12, v253, 2
	s_add_i32 s2, s4, 0
	v_lshrrev_b32_e32 v2, 5, v67
	v_lshlrev_b32_e32 v44, 2, v4
	v_mul_u32_u24_e32 v1, 0x84, v46
	v_lshlrev_b32_e32 v5, 2, v3
	v_lshl_add_u64 v[20:21], v[10:11], 0, s[0:1]
	s_mov_b64 s[0:1], 0x2080000
	v_mov_b32_e32 v45, v9
	v_readlane_b32 s37, v253, 31
	v_readlane_b32 s38, v253, 32
	v_readlane_b32 s39, v253, 33
	v_readlane_b32 s40, v253, 34
	v_readlane_b32 s41, v253, 35
	v_readlane_b32 s42, v253, 36
	v_readlane_b32 s43, v253, 37
	v_readlane_b32 s44, v253, 38
	v_readlane_b32 s45, v253, 39
	v_readlane_b32 s46, v253, 40
	v_readlane_b32 s47, v253, 41
	v_readlane_b32 s48, v253, 42
	v_readlane_b32 s49, v253, 43
	v_readlane_b32 s50, v253, 44
	v_readlane_b32 s51, v253, 45
	v_readlane_b32 s13, v253, 3
	v_readlane_b32 s14, v253, 4
	v_readlane_b32 s15, v253, 5
	v_add3_u32 v5, s2, v1, v5
	v_lshl_add_u64 v[22:23], v[10:11], 0, s[0:1]
	s_mov_b64 s[0:1], 0x1780000
	v_lshl_add_u64 v[28:29], s[44:45], 0, v[44:45]
	v_lshl_add_u64 v[30:31], s[38:39], 0, v[44:45]
	v_readlane_b32 s36, v253, 14
	v_lshl_add_u64 v[34:35], s[12:13], 0, v[44:45]
	v_readlane_b32 s12, v253, 6
	v_mul_u32_u24_e32 v1, 0x84, v2
	v_add_u32_e32 v6, s2, v44
	s_add_u32 s9, s20, 0x1d80000
	v_lshl_add_u64 v[24:25], v[10:11], 0, s[0:1]
	s_mov_b64 s[0:1], 0x1080000
	s_mov_b64 s[2:3], 0xb00000
	v_readlane_b32 s40, v253, 18
	v_readlane_b32 s41, v253, 19
	v_readlane_b32 s48, v253, 26
	v_readlane_b32 s49, v253, 27
	v_readlane_b32 s13, v253, 7
	v_readlane_b32 s18, v253, 12
	v_readlane_b32 s19, v253, 13
	v_or_b32_e32 v1, s4, v1
	s_mov_b32 s25, 0
	s_movk_i32 s8, 0x84
	v_or_b32_e32 v7, 8, v3
	v_or_b32_e32 v68, 16, v3
	v_or_b32_e32 v69, 24, v3
	s_addc_u32 s10, s21, 0
	v_lshl_add_u64 v[26:27], v[10:11], 0, s[0:1]
	v_cmp_gt_u32_e64 s[0:1], 24, v4
	v_lshl_add_u64 v[32:33], s[48:49], 0, v[44:45]
	v_lshl_add_u64 v[36:37], s[18:19], 0, v[44:45]
	v_lshl_add_u64 v[38:39], s[12:13], 0, v[44:45]
	v_lshl_add_u64 v[40:41], s[84:85], 0, v[44:45]
	v_lshl_add_u64 v[42:43], s[82:83], 0, v[44:45]
	v_add3_u32 v70, v1, v44, 0
	v_lshl_add_u64 v[44:45], s[40:41], 0, v[44:45]
	v_or_b32_e32 v71, 14, v2
	v_or_b32_e32 v72, 12, v2
	v_or_b32_e32 v73, 10, v2
	v_or_b32_e32 v74, 8, v2
	s_movk_i32 s11, 0x5800
	v_lshlrev_b32_e32 v46, 1, v46
	v_or_b32_e32 v75, 6, v2
	s_movk_i32 s12, 0x6460
	v_or_b32_e32 v76, 4, v2
	s_mov_b32 s13, s22
	v_or_b32_e32 v77, 2, v2
	v_lshl_add_u64 v[48:49], v[10:11], 0, s[2:3]
	v_mov_b32_e32 v1, v2
	v_readlane_b32 s37, v253, 15
	v_readlane_b32 s38, v253, 16
	v_readlane_b32 s39, v253, 17
	v_readlane_b32 s42, v253, 20
	v_readlane_b32 s43, v253, 21
	v_readlane_b32 s44, v253, 22
	v_readlane_b32 s45, v253, 23
	v_readlane_b32 s46, v253, 24
	v_readlane_b32 s47, v253, 25
	v_readlane_b32 s50, v253, 28
	v_readlane_b32 s51, v253, 29
	v_readlane_b32 s14, v253, 8
	v_readlane_b32 s15, v253, 9
	v_readlane_b32 s16, v253, 10
	v_readlane_b32 s17, v253, 11
	s_branch .LBB0_20

; #define PG8_STAGE(bufoff, gbase, voff) do { _Pragma("unroll") for (int _i = 0; _i < 2; ++_i) \
;         __builtin_amdgcn_global_load_lds((const unsigned*)((const char*)(gbase) + (voff)[_i]), (LAS unsigned*)(lds + (bufoff) + ldsw + _i * 8192), 16, 0, 0); } while (0)
; #define PG8_LDA(dst, b, h) do { _Pragma("unroll") for (int m = 0; m < 4; ++m) _Pragma("unroll") for (int k = 0; k < 2; ++k) dst[m][k] = *(const LAS bf16x8*)(lds + PG8_SA(b, h) + aoff + m * 2048 + k * 1024); } while (0)
; #define PG8_WAIT_V(n) asm volatile("s_waitcnt vmcnt(" #n ")" ::: "memory")
; #define PG8_WAIT_L(n) asm volatile("s_waitcnt lgkmcnt(" #n ")" ::: "memory")
; #define PG8_BAR __builtin_amdgcn_s_barrier()
; template <class EpiT, class Sched>
; __device__ __forceinline__ void gemm_phase(LAS unsigned char* lds, int tid_in, const GemmDesc g, const Sched& S, const EpiT& E) {
;     ...
;     for (;;) {
;         const bool has_next = S.next(ui + 1, nxt);
;         const char* nA = has_next ? g.A + nxt.aoff : cA; const char* nB = has_next ? g.Bt + nxt.boff : cB;
;         for (int t = 0; t < nt; t += 2) {
;             const bool last = (t == nt - 2);
;             const char* a1 = cA + (size_t)(t + 1) * kA;
;             const char* a2 = last ? nA : cA + (size_t)(t + 2) * kA; const char* b2 = last ? nB : cB + (size_t)(t + 2) * kB;
;             const char* a3 = a2 + kA; const char* b3 = b2 + kB;
;             PG8_LDB(B0, 0, 0); PG8_LDB(B1, 0, 1); PG8_SCHED; PG8_LDA(At, 0, 0); PG8_STAGE(PG8_SA(1, 1), a1 + hA, voffA);
;             PG8_WAIT_V(8); PG8_WAIT_L(0); PG8_BAR; PG8_MMA(0, 0, At, B0); PG8_MMA(0, 1, At, B1); PG8_BAR; PG8_SCHED;
;             PG8_LDA(At, 0, 1); PG8_STAGE(PG8_SB(0, 0), b2, voffB); PG8_STAGE(PG8_SB(0, 1), b2 + hB, voffB); PG8_STAGE(PG8_SA(0, 0), a2, voffA);
;             PG8_WAIT_V(8); PG8_WAIT_L(0); PG8_BAR; PG8_MMA(1, 0, At, B0); PG8_MMA(1, 1, At, B1); PG8_BAR; PG8_SCHED;
;             PG8_LDB(B0, 1, 0); PG8_LDB(B1, 1, 1); PG8_SCHED; PG8_LDA(At, 1, 0); PG8_STAGE(PG8_SA(0, 1), a2 + hA, voffA);
;             PG8_WAIT_V(8); PG8_WAIT_L(0); PG8_BAR; PG8_MMA(0, 0, At, B0); PG8_MMA(0, 1, At, B1); PG8_BAR; PG8_SCHED;
;             PG8_LDA(At, 1, 1); PG8_STAGE(PG8_SB(1, 0), b3, voffB); PG8_STAGE(PG8_SB(1, 1), b3 + hB, voffB); PG8_STAGE(PG8_SA(1, 0), a3, voffA);
;             PG8_WAIT_V(8); PG8_WAIT_L(0); PG8_BAR; PG8_MMA(1, 0, At, B0); PG8_MMA(1, 1, At, B1); PG8_BAR; PG8_SCHED;
.LBB0_187:
	s_add_u32 s10, vcc_lo, 0xfffc0080
	s_addc_u32 s11, vcc_hi, -1
	s_add_i32 s63, 0, 0x10000
	s_cmp_eq_u32 s62, 12
	s_cselect_b32 s95, s2, s11
	s_cselect_b32 s94, s3, s10
	v_add_u32_e32 v140, s63, v143
	s_cselect_b32 s93, s58, s80
	s_cselect_b32 s92, s59, s79
	s_add_i32 s81, 0, 0x14000
	ds_read_b128 v[146:149], v140
	ds_read_b128 v[150:153], v140 offset:1024
	ds_read_b128 v[154:157], v140 offset:2048
	ds_read_b128 v[158:161], v140 offset:3072
	v_add_u32_e32 v140, s81, v143
	ds_read_b128 v[162:165], v140
	ds_read_b128 v[166:169], v140 offset:1024
	ds_read_b128 v[170:173], v140 offset:2048
	ds_read_b128 v[174:177], v140 offset:3072
	v_lshl_add_u64 v[140:141], vcc, 0, v[136:137]
	s_add_i32 m0, s73, 0xc000
	ds_read_b128 v[178:181], v145
	ds_read_b128 v[182:185], v145 offset:1024
	ds_read_b128 v[186:189], v145 offset:2048
	ds_read_b128 v[190:193], v145 offset:3072
	ds_read_b128 v[194:197], v145 offset:4096
	ds_read_b128 v[198:201], v145 offset:5120
	ds_read_b128 v[202:205], v145 offset:6144
	ds_read_b128 v[206:209], v145 offset:7168
	global_load_lds_dwordx4 v[140:141], off
	v_lshl_add_u64 v[140:141], vcc, 0, v[138:139]
	s_add_i32 m0, s73, 0xe000
	s_nop 0
	global_load_lds_dwordx4 v[140:141], off
	s_waitcnt vmcnt(8)
	s_waitcnt lgkmcnt(0)
	s_barrier
	s_waitcnt lgkmcnt(0)
	v_mfma_f32_16x16x32_bf16 v[126:129], v[146:149], v[178:181], v[126:129]
	v_mfma_f32_16x16x32_bf16 v[118:121], v[154:157], v[178:181], v[118:121]
	v_mfma_f32_16x16x32_bf16 v[110:113], v[146:149], v[186:189], v[110:113]
	v_mfma_f32_16x16x32_bf16 v[102:105], v[154:157], v[186:189], v[102:105]
	v_mfma_f32_16x16x32_bf16 v[94:97], v[146:149], v[194:197], v[94:97]
	v_mfma_f32_16x16x32_bf16 v[86:89], v[154:157], v[194:197], v[86:89]
	v_mfma_f32_16x16x32_bf16 v[78:81], v[146:149], v[202:205], v[78:81]
	v_mfma_f32_16x16x32_bf16 v[70:73], v[154:157], v[202:205], v[70:73]
	v_mfma_f32_16x16x32_bf16 v[126:129], v[150:153], v[182:185], v[126:129]
	v_mfma_f32_16x16x32_bf16 v[118:121], v[158:161], v[182:185], v[118:121]
	v_mfma_f32_16x16x32_bf16 v[110:113], v[150:153], v[190:193], v[110:113]
	v_mfma_f32_16x16x32_bf16 v[102:105], v[158:161], v[190:193], v[102:105]
	v_mfma_f32_16x16x32_bf16 v[94:97], v[150:153], v[198:201], v[94:97]
	v_mfma_f32_16x16x32_bf16 v[86:89], v[158:161], v[198:201], v[86:89]
	v_mfma_f32_16x16x32_bf16 v[78:81], v[150:153], v[206:209], v[78:81]
	v_mfma_f32_16x16x32_bf16 v[70:73], v[158:161], v[206:209], v[70:73]
	v_mfma_f32_16x16x32_bf16 v[122:125], v[162:165], v[178:181], v[122:125]
	v_mfma_f32_16x16x32_bf16 v[114:117], v[170:173], v[178:181], v[114:117]
	v_mfma_f32_16x16x32_bf16 v[106:109], v[162:165], v[186:189], v[106:109]
	v_mfma_f32_16x16x32_bf16 v[98:101], v[170:173], v[186:189], v[98:101]
	v_mfma_f32_16x16x32_bf16 v[90:93], v[162:165], v[194:197], v[90:93]
	v_mfma_f32_16x16x32_bf16 v[82:85], v[170:173], v[194:197], v[82:85]
	v_mfma_f32_16x16x32_bf16 v[74:77], v[162:165], v[202:205], v[74:77]
	v_mfma_f32_16x16x32_bf16 v[66:69], v[170:173], v[202:205], v[66:69]
	v_mfma_f32_16x16x32_bf16 v[122:125], v[166:169], v[182:185], v[122:125]
	v_mfma_f32_16x16x32_bf16 v[114:117], v[174:177], v[182:185], v[114:117]
	v_mfma_f32_16x16x32_bf16 v[106:109], v[166:169], v[190:193], v[106:109]
	v_mfma_f32_16x16x32_bf16 v[98:101], v[174:177], v[190:193], v[98:101]
	v_mfma_f32_16x16x32_bf16 v[90:93], v[166:169], v[198:201], v[90:93]
	v_mfma_f32_16x16x32_bf16 v[82:85], v[174:177], v[198:201], v[82:85]
	v_mfma_f32_16x16x32_bf16 v[74:77], v[166:169], v[206:209], v[74:77]
	v_mfma_f32_16x16x32_bf16 v[66:69], v[174:177], v[206:209], v[66:69]
	s_barrier
	s_add_i32 s10, s63, s71
	v_lshl_add_u64 v[140:141], s[92:93], 0, v[0:1]
	s_mov_b32 m0, s10
	ds_read_b128 v[178:181], v145 offset:16384
	ds_read_b128 v[182:185], v145 offset:17408
	ds_read_b128 v[186:189], v145 offset:18432
	ds_read_b128 v[190:193], v145 offset:19456
	ds_read_b128 v[194:197], v145 offset:20480
	ds_read_b128 v[198:201], v145 offset:21504
	ds_read_b128 v[202:205], v145 offset:22528
	ds_read_b128 v[206:209], v145 offset:23552
	global_load_lds_dwordx4 v[140:141], off
	s_add_i32 m0, s10, 0x2000
	s_add_u32 s10, s92, 0x40000
	v_lshl_add_u64 v[210:211], s[92:93], 0, v[130:131]
	s_addc_u32 s11, s93, 0
	s_add_i32 s63, s81, s71
	global_load_lds_dwordx4 v[210:211], off
	v_lshl_add_u64 v[212:213], s[10:11], 0, v[0:1]
	s_mov_b32 m0, s63
	v_lshl_add_u64 v[218:219], s[94:95], 0, v[132:133]
	global_load_lds_dwordx4 v[212:213], off
	v_lshl_add_u64 v[212:213], s[10:11], 0, v[130:131]
	s_add_i32 m0, s63, 0x2000
	s_nop 0
	global_load_lds_dwordx4 v[212:213], off
	v_lshl_add_u64 v[212:213], s[94:95], 0, v[134:135]
	s_mov_b32 m0, s73
	s_nop 0
	global_load_lds_dwordx4 v[212:213], off
	s_mov_b32 m0, s74
	s_nop 0
	global_load_lds_dwordx4 v[218:219], off
	s_waitcnt vmcnt(8)
	s_waitcnt lgkmcnt(0)
	s_barrier
; #define PG8_STAGE(bufoff, gbase, voff) do { _Pragma("unroll") for (int _i = 0; _i < 2; ++_i) \
;         __builtin_amdgcn_global_load_lds((const unsigned*)((const char*)(gbase) + (voff)[_i]), (LAS unsigned*)(lds + (bufoff) + ldsw + _i * 8192), 16, 0, 0); } while (0)
; #define PG8_LDA(dst, b, h) do { _Pragma("unroll") for (int m = 0; m < 4; ++m) _Pragma("unroll") for (int k = 0; k < 2; ++k) dst[m][k] = *(const LAS bf16x8*)(lds + PG8_SA(b, h) + aoff + m * 2048 + k * 1024); } while (0)
; #define PG8_LDB(dst, b, h) do { _Pragma("unroll") for (int n = 0; n < 2; ++n) _Pragma("unroll") for (int k = 0; k < 2; ++k) dst[n][k] = *(const LAS bf16x8*)(lds + PG8_SB(b, h) + boff + n * 2048 + k * 1024); } while (0)
; #define PG8_MMA(ai, bj, At, Bt) do { __builtin_amdgcn_s_setprio(1); _Pragma("unroll") for (int m = 0; m < 4; ++m) _Pragma("unroll") for (int n = 0; n < 2; ++n) _Pragma("unroll") for (int k = 0; k < 2; ++k) \
;         acc[ai][bj][m][n] = __builtin_amdgcn_mfma_f32_16x16x32_bf16(Bt[n][k], At[m][k], acc[ai][bj][m][n], 0, 0, 0); __builtin_amdgcn_s_setprio(0); } while (0)
; #define PG8_WAIT_V(n) asm volatile("s_waitcnt vmcnt(" #n ")" ::: "memory")
; #define PG8_WAIT_L(n) asm volatile("s_waitcnt lgkmcnt(" #n ")" ::: "memory")
; #define PG8_BAR __builtin_amdgcn_s_barrier()
; #define PG8_SCHED __builtin_amdgcn_sched_barrier(0)
; template <class EpiT, class Sched>
; __device__ __forceinline__ void gemm_phase(LAS unsigned char* lds, int tid_in, const GemmDesc g, const Sched& S, const EpiT& E) {
;     ...
;             PG8_WAIT_V(8); PG8_WAIT_L(0); PG8_BAR; PG8_MMA(1, 0, At, B0); PG8_MMA(1, 1, At, B1); PG8_BAR; PG8_SCHED;
;             PG8_LDB(B0, 1, 0); PG8_LDB(B1, 1, 1); PG8_SCHED; PG8_LDA(At, 1, 0); PG8_STAGE(PG8_SA(0, 1), a2 + hA, voffA);
;             PG8_WAIT_V(8); PG8_WAIT_L(0); PG8_BAR; PG8_MMA(0, 0, At, B0); PG8_MMA(0, 1, At, B1); PG8_BAR; PG8_SCHED;
;             PG8_LDA(At, 1, 1); PG8_STAGE(PG8_SB(1, 0), b3, voffB); PG8_STAGE(PG8_SB(1, 1), b3 + hB, voffB); PG8_STAGE(PG8_SA(1, 0), a3, voffA);
;             PG8_WAIT_V(8); PG8_WAIT_L(0); PG8_BAR; PG8_MMA(1, 0, At, B0); PG8_MMA(1, 1, At, B1); PG8_BAR; PG8_SCHED;
	s_waitcnt lgkmcnt(0)
	v_mfma_f32_16x16x32_bf16 v[62:65], v[146:149], v[178:181], v[62:65]
	v_mfma_f32_16x16x32_bf16 v[54:57], v[154:157], v[178:181], v[54:57]
	v_mfma_f32_16x16x32_bf16 v[46:49], v[146:149], v[186:189], v[46:49]
	v_mfma_f32_16x16x32_bf16 v[38:41], v[154:157], v[186:189], v[38:41]
	v_mfma_f32_16x16x32_bf16 v[30:33], v[146:149], v[194:197], v[30:33]
	v_mfma_f32_16x16x32_bf16 v[22:25], v[154:157], v[194:197], v[22:25]
	v_mfma_f32_16x16x32_bf16 v[14:17], v[146:149], v[202:205], v[14:17]
	v_mfma_f32_16x16x32_bf16 v[6:9], v[154:157], v[202:205], v[6:9]
	v_mfma_f32_16x16x32_bf16 v[62:65], v[150:153], v[182:185], v[62:65]
	v_mfma_f32_16x16x32_bf16 v[54:57], v[158:161], v[182:185], v[54:57]
	v_mfma_f32_16x16x32_bf16 v[46:49], v[150:153], v[190:193], v[46:49]
	v_mfma_f32_16x16x32_bf16 v[38:41], v[158:161], v[190:193], v[38:41]
	v_mfma_f32_16x16x32_bf16 v[30:33], v[150:153], v[198:201], v[30:33]
	v_mfma_f32_16x16x32_bf16 v[22:25], v[158:161], v[198:201], v[22:25]
	v_mfma_f32_16x16x32_bf16 v[14:17], v[150:153], v[206:209], v[14:17]
	v_mfma_f32_16x16x32_bf16 v[6:9], v[158:161], v[206:209], v[6:9]
	v_mfma_f32_16x16x32_bf16 v[58:61], v[162:165], v[178:181], v[58:61]
	v_mfma_f32_16x16x32_bf16 v[50:53], v[170:173], v[178:181], v[50:53]
	v_mfma_f32_16x16x32_bf16 v[42:45], v[162:165], v[186:189], v[42:45]
	v_mfma_f32_16x16x32_bf16 v[34:37], v[170:173], v[186:189], v[34:37]
	v_mfma_f32_16x16x32_bf16 v[26:29], v[162:165], v[194:197], v[26:29]
	v_mfma_f32_16x16x32_bf16 v[18:21], v[170:173], v[194:197], v[18:21]
	v_mfma_f32_16x16x32_bf16 v[10:13], v[162:165], v[202:205], v[10:13]
	v_mfma_f32_16x16x32_bf16 v[2:5], v[170:173], v[202:205], v[2:5]
	v_mfma_f32_16x16x32_bf16 v[58:61], v[166:169], v[182:185], v[58:61]
	v_mfma_f32_16x16x32_bf16 v[50:53], v[174:177], v[182:185], v[50:53]
	v_mfma_f32_16x16x32_bf16 v[42:45], v[166:169], v[190:193], v[42:45]
	v_mfma_f32_16x16x32_bf16 v[34:37], v[174:177], v[190:193], v[34:37]
	v_mfma_f32_16x16x32_bf16 v[26:29], v[166:169], v[198:201], v[26:29]
	v_mfma_f32_16x16x32_bf16 v[18:21], v[174:177], v[198:201], v[18:21]
	v_mfma_f32_16x16x32_bf16 v[10:13], v[166:169], v[206:209], v[10:13]
	v_mfma_f32_16x16x32_bf16 v[2:5], v[174:177], v[206:209], v[2:5]
	s_barrier
	s_add_i32 s63, 0, 0x18000
	s_add_i32 s81, 0, 0x1c000
	v_add_u32_e32 v158, s63, v143
	v_add_u32_e32 v174, s81, v143
	ds_read_b128 v[146:149], v158
	ds_read_b128 v[150:153], v158 offset:1024
	ds_read_b128 v[154:157], v158 offset:2048
	ds_read_b128 v[158:161], v158 offset:3072
	ds_read_b128 v[162:165], v174
	ds_read_b128 v[166:169], v174 offset:1024
	ds_read_b128 v[170:173], v174 offset:2048
	ds_read_b128 v[174:177], v174 offset:3072
	s_add_u32 s10, s94, 0x40000
	s_addc_u32 s11, s95, 0
	s_mov_b32 m0, s75
	v_lshl_add_u64 v[220:221], s[10:11], 0, v[134:135]
	ds_read_b128 v[178:181], v145 offset:32768
	ds_read_b128 v[182:185], v145 offset:33792
	ds_read_b128 v[186:189], v145 offset:34816
	ds_read_b128 v[190:193], v145 offset:35840
	ds_read_b128 v[194:197], v145 offset:36864
	ds_read_b128 v[198:201], v145 offset:37888
	ds_read_b128 v[202:205], v145 offset:38912
	ds_read_b128 v[206:209], v145 offset:39936
	global_load_lds_dwordx4 v[220:221], off
	v_lshl_add_u64 v[220:221], s[10:11], 0, v[132:133]
	s_mov_b32 m0, s76
	s_nop 0
	global_load_lds_dwordx4 v[220:221], off
	s_waitcnt vmcnt(8)
	s_waitcnt lgkmcnt(0)
	s_barrier
	s_waitcnt lgkmcnt(0)
	v_mfma_f32_16x16x32_bf16 v[126:129], v[146:149], v[178:181], v[126:129]
	v_mfma_f32_16x16x32_bf16 v[118:121], v[154:157], v[178:181], v[118:121]
	v_mfma_f32_16x16x32_bf16 v[110:113], v[146:149], v[186:189], v[110:113]
	v_mfma_f32_16x16x32_bf16 v[102:105], v[154:157], v[186:189], v[102:105]
	v_mfma_f32_16x16x32_bf16 v[94:97], v[146:149], v[194:197], v[94:97]
	v_mfma_f32_16x16x32_bf16 v[86:89], v[154:157], v[194:197], v[86:89]
	v_mfma_f32_16x16x32_bf16 v[78:81], v[146:149], v[202:205], v[78:81]
	v_mfma_f32_16x16x32_bf16 v[70:73], v[154:157], v[202:205], v[70:73]
	v_mfma_f32_16x16x32_bf16 v[126:129], v[150:153], v[182:185], v[126:129]
	v_mfma_f32_16x16x32_bf16 v[118:121], v[158:161], v[182:185], v[118:121]
	v_mfma_f32_16x16x32_bf16 v[110:113], v[150:153], v[190:193], v[110:113]
	v_mfma_f32_16x16x32_bf16 v[102:105], v[158:161], v[190:193], v[102:105]
	v_mfma_f32_16x16x32_bf16 v[94:97], v[150:153], v[198:201], v[94:97]
	v_mfma_f32_16x16x32_bf16 v[86:89], v[158:161], v[198:201], v[86:89]
	v_mfma_f32_16x16x32_bf16 v[78:81], v[150:153], v[206:209], v[78:81]
	v_mfma_f32_16x16x32_bf16 v[70:73], v[158:161], v[206:209], v[70:73]
	v_mfma_f32_16x16x32_bf16 v[122:125], v[162:165], v[178:181], v[122:125]
	v_mfma_f32_16x16x32_bf16 v[114:117], v[170:173], v[178:181], v[114:117]
	v_mfma_f32_16x16x32_bf16 v[106:109], v[162:165], v[186:189], v[106:109]
	v_mfma_f32_16x16x32_bf16 v[98:101], v[170:173], v[186:189], v[98:101]
	v_mfma_f32_16x16x32_bf16 v[90:93], v[162:165], v[194:197], v[90:93]
	v_mfma_f32_16x16x32_bf16 v[82:85], v[170:173], v[194:197], v[82:85]
	v_mfma_f32_16x16x32_bf16 v[74:77], v[162:165], v[202:205], v[74:77]
	v_mfma_f32_16x16x32_bf16 v[66:69], v[170:173], v[202:205], v[66:69]
	v_mfma_f32_16x16x32_bf16 v[122:125], v[166:169], v[182:185], v[122:125]
	v_mfma_f32_16x16x32_bf16 v[114:117], v[174:177], v[182:185], v[114:117]
	v_mfma_f32_16x16x32_bf16 v[106:109], v[166:169], v[190:193], v[106:109]
	v_mfma_f32_16x16x32_bf16 v[98:101], v[174:177], v[190:193], v[98:101]
	v_mfma_f32_16x16x32_bf16 v[90:93], v[166:169], v[198:201], v[90:93]
	v_mfma_f32_16x16x32_bf16 v[82:85], v[174:177], v[198:201], v[82:85]
	v_mfma_f32_16x16x32_bf16 v[74:77], v[166:169], v[206:209], v[74:77]
	v_mfma_f32_16x16x32_bf16 v[66:69], v[174:177], v[206:209], v[66:69]
	s_barrier
; #define PG8_STAGE(bufoff, gbase, voff) do { _Pragma("unroll") for (int _i = 0; _i < 2; ++_i) \
;         __builtin_amdgcn_global_load_lds((const unsigned*)((const char*)(gbase) + (voff)[_i]), (LAS unsigned*)(lds + (bufoff) + ldsw + _i * 8192), 16, 0, 0); } while (0)
; #define PG8_LDA(dst, b, h) do { _Pragma("unroll") for (int m = 0; m < 4; ++m) _Pragma("unroll") for (int k = 0; k < 2; ++k) dst[m][k] = *(const LAS bf16x8*)(lds + PG8_SA(b, h) + aoff + m * 2048 + k * 1024); } while (0)
; #define PG8_LDB(dst, b, h) do { _Pragma("unroll") for (int n = 0; n < 2; ++n) _Pragma("unroll") for (int k = 0; k < 2; ++k) dst[n][k] = *(const LAS bf16x8*)(lds + PG8_SB(b, h) + boff + n * 2048 + k * 1024); } while (0)
; #define PG8_MMA(ai, bj, At, Bt) do { __builtin_amdgcn_s_setprio(1); _Pragma("unroll") for (int m = 0; m < 4; ++m) _Pragma("unroll") for (int n = 0; n < 2; ++n) _Pragma("unroll") for (int k = 0; k < 2; ++k) \
;         acc[ai][bj][m][n] = __builtin_amdgcn_mfma_f32_16x16x32_bf16(Bt[n][k], At[m][k], acc[ai][bj][m][n], 0, 0, 0); __builtin_amdgcn_s_setprio(0); } while (0)
; #define PG8_WAIT_V(n) asm volatile("s_waitcnt vmcnt(" #n ")" ::: "memory")
; #define PG8_WAIT_L(n) asm volatile("s_waitcnt lgkmcnt(" #n ")" ::: "memory")
; #define PG8_BAR __builtin_amdgcn_s_barrier()
; #define PG8_SCHED __builtin_amdgcn_sched_barrier(0)
; template <class EpiT, class Sched>
; __device__ __forceinline__ void gemm_phase(LAS unsigned char* lds, int tid_in, const GemmDesc g, const Sched& S, const EpiT& E) {
;     ...
;             PG8_LDB(B0, 1, 0); PG8_LDB(B1, 1, 1); PG8_SCHED; PG8_LDA(At, 1, 0); PG8_STAGE(PG8_SA(0, 1), a2 + hA, voffA);
;             PG8_WAIT_V(8); PG8_WAIT_L(0); PG8_BAR; PG8_MMA(0, 0, At, B0); PG8_MMA(0, 1, At, B1); PG8_BAR; PG8_SCHED;
;             PG8_LDA(At, 1, 1); PG8_STAGE(PG8_SB(1, 0), b3, voffB); PG8_STAGE(PG8_SB(1, 1), b3 + hB, voffB); PG8_STAGE(PG8_SA(1, 0), a3, voffA);
;             PG8_WAIT_V(8); PG8_WAIT_L(0); PG8_BAR; PG8_MMA(1, 0, At, B0); PG8_MMA(1, 1, At, B1); PG8_BAR; PG8_SCHED;
	s_add_i32 s10, s63, s71
	v_lshl_add_u64 v[140:141], v[140:141], 0, s[60:61]
	s_mov_b32 m0, s10
	ds_read_b128 v[178:181], v145 offset:49152
	ds_read_b128 v[182:185], v145 offset:50176
	ds_read_b128 v[186:189], v145 offset:51200
	ds_read_b128 v[190:193], v145 offset:52224
	ds_read_b128 v[194:197], v145 offset:53248
	ds_read_b128 v[198:201], v145 offset:54272
	ds_read_b128 v[202:205], v145 offset:55296
	ds_read_b128 v[206:209], v145 offset:56320
	global_load_lds_dwordx4 v[140:141], off
	s_add_i32 m0, s10, 0x2000
	s_add_u32 s10, s92, 0x40080
	v_lshl_add_u64 v[140:141], v[210:211], 0, s[60:61]
	s_addc_u32 s11, s93, 0
	s_add_i32 s63, s81, s71
	global_load_lds_dwordx4 v[140:141], off
	v_lshl_add_u64 v[140:141], s[10:11], 0, v[0:1]
	s_mov_b32 m0, s63
	s_nop 0
	global_load_lds_dwordx4 v[140:141], off
	v_lshl_add_u64 v[140:141], s[10:11], 0, v[130:131]
	s_add_i32 m0, s63, 0x2000
	s_nop 0
	global_load_lds_dwordx4 v[140:141], off
	v_lshl_add_u64 v[140:141], v[212:213], 0, s[60:61]
	s_mov_b32 m0, s17
	s_nop 0
	global_load_lds_dwordx4 v[140:141], off
	v_lshl_add_u64 v[140:141], v[218:219], 0, s[60:61]
	s_mov_b32 m0, s77
	s_nop 0
	global_load_lds_dwordx4 v[140:141], off
	s_waitcnt vmcnt(8)
	s_waitcnt lgkmcnt(0)
	s_barrier
	s_waitcnt lgkmcnt(0)
	v_mfma_f32_16x16x32_bf16 v[62:65], v[146:149], v[178:181], v[62:65]
	v_mfma_f32_16x16x32_bf16 v[54:57], v[154:157], v[178:181], v[54:57]
	v_mfma_f32_16x16x32_bf16 v[46:49], v[146:149], v[186:189], v[46:49]
	v_mfma_f32_16x16x32_bf16 v[38:41], v[154:157], v[186:189], v[38:41]
	v_mfma_f32_16x16x32_bf16 v[30:33], v[146:149], v[194:197], v[30:33]
	v_mfma_f32_16x16x32_bf16 v[22:25], v[154:157], v[194:197], v[22:25]
	v_mfma_f32_16x16x32_bf16 v[14:17], v[146:149], v[202:205], v[14:17]
	v_mfma_f32_16x16x32_bf16 v[6:9], v[154:157], v[202:205], v[6:9]
	v_mfma_f32_16x16x32_bf16 v[62:65], v[150:153], v[182:185], v[62:65]
	v_mfma_f32_16x16x32_bf16 v[54:57], v[158:161], v[182:185], v[54:57]
	v_mfma_f32_16x16x32_bf16 v[46:49], v[150:153], v[190:193], v[46:49]
	v_mfma_f32_16x16x32_bf16 v[38:41], v[158:161], v[190:193], v[38:41]
	v_mfma_f32_16x16x32_bf16 v[30:33], v[150:153], v[198:201], v[30:33]
	v_mfma_f32_16x16x32_bf16 v[22:25], v[158:161], v[198:201], v[22:25]
	v_mfma_f32_16x16x32_bf16 v[14:17], v[150:153], v[206:209], v[14:17]
	v_mfma_f32_16x16x32_bf16 v[6:9], v[158:161], v[206:209], v[6:9]
	v_mfma_f32_16x16x32_bf16 v[58:61], v[162:165], v[178:181], v[58:61]
	v_mfma_f32_16x16x32_bf16 v[50:53], v[170:173], v[178:181], v[50:53]
	v_mfma_f32_16x16x32_bf16 v[42:45], v[162:165], v[186:189], v[42:45]
	v_mfma_f32_16x16x32_bf16 v[34:37], v[170:173], v[186:189], v[34:37]
	v_mfma_f32_16x16x32_bf16 v[26:29], v[162:165], v[194:197], v[26:29]
	v_mfma_f32_16x16x32_bf16 v[18:21], v[170:173], v[194:197], v[18:21]
	v_mfma_f32_16x16x32_bf16 v[10:13], v[162:165], v[202:205], v[10:13]
	v_mfma_f32_16x16x32_bf16 v[2:5], v[170:173], v[202:205], v[2:5]
	v_mfma_f32_16x16x32_bf16 v[58:61], v[166:169], v[182:185], v[58:61]
	v_mfma_f32_16x16x32_bf16 v[50:53], v[174:177], v[182:185], v[50:53]
	v_mfma_f32_16x16x32_bf16 v[42:45], v[166:169], v[190:193], v[42:45]
	v_mfma_f32_16x16x32_bf16 v[34:37], v[174:177], v[190:193], v[34:37]
	v_mfma_f32_16x16x32_bf16 v[26:29], v[166:169], v[198:201], v[26:29]
	v_mfma_f32_16x16x32_bf16 v[18:21], v[174:177], v[198:201], v[18:21]
	v_mfma_f32_16x16x32_bf16 v[10:13], v[166:169], v[206:209], v[10:13]
	v_mfma_f32_16x16x32_bf16 v[2:5], v[174:177], v[206:209], v[2:5]
	s_barrier
	s_add_i32 s62, s62, 2
	s_add_u32 vcc_lo, vcc_lo, 0x100
	s_addc_u32 vcc_hi, vcc_hi, 0
	s_add_u32 s79, s79, 0x100
	s_addc_u32 s80, s80, 0
	s_cmp_gt_u32 s62, 13
	s_cbranch_scc0 .LBB0_187
	s_and_b64 vcc, exec, s[34:35]
	s_cbranch_vccz .LBB0_190
	s_barrier

; #define PG8_STAGE(bufoff, gbase, voff) do { _Pragma("unroll") for (int _i = 0; _i < 2; ++_i) \
;         __builtin_amdgcn_global_load_lds((const unsigned*)((const char*)(gbase) + (voff)[_i]), (LAS unsigned*)(lds + (bufoff) + ldsw + _i * 8192), 16, 0, 0); } while (0)
; #define PG8_LDA(dst, b, h) do { _Pragma("unroll") for (int m = 0; m < 4; ++m) _Pragma("unroll") for (int k = 0; k < 2; ++k) dst[m][k] = *(const LAS bf16x8*)(lds + PG8_SA(b, h) + aoff + m * 2048 + k * 1024); } while (0)
; #define PG8_WAIT_V(n) asm volatile("s_waitcnt vmcnt(" #n ")" ::: "memory")
; #define PG8_WAIT_L(n) asm volatile("s_waitcnt lgkmcnt(" #n ")" ::: "memory")
; #define PG8_BAR __builtin_amdgcn_s_barrier()
; template <class EpiT, class Sched>
; __device__ __forceinline__ void gemm_phase(LAS unsigned char* lds, int tid_in, const GemmDesc g, const Sched& S, const EpiT& E) {
;     ...
;     for (;;) {
;         const bool has_next = S.next(ui + 1, nxt);
;         const char* nA = has_next ? g.A + nxt.aoff : cA; const char* nB = has_next ? g.Bt + nxt.boff : cB;
;         for (int t = 0; t < nt; t += 2) {
;             const bool last = (t == nt - 2);
;             const char* a1 = cA + (size_t)(t + 1) * kA;
;             const char* a2 = last ? nA : cA + (size_t)(t + 2) * kA; const char* b2 = last ? nB : cB + (size_t)(t + 2) * kB;
;             const char* a3 = a2 + kA; const char* b3 = b2 + kB;
;             PG8_LDB(B0, 0, 0); PG8_LDB(B1, 0, 1); PG8_SCHED; PG8_LDA(At, 0, 0); PG8_STAGE(PG8_SA(1, 1), a1 + hA, voffA);
;             PG8_WAIT_V(8); PG8_WAIT_L(0); PG8_BAR; PG8_MMA(0, 0, At, B0); PG8_MMA(0, 1, At, B1); PG8_BAR; PG8_SCHED;
;             PG8_LDA(At, 0, 1); PG8_STAGE(PG8_SB(0, 0), b2, voffB); PG8_STAGE(PG8_SB(0, 1), b2 + hB, voffB); PG8_STAGE(PG8_SA(0, 0), a2, voffA);
;             PG8_WAIT_V(8); PG8_WAIT_L(0); PG8_BAR; PG8_MMA(1, 0, At, B0); PG8_MMA(1, 1, At, B1); PG8_BAR; PG8_SCHED;
;             PG8_LDB(B0, 1, 0); PG8_LDB(B1, 1, 1); PG8_SCHED; PG8_LDA(At, 1, 0); PG8_STAGE(PG8_SA(0, 1), a2 + hA, voffA);
;             PG8_WAIT_V(8); PG8_WAIT_L(0); PG8_BAR; PG8_MMA(0, 0, At, B0); PG8_MMA(0, 1, At, B1); PG8_BAR; PG8_SCHED;
;             PG8_LDA(At, 1, 1); PG8_STAGE(PG8_SB(1, 0), b3, voffB); PG8_STAGE(PG8_SB(1, 1), b3 + hB, voffB); PG8_STAGE(PG8_SA(1, 0), a3, voffA);
;             PG8_WAIT_V(8); PG8_WAIT_L(0); PG8_BAR; PG8_MMA(1, 0, At, B0); PG8_MMA(1, 1, At, B1); PG8_BAR; PG8_SCHED;
.LBB0_263:
	s_add_u32 s86, s82, 0x100
	s_addc_u32 s87, s83, 0
	s_add_i32 s10, 0, 0x10000
	s_cmp_eq_u32 s63, 40
	s_cselect_b32 s93, s2, s87
	s_cselect_b32 s92, s3, s86
	s_cselect_b32 s89, s59, s62
	s_cselect_b32 s88, s95, s96
	s_add_i32 s97, 0, 0x14000
	v_add_u32_e32 v156, s10, v141
	v_add_u32_e32 v172, s97, v141
	ds_read_b128 v[144:147], v156
	ds_read_b128 v[148:151], v156 offset:1024
	ds_read_b128 v[152:155], v156 offset:2048
	ds_read_b128 v[156:159], v156 offset:3072
	ds_read_b128 v[160:163], v172
	ds_read_b128 v[164:167], v172 offset:1024
	ds_read_b128 v[168:171], v172 offset:2048
	ds_read_b128 v[172:175], v172 offset:3072
	v_lshl_add_u64 v[208:209], s[82:83], 0, v[136:137]
	s_add_i32 m0, s73, 0xc000
	ds_read_b128 v[176:179], v143
	ds_read_b128 v[180:183], v143 offset:1024
	ds_read_b128 v[184:187], v143 offset:2048
	ds_read_b128 v[188:191], v143 offset:3072
	ds_read_b128 v[192:195], v143 offset:4096
	ds_read_b128 v[196:199], v143 offset:5120
	ds_read_b128 v[200:203], v143 offset:6144
	ds_read_b128 v[204:207], v143 offset:7168
	global_load_lds_dwordx4 v[208:209], off
	v_lshl_add_u64 v[208:209], s[82:83], 0, v[138:139]
	s_add_i32 m0, s73, 0xe000
	s_nop 0
	global_load_lds_dwordx4 v[208:209], off
	s_waitcnt vmcnt(8)
	s_waitcnt lgkmcnt(0)
	s_barrier
	s_waitcnt lgkmcnt(0)
	v_mfma_f32_16x16x32_bf16 v[126:129], v[144:147], v[176:179], v[126:129]
	v_mfma_f32_16x16x32_bf16 v[122:125], v[152:155], v[176:179], v[122:125]
	v_mfma_f32_16x16x32_bf16 v[118:121], v[144:147], v[184:187], v[118:121]
	v_mfma_f32_16x16x32_bf16 v[114:117], v[152:155], v[184:187], v[114:117]
	v_mfma_f32_16x16x32_bf16 v[102:105], v[144:147], v[192:195], v[102:105]
	v_mfma_f32_16x16x32_bf16 v[98:101], v[152:155], v[192:195], v[98:101]
	v_mfma_f32_16x16x32_bf16 v[86:89], v[144:147], v[200:203], v[86:89]
	v_mfma_f32_16x16x32_bf16 v[82:85], v[152:155], v[200:203], v[82:85]
	v_mfma_f32_16x16x32_bf16 v[126:129], v[148:151], v[180:183], v[126:129]
	v_mfma_f32_16x16x32_bf16 v[122:125], v[156:159], v[180:183], v[122:125]
	v_mfma_f32_16x16x32_bf16 v[118:121], v[148:151], v[188:191], v[118:121]
	v_mfma_f32_16x16x32_bf16 v[114:117], v[156:159], v[188:191], v[114:117]
	v_mfma_f32_16x16x32_bf16 v[102:105], v[148:151], v[196:199], v[102:105]
	v_mfma_f32_16x16x32_bf16 v[98:101], v[156:159], v[196:199], v[98:101]
	v_mfma_f32_16x16x32_bf16 v[86:89], v[148:151], v[204:207], v[86:89]
	v_mfma_f32_16x16x32_bf16 v[82:85], v[156:159], v[204:207], v[82:85]
	v_mfma_f32_16x16x32_bf16 v[110:113], v[160:163], v[176:179], v[110:113]
	v_mfma_f32_16x16x32_bf16 v[106:109], v[168:171], v[176:179], v[106:109]
	v_mfma_f32_16x16x32_bf16 v[94:97], v[160:163], v[184:187], v[94:97]
	v_mfma_f32_16x16x32_bf16 v[90:93], v[168:171], v[184:187], v[90:93]
	v_mfma_f32_16x16x32_bf16 v[78:81], v[160:163], v[192:195], v[78:81]
	v_mfma_f32_16x16x32_bf16 v[74:77], v[168:171], v[192:195], v[74:77]
	v_mfma_f32_16x16x32_bf16 v[70:73], v[160:163], v[200:203], v[70:73]
	v_mfma_f32_16x16x32_bf16 v[66:69], v[168:171], v[200:203], v[66:69]
	v_mfma_f32_16x16x32_bf16 v[110:113], v[164:167], v[180:183], v[110:113]
	v_mfma_f32_16x16x32_bf16 v[106:109], v[172:175], v[180:183], v[106:109]
	v_mfma_f32_16x16x32_bf16 v[94:97], v[164:167], v[188:191], v[94:97]
	v_mfma_f32_16x16x32_bf16 v[90:93], v[172:175], v[188:191], v[90:93]
	v_mfma_f32_16x16x32_bf16 v[78:81], v[164:167], v[196:199], v[78:81]
	v_mfma_f32_16x16x32_bf16 v[74:77], v[172:175], v[196:199], v[74:77]
	v_mfma_f32_16x16x32_bf16 v[70:73], v[164:167], v[204:207], v[70:73]
	v_mfma_f32_16x16x32_bf16 v[66:69], v[172:175], v[204:207], v[66:69]
	s_barrier
	s_add_i32 s10, s10, s72
	v_lshl_add_u64 v[208:209], s[88:89], 0, v[0:1]
	s_mov_b32 m0, s10
	ds_read_b128 v[176:179], v143 offset:16384
	ds_read_b128 v[180:183], v143 offset:17408
	ds_read_b128 v[184:187], v143 offset:18432
	ds_read_b128 v[188:191], v143 offset:19456
	ds_read_b128 v[192:195], v143 offset:20480
	ds_read_b128 v[196:199], v143 offset:21504
	ds_read_b128 v[200:203], v143 offset:22528
	ds_read_b128 v[204:207], v143 offset:23552
	global_load_lds_dwordx4 v[208:209], off
	s_add_i32 m0, s10, 0x2000
	s_add_u32 s10, s88, 0xb0000
	v_lshl_add_u64 v[210:211], s[88:89], 0, v[134:135]
	s_addc_u32 s11, s89, 0
	s_add_i32 s82, s97, s72
	global_load_lds_dwordx4 v[210:211], off
	v_lshl_add_u64 v[212:213], s[10:11], 0, v[0:1]
	s_mov_b32 m0, s82
	v_lshl_add_u64 v[218:219], s[92:93], 0, v[132:133]
	global_load_lds_dwordx4 v[212:213], off
	v_lshl_add_u64 v[212:213], s[10:11], 0, v[134:135]
	s_add_i32 m0, s82, 0x2000
	s_nop 0
	global_load_lds_dwordx4 v[212:213], off
	v_lshl_add_u64 v[212:213], s[92:93], 0, v[130:131]
	s_mov_b32 m0, s73
	s_nop 0
	global_load_lds_dwordx4 v[212:213], off
	s_mov_b32 m0, s74
	s_nop 0
	global_load_lds_dwordx4 v[218:219], off
	s_waitcnt vmcnt(8)
	s_waitcnt lgkmcnt(0)
	s_barrier
; #define PG8_STAGE(bufoff, gbase, voff) do { _Pragma("unroll") for (int _i = 0; _i < 2; ++_i) \
;         __builtin_amdgcn_global_load_lds((const unsigned*)((const char*)(gbase) + (voff)[_i]), (LAS unsigned*)(lds + (bufoff) + ldsw + _i * 8192), 16, 0, 0); } while (0)
; #define PG8_LDA(dst, b, h) do { _Pragma("unroll") for (int m = 0; m < 4; ++m) _Pragma("unroll") for (int k = 0; k < 2; ++k) dst[m][k] = *(const LAS bf16x8*)(lds + PG8_SA(b, h) + aoff + m * 2048 + k * 1024); } while (0)
; #define PG8_LDB(dst, b, h) do { _Pragma("unroll") for (int n = 0; n < 2; ++n) _Pragma("unroll") for (int k = 0; k < 2; ++k) dst[n][k] = *(const LAS bf16x8*)(lds + PG8_SB(b, h) + boff + n * 2048 + k * 1024); } while (0)
; #define PG8_MMA(ai, bj, At, Bt) do { __builtin_amdgcn_s_setprio(1); _Pragma("unroll") for (int m = 0; m < 4; ++m) _Pragma("unroll") for (int n = 0; n < 2; ++n) _Pragma("unroll") for (int k = 0; k < 2; ++k) \
;         acc[ai][bj][m][n] = __builtin_amdgcn_mfma_f32_16x16x32_bf16(Bt[n][k], At[m][k], acc[ai][bj][m][n], 0, 0, 0); __builtin_amdgcn_s_setprio(0); } while (0)
; #define PG8_WAIT_V(n) asm volatile("s_waitcnt vmcnt(" #n ")" ::: "memory")
; #define PG8_WAIT_L(n) asm volatile("s_waitcnt lgkmcnt(" #n ")" ::: "memory")
; #define PG8_BAR __builtin_amdgcn_s_barrier()
; #define PG8_SCHED __builtin_amdgcn_sched_barrier(0)
; template <class EpiT, class Sched>
; __device__ __forceinline__ void gemm_phase(LAS unsigned char* lds, int tid_in, const GemmDesc g, const Sched& S, const EpiT& E) {
;     ...
;             PG8_WAIT_V(8); PG8_WAIT_L(0); PG8_BAR; PG8_MMA(1, 0, At, B0); PG8_MMA(1, 1, At, B1); PG8_BAR; PG8_SCHED;
;             PG8_LDB(B0, 1, 0); PG8_LDB(B1, 1, 1); PG8_SCHED; PG8_LDA(At, 1, 0); PG8_STAGE(PG8_SA(0, 1), a2 + hA, voffA);
;             PG8_WAIT_V(8); PG8_WAIT_L(0); PG8_BAR; PG8_MMA(0, 0, At, B0); PG8_MMA(0, 1, At, B1); PG8_BAR; PG8_SCHED;
;             PG8_LDA(At, 1, 1); PG8_STAGE(PG8_SB(1, 0), b3, voffB); PG8_STAGE(PG8_SB(1, 1), b3 + hB, voffB); PG8_STAGE(PG8_SA(1, 0), a3, voffA);
;             PG8_WAIT_V(8); PG8_WAIT_L(0); PG8_BAR; PG8_MMA(1, 0, At, B0); PG8_MMA(1, 1, At, B1); PG8_BAR; PG8_SCHED;
	s_waitcnt lgkmcnt(0)
	v_mfma_f32_16x16x32_bf16 v[62:65], v[144:147], v[176:179], v[62:65]
	v_mfma_f32_16x16x32_bf16 v[58:61], v[152:155], v[176:179], v[58:61]
	v_mfma_f32_16x16x32_bf16 v[54:57], v[144:147], v[184:187], v[54:57]
	v_mfma_f32_16x16x32_bf16 v[50:53], v[152:155], v[184:187], v[50:53]
	v_mfma_f32_16x16x32_bf16 v[38:41], v[144:147], v[192:195], v[38:41]
	v_mfma_f32_16x16x32_bf16 v[34:37], v[152:155], v[192:195], v[34:37]
	v_mfma_f32_16x16x32_bf16 v[22:25], v[144:147], v[200:203], v[22:25]
	v_mfma_f32_16x16x32_bf16 v[18:21], v[152:155], v[200:203], v[18:21]
	v_mfma_f32_16x16x32_bf16 v[62:65], v[148:151], v[180:183], v[62:65]
	v_mfma_f32_16x16x32_bf16 v[58:61], v[156:159], v[180:183], v[58:61]
	v_mfma_f32_16x16x32_bf16 v[54:57], v[148:151], v[188:191], v[54:57]
	v_mfma_f32_16x16x32_bf16 v[50:53], v[156:159], v[188:191], v[50:53]
	v_mfma_f32_16x16x32_bf16 v[38:41], v[148:151], v[196:199], v[38:41]
	v_mfma_f32_16x16x32_bf16 v[34:37], v[156:159], v[196:199], v[34:37]
	v_mfma_f32_16x16x32_bf16 v[22:25], v[148:151], v[204:207], v[22:25]
	v_mfma_f32_16x16x32_bf16 v[18:21], v[156:159], v[204:207], v[18:21]
	v_mfma_f32_16x16x32_bf16 v[46:49], v[160:163], v[176:179], v[46:49]
	v_mfma_f32_16x16x32_bf16 v[42:45], v[168:171], v[176:179], v[42:45]
	v_mfma_f32_16x16x32_bf16 v[30:33], v[160:163], v[184:187], v[30:33]
	v_mfma_f32_16x16x32_bf16 v[26:29], v[168:171], v[184:187], v[26:29]
	v_mfma_f32_16x16x32_bf16 v[14:17], v[160:163], v[192:195], v[14:17]
	v_mfma_f32_16x16x32_bf16 v[10:13], v[168:171], v[192:195], v[10:13]
	v_mfma_f32_16x16x32_bf16 v[6:9], v[160:163], v[200:203], v[6:9]
	v_mfma_f32_16x16x32_bf16 v[2:5], v[168:171], v[200:203], v[2:5]
	v_mfma_f32_16x16x32_bf16 v[46:49], v[164:167], v[180:183], v[46:49]
	v_mfma_f32_16x16x32_bf16 v[42:45], v[172:175], v[180:183], v[42:45]
	v_mfma_f32_16x16x32_bf16 v[30:33], v[164:167], v[188:191], v[30:33]
	v_mfma_f32_16x16x32_bf16 v[26:29], v[172:175], v[188:191], v[26:29]
	v_mfma_f32_16x16x32_bf16 v[14:17], v[164:167], v[196:199], v[14:17]
	v_mfma_f32_16x16x32_bf16 v[10:13], v[172:175], v[196:199], v[10:13]
	v_mfma_f32_16x16x32_bf16 v[6:9], v[164:167], v[204:207], v[6:9]
	v_mfma_f32_16x16x32_bf16 v[2:5], v[172:175], v[204:207], v[2:5]
	s_barrier
	s_add_i32 s82, 0, 0x18000
	s_add_i32 s83, 0, 0x1c000
	v_add_u32_e32 v156, s82, v141
	v_add_u32_e32 v172, s83, v141
	ds_read_b128 v[144:147], v156
	ds_read_b128 v[148:151], v156 offset:1024
	ds_read_b128 v[152:155], v156 offset:2048
	ds_read_b128 v[156:159], v156 offset:3072
	ds_read_b128 v[160:163], v172
	ds_read_b128 v[164:167], v172 offset:1024
	ds_read_b128 v[168:171], v172 offset:2048
	ds_read_b128 v[172:175], v172 offset:3072
	s_add_u32 s10, s92, 0xb0000
	s_addc_u32 s11, s93, 0
	s_mov_b32 m0, s75
	v_lshl_add_u64 v[220:221], s[10:11], 0, v[130:131]
	ds_read_b128 v[176:179], v143 offset:32768
	ds_read_b128 v[180:183], v143 offset:33792
	ds_read_b128 v[184:187], v143 offset:34816
	ds_read_b128 v[188:191], v143 offset:35840
	ds_read_b128 v[192:195], v143 offset:36864
	ds_read_b128 v[196:199], v143 offset:37888
	ds_read_b128 v[200:203], v143 offset:38912
	ds_read_b128 v[204:207], v143 offset:39936
	global_load_lds_dwordx4 v[220:221], off
	v_lshl_add_u64 v[220:221], s[10:11], 0, v[132:133]
	s_mov_b32 m0, s76
	s_nop 0
	global_load_lds_dwordx4 v[220:221], off
	s_waitcnt vmcnt(8)
	s_waitcnt lgkmcnt(0)
	s_barrier
	s_waitcnt lgkmcnt(0)
	v_mfma_f32_16x16x32_bf16 v[126:129], v[144:147], v[176:179], v[126:129]
	v_mfma_f32_16x16x32_bf16 v[122:125], v[152:155], v[176:179], v[122:125]
	v_mfma_f32_16x16x32_bf16 v[118:121], v[144:147], v[184:187], v[118:121]
	v_mfma_f32_16x16x32_bf16 v[114:117], v[152:155], v[184:187], v[114:117]
	v_mfma_f32_16x16x32_bf16 v[102:105], v[144:147], v[192:195], v[102:105]
	v_mfma_f32_16x16x32_bf16 v[98:101], v[152:155], v[192:195], v[98:101]
	v_mfma_f32_16x16x32_bf16 v[86:89], v[144:147], v[200:203], v[86:89]
	v_mfma_f32_16x16x32_bf16 v[82:85], v[152:155], v[200:203], v[82:85]
	v_mfma_f32_16x16x32_bf16 v[126:129], v[148:151], v[180:183], v[126:129]
	v_mfma_f32_16x16x32_bf16 v[122:125], v[156:159], v[180:183], v[122:125]
	v_mfma_f32_16x16x32_bf16 v[118:121], v[148:151], v[188:191], v[118:121]
	v_mfma_f32_16x16x32_bf16 v[114:117], v[156:159], v[188:191], v[114:117]
	v_mfma_f32_16x16x32_bf16 v[102:105], v[148:151], v[196:199], v[102:105]
	v_mfma_f32_16x16x32_bf16 v[98:101], v[156:159], v[196:199], v[98:101]
	v_mfma_f32_16x16x32_bf16 v[86:89], v[148:151], v[204:207], v[86:89]
	v_mfma_f32_16x16x32_bf16 v[82:85], v[156:159], v[204:207], v[82:85]
	v_mfma_f32_16x16x32_bf16 v[110:113], v[160:163], v[176:179], v[110:113]
	v_mfma_f32_16x16x32_bf16 v[106:109], v[168:171], v[176:179], v[106:109]
	v_mfma_f32_16x16x32_bf16 v[94:97], v[160:163], v[184:187], v[94:97]
	v_mfma_f32_16x16x32_bf16 v[90:93], v[168:171], v[184:187], v[90:93]
	v_mfma_f32_16x16x32_bf16 v[78:81], v[160:163], v[192:195], v[78:81]
	v_mfma_f32_16x16x32_bf16 v[74:77], v[168:171], v[192:195], v[74:77]
	v_mfma_f32_16x16x32_bf16 v[70:73], v[160:163], v[200:203], v[70:73]
	v_mfma_f32_16x16x32_bf16 v[66:69], v[168:171], v[200:203], v[66:69]
	v_mfma_f32_16x16x32_bf16 v[110:113], v[164:167], v[180:183], v[110:113]
	v_mfma_f32_16x16x32_bf16 v[106:109], v[172:175], v[180:183], v[106:109]
	v_mfma_f32_16x16x32_bf16 v[94:97], v[164:167], v[188:191], v[94:97]
	v_mfma_f32_16x16x32_bf16 v[90:93], v[172:175], v[188:191], v[90:93]
	v_mfma_f32_16x16x32_bf16 v[78:81], v[164:167], v[196:199], v[78:81]
	v_mfma_f32_16x16x32_bf16 v[74:77], v[172:175], v[196:199], v[74:77]
	v_mfma_f32_16x16x32_bf16 v[70:73], v[164:167], v[204:207], v[70:73]
	v_mfma_f32_16x16x32_bf16 v[66:69], v[172:175], v[204:207], v[66:69]
	s_barrier
; #define PG8_STAGE(bufoff, gbase, voff) do { _Pragma("unroll") for (int _i = 0; _i < 2; ++_i) \
;         __builtin_amdgcn_global_load_lds((const unsigned*)((const char*)(gbase) + (voff)[_i]), (LAS unsigned*)(lds + (bufoff) + ldsw + _i * 8192), 16, 0, 0); } while (0)
; #define PG8_LDA(dst, b, h) do { _Pragma("unroll") for (int m = 0; m < 4; ++m) _Pragma("unroll") for (int k = 0; k < 2; ++k) dst[m][k] = *(const LAS bf16x8*)(lds + PG8_SA(b, h) + aoff + m * 2048 + k * 1024); } while (0)
; #define PG8_LDB(dst, b, h) do { _Pragma("unroll") for (int n = 0; n < 2; ++n) _Pragma("unroll") for (int k = 0; k < 2; ++k) dst[n][k] = *(const LAS bf16x8*)(lds + PG8_SB(b, h) + boff + n * 2048 + k * 1024); } while (0)
; #define PG8_MMA(ai, bj, At, Bt) do { __builtin_amdgcn_s_setprio(1); _Pragma("unroll") for (int m = 0; m < 4; ++m) _Pragma("unroll") for (int n = 0; n < 2; ++n) _Pragma("unroll") for (int k = 0; k < 2; ++k) \
;         acc[ai][bj][m][n] = __builtin_amdgcn_mfma_f32_16x16x32_bf16(Bt[n][k], At[m][k], acc[ai][bj][m][n], 0, 0, 0); __builtin_amdgcn_s_setprio(0); } while (0)
; #define PG8_WAIT_V(n) asm volatile("s_waitcnt vmcnt(" #n ")" ::: "memory")
; #define PG8_WAIT_L(n) asm volatile("s_waitcnt lgkmcnt(" #n ")" ::: "memory")
; #define PG8_BAR __builtin_amdgcn_s_barrier()
; #define PG8_SCHED __builtin_amdgcn_sched_barrier(0)
; template <class EpiT, class Sched>
; __device__ __forceinline__ void gemm_phase(LAS unsigned char* lds, int tid_in, const GemmDesc g, const Sched& S, const EpiT& E) {
;     ...
;             PG8_LDB(B0, 1, 0); PG8_LDB(B1, 1, 1); PG8_SCHED; PG8_LDA(At, 1, 0); PG8_STAGE(PG8_SA(0, 1), a2 + hA, voffA);
;             PG8_WAIT_V(8); PG8_WAIT_L(0); PG8_BAR; PG8_MMA(0, 0, At, B0); PG8_MMA(0, 1, At, B1); PG8_BAR; PG8_SCHED;
;             PG8_LDA(At, 1, 1); PG8_STAGE(PG8_SB(1, 0), b3, voffB); PG8_STAGE(PG8_SB(1, 1), b3 + hB, voffB); PG8_STAGE(PG8_SA(1, 0), a3, voffA);
;             PG8_WAIT_V(8); PG8_WAIT_L(0); PG8_BAR; PG8_MMA(1, 0, At, B0); PG8_MMA(1, 1, At, B1); PG8_BAR; PG8_SCHED;
	s_add_i32 s10, s82, s72
	v_lshl_add_u64 v[208:209], v[208:209], 0, s[60:61]
	s_mov_b32 m0, s10
	ds_read_b128 v[176:179], v143 offset:49152
	ds_read_b128 v[180:183], v143 offset:50176
	ds_read_b128 v[184:187], v143 offset:51200
	ds_read_b128 v[188:191], v143 offset:52224
	ds_read_b128 v[192:195], v143 offset:53248
	ds_read_b128 v[196:199], v143 offset:54272
	ds_read_b128 v[200:203], v143 offset:55296
	ds_read_b128 v[204:207], v143 offset:56320
	global_load_lds_dwordx4 v[208:209], off
	s_add_i32 m0, s10, 0x2000
	s_add_u32 s10, s88, 0xb0080
	v_lshl_add_u64 v[208:209], v[210:211], 0, s[60:61]
	s_addc_u32 s11, s89, 0
	s_add_i32 s82, s83, s72
	global_load_lds_dwordx4 v[208:209], off
	v_lshl_add_u64 v[208:209], s[10:11], 0, v[0:1]
	s_mov_b32 m0, s82
	s_nop 0
	global_load_lds_dwordx4 v[208:209], off
	v_lshl_add_u64 v[208:209], s[10:11], 0, v[134:135]
	s_add_i32 m0, s82, 0x2000
	s_nop 0
	global_load_lds_dwordx4 v[208:209], off
	v_lshl_add_u64 v[208:209], v[212:213], 0, s[60:61]
	s_mov_b32 m0, s58
	s_nop 0
	global_load_lds_dwordx4 v[208:209], off
	v_lshl_add_u64 v[208:209], v[218:219], 0, s[60:61]
	s_mov_b32 m0, s77
	s_nop 0
	global_load_lds_dwordx4 v[208:209], off
	s_waitcnt vmcnt(8)
	s_waitcnt lgkmcnt(0)
	s_barrier
	s_waitcnt lgkmcnt(0)
	v_mfma_f32_16x16x32_bf16 v[62:65], v[144:147], v[176:179], v[62:65]
	v_mfma_f32_16x16x32_bf16 v[58:61], v[152:155], v[176:179], v[58:61]
	v_mfma_f32_16x16x32_bf16 v[54:57], v[144:147], v[184:187], v[54:57]
	v_mfma_f32_16x16x32_bf16 v[50:53], v[152:155], v[184:187], v[50:53]
	v_mfma_f32_16x16x32_bf16 v[38:41], v[144:147], v[192:195], v[38:41]
	v_mfma_f32_16x16x32_bf16 v[34:37], v[152:155], v[192:195], v[34:37]
	v_mfma_f32_16x16x32_bf16 v[22:25], v[144:147], v[200:203], v[22:25]
	v_mfma_f32_16x16x32_bf16 v[18:21], v[152:155], v[200:203], v[18:21]
	v_mfma_f32_16x16x32_bf16 v[62:65], v[148:151], v[180:183], v[62:65]
	v_mfma_f32_16x16x32_bf16 v[58:61], v[156:159], v[180:183], v[58:61]
	v_mfma_f32_16x16x32_bf16 v[54:57], v[148:151], v[188:191], v[54:57]
	v_mfma_f32_16x16x32_bf16 v[50:53], v[156:159], v[188:191], v[50:53]
	v_mfma_f32_16x16x32_bf16 v[38:41], v[148:151], v[196:199], v[38:41]
	v_mfma_f32_16x16x32_bf16 v[34:37], v[156:159], v[196:199], v[34:37]
	v_mfma_f32_16x16x32_bf16 v[22:25], v[148:151], v[204:207], v[22:25]
	v_mfma_f32_16x16x32_bf16 v[18:21], v[156:159], v[204:207], v[18:21]
	v_mfma_f32_16x16x32_bf16 v[46:49], v[160:163], v[176:179], v[46:49]
	v_mfma_f32_16x16x32_bf16 v[42:45], v[168:171], v[176:179], v[42:45]
	v_mfma_f32_16x16x32_bf16 v[30:33], v[160:163], v[184:187], v[30:33]
	v_mfma_f32_16x16x32_bf16 v[26:29], v[168:171], v[184:187], v[26:29]
	v_mfma_f32_16x16x32_bf16 v[14:17], v[160:163], v[192:195], v[14:17]
	v_mfma_f32_16x16x32_bf16 v[10:13], v[168:171], v[192:195], v[10:13]
	v_mfma_f32_16x16x32_bf16 v[6:9], v[160:163], v[200:203], v[6:9]
	v_mfma_f32_16x16x32_bf16 v[2:5], v[168:171], v[200:203], v[2:5]
	v_mfma_f32_16x16x32_bf16 v[46:49], v[164:167], v[180:183], v[46:49]
	v_mfma_f32_16x16x32_bf16 v[42:45], v[172:175], v[180:183], v[42:45]
	v_mfma_f32_16x16x32_bf16 v[30:33], v[164:167], v[188:191], v[30:33]
	v_mfma_f32_16x16x32_bf16 v[26:29], v[172:175], v[188:191], v[26:29]
	v_mfma_f32_16x16x32_bf16 v[14:17], v[164:167], v[196:199], v[14:17]
	v_mfma_f32_16x16x32_bf16 v[10:13], v[172:175], v[196:199], v[10:13]
	v_mfma_f32_16x16x32_bf16 v[6:9], v[164:167], v[204:207], v[6:9]
	v_mfma_f32_16x16x32_bf16 v[2:5], v[172:175], v[204:207], v[2:5]
	s_barrier
	s_add_i32 s63, s63, 2
	s_add_u32 s96, s96, 0x100
	s_addc_u32 s62, s62, 0
	s_cmp_gt_u32 s63, 41
	s_mov_b64 s[82:83], s[86:87]
	s_cbranch_scc0 .LBB0_263
	s_and_b64 vcc, exec, s[22:23]
	s_cbranch_vccz .LBB0_266
	s_barrier

; #define PG8_STAGE(bufoff, gbase, voff) do { _Pragma("unroll") for (int _i = 0; _i < 2; ++_i) \
;         __builtin_amdgcn_global_load_lds((const unsigned*)((const char*)(gbase) + (voff)[_i]), (LAS unsigned*)(lds + (bufoff) + ldsw + _i * 8192), 16, 0, 0); } while (0)
; #define PG8_LDA(dst, b, h) do { _Pragma("unroll") for (int m = 0; m < 4; ++m) _Pragma("unroll") for (int k = 0; k < 2; ++k) dst[m][k] = *(const LAS bf16x8*)(lds + PG8_SA(b, h) + aoff + m * 2048 + k * 1024); } while (0)
; #define PG8_WAIT_V(n) asm volatile("s_waitcnt vmcnt(" #n ")" ::: "memory")
; #define PG8_WAIT_L(n) asm volatile("s_waitcnt lgkmcnt(" #n ")" ::: "memory")
; #define PG8_BAR __builtin_amdgcn_s_barrier()
; template <class EpiT, class Sched>
; __device__ __forceinline__ void gemm_phase(LAS unsigned char* lds, int tid_in, const GemmDesc g, const Sched& S, const EpiT& E) {
;     ...
;     for (;;) {
;         const bool has_next = S.next(ui + 1, nxt);
;         const char* nA = has_next ? g.A + nxt.aoff : cA; const char* nB = has_next ? g.Bt + nxt.boff : cB;
;         for (int t = 0; t < nt; t += 2) {
;             const bool last = (t == nt - 2);
;             const char* a1 = cA + (size_t)(t + 1) * kA;
;             const char* a2 = last ? nA : cA + (size_t)(t + 2) * kA; const char* b2 = last ? nB : cB + (size_t)(t + 2) * kB;
;             const char* a3 = a2 + kA; const char* b3 = b2 + kB;
;             PG8_LDB(B0, 0, 0); PG8_LDB(B1, 0, 1); PG8_SCHED; PG8_LDA(At, 0, 0); PG8_STAGE(PG8_SA(1, 1), a1 + hA, voffA);
;             PG8_WAIT_V(8); PG8_WAIT_L(0); PG8_BAR; PG8_MMA(0, 0, At, B0); PG8_MMA(0, 1, At, B1); PG8_BAR; PG8_SCHED;
;             PG8_LDA(At, 0, 1); PG8_STAGE(PG8_SB(0, 0), b2, voffB); PG8_STAGE(PG8_SB(0, 1), b2 + hB, voffB); PG8_STAGE(PG8_SA(0, 0), a2, voffA);
;             PG8_WAIT_V(8); PG8_WAIT_L(0); PG8_BAR; PG8_MMA(1, 0, At, B0); PG8_MMA(1, 1, At, B1); PG8_BAR; PG8_SCHED;
;             PG8_LDB(B0, 1, 0); PG8_LDB(B1, 1, 1); PG8_SCHED; PG8_LDA(At, 1, 0); PG8_STAGE(PG8_SA(0, 1), a2 + hA, voffA);
;             PG8_WAIT_V(8); PG8_WAIT_L(0); PG8_BAR; PG8_MMA(0, 0, At, B0); PG8_MMA(0, 1, At, B1); PG8_BAR; PG8_SCHED;
;             PG8_LDA(At, 1, 1); PG8_STAGE(PG8_SB(1, 0), b3, voffB); PG8_STAGE(PG8_SB(1, 1), b3 + hB, voffB); PG8_STAGE(PG8_SA(1, 0), a3, voffA);
;             PG8_WAIT_V(8); PG8_WAIT_L(0); PG8_BAR; PG8_MMA(1, 0, At, B0); PG8_MMA(1, 1, At, B1); PG8_BAR; PG8_SCHED;
.LBB0_341:
	s_add_u32 s10, vcc_lo, 0xfffc0080
	s_addc_u32 s11, vcc_hi, -1
	s_add_i32 s63, 0, 0x10000
	s_cmp_eq_u32 s62, 12
	s_cselect_b32 s95, s2, s11
	s_cselect_b32 s94, s3, s10
	v_add_u32_e32 v145, s63, v142
	s_cselect_b32 s93, s25, s90
	s_cselect_b32 s92, s31, s59
	s_add_i32 s91, 0, 0x14000
	ds_read_b128 v[146:149], v145
	ds_read_b128 v[150:153], v145 offset:1024
	ds_read_b128 v[154:157], v145 offset:2048
	ds_read_b128 v[158:161], v145 offset:3072
	v_add_u32_e32 v145, s91, v142
	ds_read_b128 v[162:165], v145
	ds_read_b128 v[166:169], v145 offset:1024
	ds_read_b128 v[170:173], v145 offset:2048
	ds_read_b128 v[174:177], v145 offset:3072
	v_lshl_add_u64 v[210:211], vcc, 0, v[136:137]
	s_add_i32 m0, s19, 0xc000
	ds_read_b128 v[178:181], v144
	ds_read_b128 v[182:185], v144 offset:1024
	ds_read_b128 v[186:189], v144 offset:2048
	ds_read_b128 v[190:193], v144 offset:3072
	ds_read_b128 v[194:197], v144 offset:4096
	ds_read_b128 v[198:201], v144 offset:5120
	ds_read_b128 v[202:205], v144 offset:6144
	ds_read_b128 v[206:209], v144 offset:7168
	global_load_lds_dwordx4 v[210:211], off
	v_lshl_add_u64 v[210:211], vcc, 0, v[138:139]
	s_add_i32 m0, s19, 0xe000
	s_nop 0
	global_load_lds_dwordx4 v[210:211], off
	s_waitcnt vmcnt(8)
	s_waitcnt lgkmcnt(0)
	s_barrier
	s_waitcnt lgkmcnt(0)
	v_mfma_f32_16x16x32_bf16 v[126:129], v[146:149], v[178:181], v[126:129]
	v_mfma_f32_16x16x32_bf16 v[122:125], v[154:157], v[178:181], v[122:125]
	v_mfma_f32_16x16x32_bf16 v[118:121], v[146:149], v[186:189], v[118:121]
	v_mfma_f32_16x16x32_bf16 v[114:117], v[154:157], v[186:189], v[114:117]
	v_mfma_f32_16x16x32_bf16 v[102:105], v[146:149], v[194:197], v[102:105]
	v_mfma_f32_16x16x32_bf16 v[98:101], v[154:157], v[194:197], v[98:101]
	v_mfma_f32_16x16x32_bf16 v[86:89], v[146:149], v[202:205], v[86:89]
	v_mfma_f32_16x16x32_bf16 v[82:85], v[154:157], v[202:205], v[82:85]
	v_mfma_f32_16x16x32_bf16 v[126:129], v[150:153], v[182:185], v[126:129]
	v_mfma_f32_16x16x32_bf16 v[122:125], v[158:161], v[182:185], v[122:125]
	v_mfma_f32_16x16x32_bf16 v[118:121], v[150:153], v[190:193], v[118:121]
	v_mfma_f32_16x16x32_bf16 v[114:117], v[158:161], v[190:193], v[114:117]
	v_mfma_f32_16x16x32_bf16 v[102:105], v[150:153], v[198:201], v[102:105]
	v_mfma_f32_16x16x32_bf16 v[98:101], v[158:161], v[198:201], v[98:101]
	v_mfma_f32_16x16x32_bf16 v[86:89], v[150:153], v[206:209], v[86:89]
	v_mfma_f32_16x16x32_bf16 v[82:85], v[158:161], v[206:209], v[82:85]
	v_mfma_f32_16x16x32_bf16 v[110:113], v[162:165], v[178:181], v[110:113]
	v_mfma_f32_16x16x32_bf16 v[106:109], v[170:173], v[178:181], v[106:109]
	v_mfma_f32_16x16x32_bf16 v[94:97], v[162:165], v[186:189], v[94:97]
	v_mfma_f32_16x16x32_bf16 v[90:93], v[170:173], v[186:189], v[90:93]
	v_mfma_f32_16x16x32_bf16 v[78:81], v[162:165], v[194:197], v[78:81]
	v_mfma_f32_16x16x32_bf16 v[74:77], v[170:173], v[194:197], v[74:77]
	v_mfma_f32_16x16x32_bf16 v[70:73], v[162:165], v[202:205], v[70:73]
	v_mfma_f32_16x16x32_bf16 v[66:69], v[170:173], v[202:205], v[66:69]
	v_mfma_f32_16x16x32_bf16 v[110:113], v[166:169], v[182:185], v[110:113]
	v_mfma_f32_16x16x32_bf16 v[106:109], v[174:177], v[182:185], v[106:109]
	v_mfma_f32_16x16x32_bf16 v[94:97], v[166:169], v[190:193], v[94:97]
	v_mfma_f32_16x16x32_bf16 v[90:93], v[174:177], v[190:193], v[90:93]
	v_mfma_f32_16x16x32_bf16 v[78:81], v[166:169], v[198:201], v[78:81]
	v_mfma_f32_16x16x32_bf16 v[74:77], v[174:177], v[198:201], v[74:77]
	v_mfma_f32_16x16x32_bf16 v[70:73], v[166:169], v[206:209], v[70:73]
	v_mfma_f32_16x16x32_bf16 v[66:69], v[174:177], v[206:209], v[66:69]
	s_barrier
	s_add_i32 s10, s63, s74
	v_lshl_add_u64 v[210:211], s[92:93], 0, v[0:1]
	s_mov_b32 m0, s10
	ds_read_b128 v[178:181], v144 offset:16384
	ds_read_b128 v[182:185], v144 offset:17408
	ds_read_b128 v[186:189], v144 offset:18432
	ds_read_b128 v[190:193], v144 offset:19456
	ds_read_b128 v[194:197], v144 offset:20480
	ds_read_b128 v[198:201], v144 offset:21504
	ds_read_b128 v[202:205], v144 offset:22528
	ds_read_b128 v[206:209], v144 offset:23552
	global_load_lds_dwordx4 v[210:211], off
	s_add_i32 m0, s10, 0x2000
	s_add_u32 s10, s92, 0x40000
	v_lshl_add_u64 v[212:213], s[92:93], 0, v[134:135]
	s_addc_u32 s11, s93, 0
	s_add_i32 s63, s91, s74
	global_load_lds_dwordx4 v[212:213], off
	v_lshl_add_u64 v[218:219], s[10:11], 0, v[0:1]
	s_mov_b32 m0, s63
	v_lshl_add_u64 v[220:221], s[94:95], 0, v[132:133]
	global_load_lds_dwordx4 v[218:219], off
	v_lshl_add_u64 v[218:219], s[10:11], 0, v[134:135]
	s_add_i32 m0, s63, 0x2000
	s_nop 0
	global_load_lds_dwordx4 v[218:219], off
	v_lshl_add_u64 v[218:219], s[94:95], 0, v[130:131]
	s_mov_b32 m0, s19
	s_nop 0
	global_load_lds_dwordx4 v[218:219], off
	s_mov_b32 m0, s75
	s_nop 0
	global_load_lds_dwordx4 v[220:221], off
	s_waitcnt vmcnt(8)
	s_waitcnt lgkmcnt(0)
	s_barrier
; #define PG8_STAGE(bufoff, gbase, voff) do { _Pragma("unroll") for (int _i = 0; _i < 2; ++_i) \
;         __builtin_amdgcn_global_load_lds((const unsigned*)((const char*)(gbase) + (voff)[_i]), (LAS unsigned*)(lds + (bufoff) + ldsw + _i * 8192), 16, 0, 0); } while (0)
; #define PG8_LDA(dst, b, h) do { _Pragma("unroll") for (int m = 0; m < 4; ++m) _Pragma("unroll") for (int k = 0; k < 2; ++k) dst[m][k] = *(const LAS bf16x8*)(lds + PG8_SA(b, h) + aoff + m * 2048 + k * 1024); } while (0)
; #define PG8_LDB(dst, b, h) do { _Pragma("unroll") for (int n = 0; n < 2; ++n) _Pragma("unroll") for (int k = 0; k < 2; ++k) dst[n][k] = *(const LAS bf16x8*)(lds + PG8_SB(b, h) + boff + n * 2048 + k * 1024); } while (0)
; #define PG8_MMA(ai, bj, At, Bt) do { __builtin_amdgcn_s_setprio(1); _Pragma("unroll") for (int m = 0; m < 4; ++m) _Pragma("unroll") for (int n = 0; n < 2; ++n) _Pragma("unroll") for (int k = 0; k < 2; ++k) \
;         acc[ai][bj][m][n] = __builtin_amdgcn_mfma_f32_16x16x32_bf16(Bt[n][k], At[m][k], acc[ai][bj][m][n], 0, 0, 0); __builtin_amdgcn_s_setprio(0); } while (0)
; #define PG8_WAIT_V(n) asm volatile("s_waitcnt vmcnt(" #n ")" ::: "memory")
; #define PG8_WAIT_L(n) asm volatile("s_waitcnt lgkmcnt(" #n ")" ::: "memory")
; #define PG8_BAR __builtin_amdgcn_s_barrier()
; #define PG8_SCHED __builtin_amdgcn_sched_barrier(0)
; template <class EpiT, class Sched>
; __device__ __forceinline__ void gemm_phase(LAS unsigned char* lds, int tid_in, const GemmDesc g, const Sched& S, const EpiT& E) {
;     ...
;             PG8_WAIT_V(8); PG8_WAIT_L(0); PG8_BAR; PG8_MMA(1, 0, At, B0); PG8_MMA(1, 1, At, B1); PG8_BAR; PG8_SCHED;
;             PG8_LDB(B0, 1, 0); PG8_LDB(B1, 1, 1); PG8_SCHED; PG8_LDA(At, 1, 0); PG8_STAGE(PG8_SA(0, 1), a2 + hA, voffA);
;             PG8_WAIT_V(8); PG8_WAIT_L(0); PG8_BAR; PG8_MMA(0, 0, At, B0); PG8_MMA(0, 1, At, B1); PG8_BAR; PG8_SCHED;
;             PG8_LDA(At, 1, 1); PG8_STAGE(PG8_SB(1, 0), b3, voffB); PG8_STAGE(PG8_SB(1, 1), b3 + hB, voffB); PG8_STAGE(PG8_SA(1, 0), a3, voffA);
;             PG8_WAIT_V(8); PG8_WAIT_L(0); PG8_BAR; PG8_MMA(1, 0, At, B0); PG8_MMA(1, 1, At, B1); PG8_BAR; PG8_SCHED;
	s_waitcnt lgkmcnt(0)
	v_mfma_f32_16x16x32_bf16 v[62:65], v[146:149], v[178:181], v[62:65]
	v_mfma_f32_16x16x32_bf16 v[58:61], v[154:157], v[178:181], v[58:61]
	v_mfma_f32_16x16x32_bf16 v[54:57], v[146:149], v[186:189], v[54:57]
	v_mfma_f32_16x16x32_bf16 v[50:53], v[154:157], v[186:189], v[50:53]
	v_mfma_f32_16x16x32_bf16 v[38:41], v[146:149], v[194:197], v[38:41]
	v_mfma_f32_16x16x32_bf16 v[34:37], v[154:157], v[194:197], v[34:37]
	v_mfma_f32_16x16x32_bf16 v[22:25], v[146:149], v[202:205], v[22:25]
	v_mfma_f32_16x16x32_bf16 v[18:21], v[154:157], v[202:205], v[18:21]
	v_mfma_f32_16x16x32_bf16 v[62:65], v[150:153], v[182:185], v[62:65]
	v_mfma_f32_16x16x32_bf16 v[58:61], v[158:161], v[182:185], v[58:61]
	v_mfma_f32_16x16x32_bf16 v[54:57], v[150:153], v[190:193], v[54:57]
	v_mfma_f32_16x16x32_bf16 v[50:53], v[158:161], v[190:193], v[50:53]
	v_mfma_f32_16x16x32_bf16 v[38:41], v[150:153], v[198:201], v[38:41]
	v_mfma_f32_16x16x32_bf16 v[34:37], v[158:161], v[198:201], v[34:37]
	v_mfma_f32_16x16x32_bf16 v[22:25], v[150:153], v[206:209], v[22:25]
	v_mfma_f32_16x16x32_bf16 v[18:21], v[158:161], v[206:209], v[18:21]
	v_mfma_f32_16x16x32_bf16 v[46:49], v[162:165], v[178:181], v[46:49]
	v_mfma_f32_16x16x32_bf16 v[42:45], v[170:173], v[178:181], v[42:45]
	v_mfma_f32_16x16x32_bf16 v[30:33], v[162:165], v[186:189], v[30:33]
	v_mfma_f32_16x16x32_bf16 v[26:29], v[170:173], v[186:189], v[26:29]
	v_mfma_f32_16x16x32_bf16 v[14:17], v[162:165], v[194:197], v[14:17]
	v_mfma_f32_16x16x32_bf16 v[10:13], v[170:173], v[194:197], v[10:13]
	v_mfma_f32_16x16x32_bf16 v[6:9], v[162:165], v[202:205], v[6:9]
	v_mfma_f32_16x16x32_bf16 v[2:5], v[170:173], v[202:205], v[2:5]
	v_mfma_f32_16x16x32_bf16 v[46:49], v[166:169], v[182:185], v[46:49]
	v_mfma_f32_16x16x32_bf16 v[42:45], v[174:177], v[182:185], v[42:45]
	v_mfma_f32_16x16x32_bf16 v[30:33], v[166:169], v[190:193], v[30:33]
	v_mfma_f32_16x16x32_bf16 v[26:29], v[174:177], v[190:193], v[26:29]
	v_mfma_f32_16x16x32_bf16 v[14:17], v[166:169], v[198:201], v[14:17]
	v_mfma_f32_16x16x32_bf16 v[10:13], v[174:177], v[198:201], v[10:13]
	v_mfma_f32_16x16x32_bf16 v[6:9], v[166:169], v[206:209], v[6:9]
	v_mfma_f32_16x16x32_bf16 v[2:5], v[174:177], v[206:209], v[2:5]
	s_barrier
	s_add_i32 s63, 0, 0x18000
	v_add_u32_e32 v145, s63, v142
	s_add_i32 s91, 0, 0x1c000
	ds_read_b128 v[146:149], v145
	ds_read_b128 v[150:153], v145 offset:1024
	ds_read_b128 v[154:157], v145 offset:2048
	ds_read_b128 v[158:161], v145 offset:3072
	v_add_u32_e32 v145, s91, v142
	ds_read_b128 v[162:165], v145
	ds_read_b128 v[166:169], v145 offset:1024
	ds_read_b128 v[170:173], v145 offset:2048
	ds_read_b128 v[174:177], v145 offset:3072
	s_add_u32 s10, s94, 0x40000
	s_addc_u32 s11, s95, 0
	s_mov_b32 m0, s76
	v_lshl_add_u64 v[222:223], s[10:11], 0, v[130:131]
	ds_read_b128 v[178:181], v144 offset:32768
	ds_read_b128 v[182:185], v144 offset:33792
	ds_read_b128 v[186:189], v144 offset:34816
	ds_read_b128 v[190:193], v144 offset:35840
	ds_read_b128 v[194:197], v144 offset:36864
	ds_read_b128 v[198:201], v144 offset:37888
	ds_read_b128 v[202:205], v144 offset:38912
	ds_read_b128 v[206:209], v144 offset:39936
	global_load_lds_dwordx4 v[222:223], off
	v_lshl_add_u64 v[222:223], s[10:11], 0, v[132:133]
	s_mov_b32 m0, s77
	s_nop 0
	global_load_lds_dwordx4 v[222:223], off
	s_waitcnt vmcnt(8)
	s_waitcnt lgkmcnt(0)
	s_barrier
	s_waitcnt lgkmcnt(0)
	v_mfma_f32_16x16x32_bf16 v[126:129], v[146:149], v[178:181], v[126:129]
	v_mfma_f32_16x16x32_bf16 v[122:125], v[154:157], v[178:181], v[122:125]
	v_mfma_f32_16x16x32_bf16 v[118:121], v[146:149], v[186:189], v[118:121]
	v_mfma_f32_16x16x32_bf16 v[114:117], v[154:157], v[186:189], v[114:117]
	v_mfma_f32_16x16x32_bf16 v[102:105], v[146:149], v[194:197], v[102:105]
	v_mfma_f32_16x16x32_bf16 v[98:101], v[154:157], v[194:197], v[98:101]
	v_mfma_f32_16x16x32_bf16 v[86:89], v[146:149], v[202:205], v[86:89]
	v_mfma_f32_16x16x32_bf16 v[82:85], v[154:157], v[202:205], v[82:85]
	v_mfma_f32_16x16x32_bf16 v[126:129], v[150:153], v[182:185], v[126:129]
	v_mfma_f32_16x16x32_bf16 v[122:125], v[158:161], v[182:185], v[122:125]
	v_mfma_f32_16x16x32_bf16 v[118:121], v[150:153], v[190:193], v[118:121]
	v_mfma_f32_16x16x32_bf16 v[114:117], v[158:161], v[190:193], v[114:117]
	v_mfma_f32_16x16x32_bf16 v[102:105], v[150:153], v[198:201], v[102:105]
	v_mfma_f32_16x16x32_bf16 v[98:101], v[158:161], v[198:201], v[98:101]
	v_mfma_f32_16x16x32_bf16 v[86:89], v[150:153], v[206:209], v[86:89]
	v_mfma_f32_16x16x32_bf16 v[82:85], v[158:161], v[206:209], v[82:85]
	v_mfma_f32_16x16x32_bf16 v[110:113], v[162:165], v[178:181], v[110:113]
	v_mfma_f32_16x16x32_bf16 v[106:109], v[170:173], v[178:181], v[106:109]
	v_mfma_f32_16x16x32_bf16 v[94:97], v[162:165], v[186:189], v[94:97]
	v_mfma_f32_16x16x32_bf16 v[90:93], v[170:173], v[186:189], v[90:93]
	v_mfma_f32_16x16x32_bf16 v[78:81], v[162:165], v[194:197], v[78:81]
	v_mfma_f32_16x16x32_bf16 v[74:77], v[170:173], v[194:197], v[74:77]
	v_mfma_f32_16x16x32_bf16 v[70:73], v[162:165], v[202:205], v[70:73]
	v_mfma_f32_16x16x32_bf16 v[66:69], v[170:173], v[202:205], v[66:69]
	v_mfma_f32_16x16x32_bf16 v[110:113], v[166:169], v[182:185], v[110:113]
	v_mfma_f32_16x16x32_bf16 v[106:109], v[174:177], v[182:185], v[106:109]
	v_mfma_f32_16x16x32_bf16 v[94:97], v[166:169], v[190:193], v[94:97]
	v_mfma_f32_16x16x32_bf16 v[90:93], v[174:177], v[190:193], v[90:93]
	v_mfma_f32_16x16x32_bf16 v[78:81], v[166:169], v[198:201], v[78:81]
	v_mfma_f32_16x16x32_bf16 v[74:77], v[174:177], v[198:201], v[74:77]
	v_mfma_f32_16x16x32_bf16 v[70:73], v[166:169], v[206:209], v[70:73]
	v_mfma_f32_16x16x32_bf16 v[66:69], v[174:177], v[206:209], v[66:69]
	s_barrier
; #define PG8_STAGE(bufoff, gbase, voff) do { _Pragma("unroll") for (int _i = 0; _i < 2; ++_i) \
;         __builtin_amdgcn_global_load_lds((const unsigned*)((const char*)(gbase) + (voff)[_i]), (LAS unsigned*)(lds + (bufoff) + ldsw + _i * 8192), 16, 0, 0); } while (0)
; #define PG8_LDA(dst, b, h) do { _Pragma("unroll") for (int m = 0; m < 4; ++m) _Pragma("unroll") for (int k = 0; k < 2; ++k) dst[m][k] = *(const LAS bf16x8*)(lds + PG8_SA(b, h) + aoff + m * 2048 + k * 1024); } while (0)
; #define PG8_LDB(dst, b, h) do { _Pragma("unroll") for (int n = 0; n < 2; ++n) _Pragma("unroll") for (int k = 0; k < 2; ++k) dst[n][k] = *(const LAS bf16x8*)(lds + PG8_SB(b, h) + boff + n * 2048 + k * 1024); } while (0)
; #define PG8_MMA(ai, bj, At, Bt) do { __builtin_amdgcn_s_setprio(1); _Pragma("unroll") for (int m = 0; m < 4; ++m) _Pragma("unroll") for (int n = 0; n < 2; ++n) _Pragma("unroll") for (int k = 0; k < 2; ++k) \
;         acc[ai][bj][m][n] = __builtin_amdgcn_mfma_f32_16x16x32_bf16(Bt[n][k], At[m][k], acc[ai][bj][m][n], 0, 0, 0); __builtin_amdgcn_s_setprio(0); } while (0)
; #define PG8_WAIT_V(n) asm volatile("s_waitcnt vmcnt(" #n ")" ::: "memory")
; #define PG8_WAIT_L(n) asm volatile("s_waitcnt lgkmcnt(" #n ")" ::: "memory")
; #define PG8_BAR __builtin_amdgcn_s_barrier()
; #define PG8_SCHED __builtin_amdgcn_sched_barrier(0)
; template <class EpiT, class Sched>
; __device__ __forceinline__ void gemm_phase(LAS unsigned char* lds, int tid_in, const GemmDesc g, const Sched& S, const EpiT& E) {
;     ...
;             PG8_LDB(B0, 1, 0); PG8_LDB(B1, 1, 1); PG8_SCHED; PG8_LDA(At, 1, 0); PG8_STAGE(PG8_SA(0, 1), a2 + hA, voffA);
;             PG8_WAIT_V(8); PG8_WAIT_L(0); PG8_BAR; PG8_MMA(0, 0, At, B0); PG8_MMA(0, 1, At, B1); PG8_BAR; PG8_SCHED;
;             PG8_LDA(At, 1, 1); PG8_STAGE(PG8_SB(1, 0), b3, voffB); PG8_STAGE(PG8_SB(1, 1), b3 + hB, voffB); PG8_STAGE(PG8_SA(1, 0), a3, voffA);
;             PG8_WAIT_V(8); PG8_WAIT_L(0); PG8_BAR; PG8_MMA(1, 0, At, B0); PG8_MMA(1, 1, At, B1); PG8_BAR; PG8_SCHED;
	s_add_i32 s10, s63, s74
	v_lshl_add_u64 v[210:211], v[210:211], 0, s[60:61]
	s_mov_b32 m0, s10
	ds_read_b128 v[178:181], v144 offset:49152
	ds_read_b128 v[182:185], v144 offset:50176
	ds_read_b128 v[186:189], v144 offset:51200
	ds_read_b128 v[190:193], v144 offset:52224
	ds_read_b128 v[194:197], v144 offset:53248
	ds_read_b128 v[198:201], v144 offset:54272
	ds_read_b128 v[202:205], v144 offset:55296
	ds_read_b128 v[206:209], v144 offset:56320
	global_load_lds_dwordx4 v[210:211], off
	s_add_i32 m0, s10, 0x2000
	s_add_u32 s10, s92, 0x40080
	v_lshl_add_u64 v[210:211], v[212:213], 0, s[60:61]
	s_addc_u32 s11, s93, 0
	s_add_i32 s63, s91, s74
	global_load_lds_dwordx4 v[210:211], off
	v_lshl_add_u64 v[210:211], s[10:11], 0, v[0:1]
	s_mov_b32 m0, s63
	s_nop 0
	global_load_lds_dwordx4 v[210:211], off
	v_lshl_add_u64 v[210:211], s[10:11], 0, v[134:135]
	s_add_i32 m0, s63, 0x2000
	s_nop 0
	global_load_lds_dwordx4 v[210:211], off
	v_lshl_add_u64 v[210:211], v[218:219], 0, s[60:61]
	s_mov_b32 m0, s6
	s_nop 0
	global_load_lds_dwordx4 v[210:211], off
	v_lshl_add_u64 v[210:211], v[220:221], 0, s[60:61]
	s_mov_b32 m0, s58
	s_nop 0
	global_load_lds_dwordx4 v[210:211], off
	s_waitcnt vmcnt(8)
	s_waitcnt lgkmcnt(0)
	s_barrier
	s_waitcnt lgkmcnt(0)
	v_mfma_f32_16x16x32_bf16 v[62:65], v[146:149], v[178:181], v[62:65]
	v_mfma_f32_16x16x32_bf16 v[58:61], v[154:157], v[178:181], v[58:61]
	v_mfma_f32_16x16x32_bf16 v[54:57], v[146:149], v[186:189], v[54:57]
	v_mfma_f32_16x16x32_bf16 v[50:53], v[154:157], v[186:189], v[50:53]
	v_mfma_f32_16x16x32_bf16 v[38:41], v[146:149], v[194:197], v[38:41]
	v_mfma_f32_16x16x32_bf16 v[34:37], v[154:157], v[194:197], v[34:37]
	v_mfma_f32_16x16x32_bf16 v[22:25], v[146:149], v[202:205], v[22:25]
	v_mfma_f32_16x16x32_bf16 v[18:21], v[154:157], v[202:205], v[18:21]
	v_mfma_f32_16x16x32_bf16 v[62:65], v[150:153], v[182:185], v[62:65]
	v_mfma_f32_16x16x32_bf16 v[58:61], v[158:161], v[182:185], v[58:61]
	v_mfma_f32_16x16x32_bf16 v[54:57], v[150:153], v[190:193], v[54:57]
	v_mfma_f32_16x16x32_bf16 v[50:53], v[158:161], v[190:193], v[50:53]
	v_mfma_f32_16x16x32_bf16 v[38:41], v[150:153], v[198:201], v[38:41]
	v_mfma_f32_16x16x32_bf16 v[34:37], v[158:161], v[198:201], v[34:37]
	v_mfma_f32_16x16x32_bf16 v[22:25], v[150:153], v[206:209], v[22:25]
	v_mfma_f32_16x16x32_bf16 v[18:21], v[158:161], v[206:209], v[18:21]
	v_mfma_f32_16x16x32_bf16 v[46:49], v[162:165], v[178:181], v[46:49]
	v_mfma_f32_16x16x32_bf16 v[42:45], v[170:173], v[178:181], v[42:45]
	v_mfma_f32_16x16x32_bf16 v[30:33], v[162:165], v[186:189], v[30:33]
	v_mfma_f32_16x16x32_bf16 v[26:29], v[170:173], v[186:189], v[26:29]
	v_mfma_f32_16x16x32_bf16 v[14:17], v[162:165], v[194:197], v[14:17]
	v_mfma_f32_16x16x32_bf16 v[10:13], v[170:173], v[194:197], v[10:13]
	v_mfma_f32_16x16x32_bf16 v[6:9], v[162:165], v[202:205], v[6:9]
	v_mfma_f32_16x16x32_bf16 v[2:5], v[170:173], v[202:205], v[2:5]
	v_mfma_f32_16x16x32_bf16 v[46:49], v[166:169], v[182:185], v[46:49]
	v_mfma_f32_16x16x32_bf16 v[42:45], v[174:177], v[182:185], v[42:45]
	v_mfma_f32_16x16x32_bf16 v[30:33], v[166:169], v[190:193], v[30:33]
	v_mfma_f32_16x16x32_bf16 v[26:29], v[174:177], v[190:193], v[26:29]
	v_mfma_f32_16x16x32_bf16 v[14:17], v[166:169], v[198:201], v[14:17]
	v_mfma_f32_16x16x32_bf16 v[10:13], v[174:177], v[198:201], v[10:13]
	v_mfma_f32_16x16x32_bf16 v[6:9], v[166:169], v[206:209], v[6:9]
	v_mfma_f32_16x16x32_bf16 v[2:5], v[174:177], v[206:209], v[2:5]
	s_barrier
	s_add_i32 s62, s62, 2
	s_add_u32 vcc_lo, vcc_lo, 0x100
	s_addc_u32 vcc_hi, vcc_hi, 0
	s_add_u32 s59, s59, 0x100
	s_addc_u32 s90, s90, 0
	s_cmp_gt_u32 s62, 13
	s_cbranch_scc0 .LBB0_341
	s_and_b64 vcc, exec, s[12:13]
	s_cbranch_vccz .LBB0_344
	s_barrier

; #define PG8_STAGE(bufoff, gbase, voff) do { _Pragma("unroll") for (int _i = 0; _i < 2; ++_i) \
;         __builtin_amdgcn_global_load_lds((const unsigned*)((const char*)(gbase) + (voff)[_i]), (LAS unsigned*)(lds + (bufoff) + ldsw + _i * 8192), 16, 0, 0); } while (0)
; #define PG8_LDA(dst, b, h) do { _Pragma("unroll") for (int m = 0; m < 4; ++m) _Pragma("unroll") for (int k = 0; k < 2; ++k) dst[m][k] = *(const LAS bf16x8*)(lds + PG8_SA(b, h) + aoff + m * 2048 + k * 1024); } while (0)
; #define PG8_WAIT_V(n) asm volatile("s_waitcnt vmcnt(" #n ")" ::: "memory")
; #define PG8_WAIT_L(n) asm volatile("s_waitcnt lgkmcnt(" #n ")" ::: "memory")
; #define PG8_BAR __builtin_amdgcn_s_barrier()
; template <class EpiT, class Sched>
; __device__ __forceinline__ void gemm_phase(LAS unsigned char* lds, int tid_in, const GemmDesc g, const Sched& S, const EpiT& E) {
;     ...
;     for (;;) {
;         const bool has_next = S.next(ui + 1, nxt);
;         const char* nA = has_next ? g.A + nxt.aoff : cA; const char* nB = has_next ? g.Bt + nxt.boff : cB;
;         for (int t = 0; t < nt; t += 2) {
;             const bool last = (t == nt - 2);
;             const char* a1 = cA + (size_t)(t + 1) * kA;
;             const char* a2 = last ? nA : cA + (size_t)(t + 2) * kA; const char* b2 = last ? nB : cB + (size_t)(t + 2) * kB;
;             const char* a3 = a2 + kA; const char* b3 = b2 + kB;
;             PG8_LDB(B0, 0, 0); PG8_LDB(B1, 0, 1); PG8_SCHED; PG8_LDA(At, 0, 0); PG8_STAGE(PG8_SA(1, 1), a1 + hA, voffA);
;             PG8_WAIT_V(8); PG8_WAIT_L(0); PG8_BAR; PG8_MMA(0, 0, At, B0); PG8_MMA(0, 1, At, B1); PG8_BAR; PG8_SCHED;
;             PG8_LDA(At, 0, 1); PG8_STAGE(PG8_SB(0, 0), b2, voffB); PG8_STAGE(PG8_SB(0, 1), b2 + hB, voffB); PG8_STAGE(PG8_SA(0, 0), a2, voffA);
;             PG8_WAIT_V(8); PG8_WAIT_L(0); PG8_BAR; PG8_MMA(1, 0, At, B0); PG8_MMA(1, 1, At, B1); PG8_BAR; PG8_SCHED;
;             PG8_LDB(B0, 1, 0); PG8_LDB(B1, 1, 1); PG8_SCHED; PG8_LDA(At, 1, 0); PG8_STAGE(PG8_SA(0, 1), a2 + hA, voffA);
;             PG8_WAIT_V(8); PG8_WAIT_L(0); PG8_BAR; PG8_MMA(0, 0, At, B0); PG8_MMA(0, 1, At, B1); PG8_BAR; PG8_SCHED;
;             PG8_LDA(At, 1, 1); PG8_STAGE(PG8_SB(1, 0), b3, voffB); PG8_STAGE(PG8_SB(1, 1), b3 + hB, voffB); PG8_STAGE(PG8_SA(1, 0), a3, voffA);
;             PG8_WAIT_V(8); PG8_WAIT_L(0); PG8_BAR; PG8_MMA(1, 0, At, B0); PG8_MMA(1, 1, At, B1); PG8_BAR; PG8_SCHED;
.LBB0_411:
	s_add_u32 s10, vcc_lo, 0xfffc0080
	s_addc_u32 s11, vcc_hi, -1
	s_add_i32 s63, 0, 0x10000
	s_cmp_eq_u32 s62, 12
	s_cselect_b32 s95, s2, s11
	s_cselect_b32 s94, s3, s10
	s_cselect_b32 s93, s31, s81
	s_cselect_b32 s92, s35, s59
	s_add_i32 s90, 0, 0x14000
	v_add_u32_e32 v156, s63, v141
	v_add_u32_e32 v172, s90, v141
	ds_read_b128 v[144:147], v156
	ds_read_b128 v[148:151], v156 offset:1024
	ds_read_b128 v[152:155], v156 offset:2048
	ds_read_b128 v[156:159], v156 offset:3072
	ds_read_b128 v[160:163], v172
	ds_read_b128 v[164:167], v172 offset:1024
	ds_read_b128 v[168:171], v172 offset:2048
	ds_read_b128 v[172:175], v172 offset:3072
	v_lshl_add_u64 v[208:209], vcc, 0, v[136:137]
	s_add_i32 m0, s23, 0xc000
	ds_read_b128 v[176:179], v143
	ds_read_b128 v[180:183], v143 offset:1024
	ds_read_b128 v[184:187], v143 offset:2048
	ds_read_b128 v[188:191], v143 offset:3072
	ds_read_b128 v[192:195], v143 offset:4096
	ds_read_b128 v[196:199], v143 offset:5120
	ds_read_b128 v[200:203], v143 offset:6144
	ds_read_b128 v[204:207], v143 offset:7168
	global_load_lds_dwordx4 v[208:209], off
	v_lshl_add_u64 v[208:209], vcc, 0, v[138:139]
	s_add_i32 m0, s23, 0xe000
	s_nop 0
	global_load_lds_dwordx4 v[208:209], off
	s_waitcnt vmcnt(8)
	s_waitcnt lgkmcnt(0)
	s_barrier
	s_waitcnt lgkmcnt(0)
	v_mfma_f32_16x16x32_bf16 v[126:129], v[144:147], v[176:179], v[126:129]
	v_mfma_f32_16x16x32_bf16 v[122:125], v[152:155], v[176:179], v[122:125]
	v_mfma_f32_16x16x32_bf16 v[118:121], v[144:147], v[184:187], v[118:121]
	v_mfma_f32_16x16x32_bf16 v[114:117], v[152:155], v[184:187], v[114:117]
	v_mfma_f32_16x16x32_bf16 v[102:105], v[144:147], v[192:195], v[102:105]
	v_mfma_f32_16x16x32_bf16 v[98:101], v[152:155], v[192:195], v[98:101]
	v_mfma_f32_16x16x32_bf16 v[86:89], v[144:147], v[200:203], v[86:89]
	v_mfma_f32_16x16x32_bf16 v[82:85], v[152:155], v[200:203], v[82:85]
	v_mfma_f32_16x16x32_bf16 v[126:129], v[148:151], v[180:183], v[126:129]
	v_mfma_f32_16x16x32_bf16 v[122:125], v[156:159], v[180:183], v[122:125]
	v_mfma_f32_16x16x32_bf16 v[118:121], v[148:151], v[188:191], v[118:121]
	v_mfma_f32_16x16x32_bf16 v[114:117], v[156:159], v[188:191], v[114:117]
	v_mfma_f32_16x16x32_bf16 v[102:105], v[148:151], v[196:199], v[102:105]
	v_mfma_f32_16x16x32_bf16 v[98:101], v[156:159], v[196:199], v[98:101]
	v_mfma_f32_16x16x32_bf16 v[86:89], v[148:151], v[204:207], v[86:89]
	v_mfma_f32_16x16x32_bf16 v[82:85], v[156:159], v[204:207], v[82:85]
	v_mfma_f32_16x16x32_bf16 v[110:113], v[160:163], v[176:179], v[110:113]
	v_mfma_f32_16x16x32_bf16 v[106:109], v[168:171], v[176:179], v[106:109]
	v_mfma_f32_16x16x32_bf16 v[94:97], v[160:163], v[184:187], v[94:97]
	v_mfma_f32_16x16x32_bf16 v[90:93], v[168:171], v[184:187], v[90:93]
	v_mfma_f32_16x16x32_bf16 v[78:81], v[160:163], v[192:195], v[78:81]
	v_mfma_f32_16x16x32_bf16 v[74:77], v[168:171], v[192:195], v[74:77]
	v_mfma_f32_16x16x32_bf16 v[70:73], v[160:163], v[200:203], v[70:73]
	v_mfma_f32_16x16x32_bf16 v[66:69], v[168:171], v[200:203], v[66:69]
	v_mfma_f32_16x16x32_bf16 v[110:113], v[164:167], v[180:183], v[110:113]
	v_mfma_f32_16x16x32_bf16 v[106:109], v[172:175], v[180:183], v[106:109]
	v_mfma_f32_16x16x32_bf16 v[94:97], v[164:167], v[188:191], v[94:97]
	v_mfma_f32_16x16x32_bf16 v[90:93], v[172:175], v[188:191], v[90:93]
	v_mfma_f32_16x16x32_bf16 v[78:81], v[164:167], v[196:199], v[78:81]
	v_mfma_f32_16x16x32_bf16 v[74:77], v[172:175], v[196:199], v[74:77]
	v_mfma_f32_16x16x32_bf16 v[70:73], v[164:167], v[204:207], v[70:73]
	v_mfma_f32_16x16x32_bf16 v[66:69], v[172:175], v[204:207], v[66:69]
	s_barrier
	s_add_i32 s10, s63, s71
	v_lshl_add_u64 v[208:209], s[92:93], 0, v[0:1]
	s_mov_b32 m0, s10
	ds_read_b128 v[176:179], v143 offset:16384
	ds_read_b128 v[180:183], v143 offset:17408
	ds_read_b128 v[184:187], v143 offset:18432
	ds_read_b128 v[188:191], v143 offset:19456
	ds_read_b128 v[192:195], v143 offset:20480
	ds_read_b128 v[196:199], v143 offset:21504
	ds_read_b128 v[200:203], v143 offset:22528
	ds_read_b128 v[204:207], v143 offset:23552
	global_load_lds_dwordx4 v[208:209], off
	s_add_i32 m0, s10, 0x2000
	s_add_u32 s10, s92, 0x40000
	v_lshl_add_u64 v[210:211], s[92:93], 0, v[130:131]
	s_addc_u32 s11, s93, 0
	s_add_i32 s63, s90, s71
	global_load_lds_dwordx4 v[210:211], off
	v_lshl_add_u64 v[212:213], s[10:11], 0, v[0:1]
	s_mov_b32 m0, s63
	v_lshl_add_u64 v[218:219], s[94:95], 0, v[132:133]
	global_load_lds_dwordx4 v[212:213], off
	v_lshl_add_u64 v[212:213], s[10:11], 0, v[130:131]
	s_add_i32 m0, s63, 0x2000
	s_nop 0
	global_load_lds_dwordx4 v[212:213], off
	v_lshl_add_u64 v[212:213], s[94:95], 0, v[134:135]
	s_mov_b32 m0, s23
	s_nop 0
	global_load_lds_dwordx4 v[212:213], off
	s_mov_b32 m0, s73
	s_nop 0
	global_load_lds_dwordx4 v[218:219], off
	s_waitcnt vmcnt(8)
	s_waitcnt lgkmcnt(0)
	s_barrier
; #define PG8_STAGE(bufoff, gbase, voff) do { _Pragma("unroll") for (int _i = 0; _i < 2; ++_i) \
;         __builtin_amdgcn_global_load_lds((const unsigned*)((const char*)(gbase) + (voff)[_i]), (LAS unsigned*)(lds + (bufoff) + ldsw + _i * 8192), 16, 0, 0); } while (0)
; #define PG8_LDA(dst, b, h) do { _Pragma("unroll") for (int m = 0; m < 4; ++m) _Pragma("unroll") for (int k = 0; k < 2; ++k) dst[m][k] = *(const LAS bf16x8*)(lds + PG8_SA(b, h) + aoff + m * 2048 + k * 1024); } while (0)
; #define PG8_LDB(dst, b, h) do { _Pragma("unroll") for (int n = 0; n < 2; ++n) _Pragma("unroll") for (int k = 0; k < 2; ++k) dst[n][k] = *(const LAS bf16x8*)(lds + PG8_SB(b, h) + boff + n * 2048 + k * 1024); } while (0)
; #define PG8_MMA(ai, bj, At, Bt) do { __builtin_amdgcn_s_setprio(1); _Pragma("unroll") for (int m = 0; m < 4; ++m) _Pragma("unroll") for (int n = 0; n < 2; ++n) _Pragma("unroll") for (int k = 0; k < 2; ++k) \
;         acc[ai][bj][m][n] = __builtin_amdgcn_mfma_f32_16x16x32_bf16(Bt[n][k], At[m][k], acc[ai][bj][m][n], 0, 0, 0); __builtin_amdgcn_s_setprio(0); } while (0)
; #define PG8_WAIT_V(n) asm volatile("s_waitcnt vmcnt(" #n ")" ::: "memory")
; #define PG8_WAIT_L(n) asm volatile("s_waitcnt lgkmcnt(" #n ")" ::: "memory")
; #define PG8_BAR __builtin_amdgcn_s_barrier()
; #define PG8_SCHED __builtin_amdgcn_sched_barrier(0)
; template <class EpiT, class Sched>
; __device__ __forceinline__ void gemm_phase(LAS unsigned char* lds, int tid_in, const GemmDesc g, const Sched& S, const EpiT& E) {
;     ...
;             PG8_WAIT_V(8); PG8_WAIT_L(0); PG8_BAR; PG8_MMA(1, 0, At, B0); PG8_MMA(1, 1, At, B1); PG8_BAR; PG8_SCHED;
;             PG8_LDB(B0, 1, 0); PG8_LDB(B1, 1, 1); PG8_SCHED; PG8_LDA(At, 1, 0); PG8_STAGE(PG8_SA(0, 1), a2 + hA, voffA);
;             PG8_WAIT_V(8); PG8_WAIT_L(0); PG8_BAR; PG8_MMA(0, 0, At, B0); PG8_MMA(0, 1, At, B1); PG8_BAR; PG8_SCHED;
;             PG8_LDA(At, 1, 1); PG8_STAGE(PG8_SB(1, 0), b3, voffB); PG8_STAGE(PG8_SB(1, 1), b3 + hB, voffB); PG8_STAGE(PG8_SA(1, 0), a3, voffA);
;             PG8_WAIT_V(8); PG8_WAIT_L(0); PG8_BAR; PG8_MMA(1, 0, At, B0); PG8_MMA(1, 1, At, B1); PG8_BAR; PG8_SCHED;
	s_waitcnt lgkmcnt(0)
	v_mfma_f32_16x16x32_bf16 v[62:65], v[144:147], v[176:179], v[62:65]
	v_mfma_f32_16x16x32_bf16 v[58:61], v[152:155], v[176:179], v[58:61]
	v_mfma_f32_16x16x32_bf16 v[54:57], v[144:147], v[184:187], v[54:57]
	v_mfma_f32_16x16x32_bf16 v[50:53], v[152:155], v[184:187], v[50:53]
	v_mfma_f32_16x16x32_bf16 v[38:41], v[144:147], v[192:195], v[38:41]
	v_mfma_f32_16x16x32_bf16 v[34:37], v[152:155], v[192:195], v[34:37]
	v_mfma_f32_16x16x32_bf16 v[22:25], v[144:147], v[200:203], v[22:25]
	v_mfma_f32_16x16x32_bf16 v[18:21], v[152:155], v[200:203], v[18:21]
	v_mfma_f32_16x16x32_bf16 v[62:65], v[148:151], v[180:183], v[62:65]
	v_mfma_f32_16x16x32_bf16 v[58:61], v[156:159], v[180:183], v[58:61]
	v_mfma_f32_16x16x32_bf16 v[54:57], v[148:151], v[188:191], v[54:57]
	v_mfma_f32_16x16x32_bf16 v[50:53], v[156:159], v[188:191], v[50:53]
	v_mfma_f32_16x16x32_bf16 v[38:41], v[148:151], v[196:199], v[38:41]
	v_mfma_f32_16x16x32_bf16 v[34:37], v[156:159], v[196:199], v[34:37]
	v_mfma_f32_16x16x32_bf16 v[22:25], v[148:151], v[204:207], v[22:25]
	v_mfma_f32_16x16x32_bf16 v[18:21], v[156:159], v[204:207], v[18:21]
	v_mfma_f32_16x16x32_bf16 v[46:49], v[160:163], v[176:179], v[46:49]
	v_mfma_f32_16x16x32_bf16 v[42:45], v[168:171], v[176:179], v[42:45]
	v_mfma_f32_16x16x32_bf16 v[30:33], v[160:163], v[184:187], v[30:33]
	v_mfma_f32_16x16x32_bf16 v[26:29], v[168:171], v[184:187], v[26:29]
	v_mfma_f32_16x16x32_bf16 v[14:17], v[160:163], v[192:195], v[14:17]
	v_mfma_f32_16x16x32_bf16 v[10:13], v[168:171], v[192:195], v[10:13]
	v_mfma_f32_16x16x32_bf16 v[6:9], v[160:163], v[200:203], v[6:9]
	v_mfma_f32_16x16x32_bf16 v[2:5], v[168:171], v[200:203], v[2:5]
	v_mfma_f32_16x16x32_bf16 v[46:49], v[164:167], v[180:183], v[46:49]
	v_mfma_f32_16x16x32_bf16 v[42:45], v[172:175], v[180:183], v[42:45]
	v_mfma_f32_16x16x32_bf16 v[30:33], v[164:167], v[188:191], v[30:33]
	v_mfma_f32_16x16x32_bf16 v[26:29], v[172:175], v[188:191], v[26:29]
	v_mfma_f32_16x16x32_bf16 v[14:17], v[164:167], v[196:199], v[14:17]
	v_mfma_f32_16x16x32_bf16 v[10:13], v[172:175], v[196:199], v[10:13]
	v_mfma_f32_16x16x32_bf16 v[6:9], v[164:167], v[204:207], v[6:9]
	v_mfma_f32_16x16x32_bf16 v[2:5], v[172:175], v[204:207], v[2:5]
	s_barrier
	s_add_i32 s63, 0, 0x18000
	s_add_i32 s90, 0, 0x1c000
	v_add_u32_e32 v156, s63, v141
	v_add_u32_e32 v172, s90, v141
	ds_read_b128 v[144:147], v156
	ds_read_b128 v[148:151], v156 offset:1024
	ds_read_b128 v[152:155], v156 offset:2048
	ds_read_b128 v[156:159], v156 offset:3072
	ds_read_b128 v[160:163], v172
	ds_read_b128 v[164:167], v172 offset:1024
	ds_read_b128 v[168:171], v172 offset:2048
	ds_read_b128 v[172:175], v172 offset:3072
	s_add_u32 s10, s94, 0x40000
	s_addc_u32 s11, s95, 0
	s_mov_b32 m0, s74
	v_lshl_add_u64 v[220:221], s[10:11], 0, v[134:135]
	ds_read_b128 v[176:179], v143 offset:32768
	ds_read_b128 v[180:183], v143 offset:33792
	ds_read_b128 v[184:187], v143 offset:34816
	ds_read_b128 v[188:191], v143 offset:35840
	ds_read_b128 v[192:195], v143 offset:36864
	ds_read_b128 v[196:199], v143 offset:37888
	ds_read_b128 v[200:203], v143 offset:38912
	ds_read_b128 v[204:207], v143 offset:39936
	global_load_lds_dwordx4 v[220:221], off
	v_lshl_add_u64 v[220:221], s[10:11], 0, v[132:133]
	s_mov_b32 m0, s75
	s_nop 0
	global_load_lds_dwordx4 v[220:221], off
	s_waitcnt vmcnt(8)
	s_waitcnt lgkmcnt(0)
	s_barrier
	s_waitcnt lgkmcnt(0)
	v_mfma_f32_16x16x32_bf16 v[126:129], v[144:147], v[176:179], v[126:129]
	v_mfma_f32_16x16x32_bf16 v[122:125], v[152:155], v[176:179], v[122:125]
	v_mfma_f32_16x16x32_bf16 v[118:121], v[144:147], v[184:187], v[118:121]
	v_mfma_f32_16x16x32_bf16 v[114:117], v[152:155], v[184:187], v[114:117]
	v_mfma_f32_16x16x32_bf16 v[102:105], v[144:147], v[192:195], v[102:105]
	v_mfma_f32_16x16x32_bf16 v[98:101], v[152:155], v[192:195], v[98:101]
	v_mfma_f32_16x16x32_bf16 v[86:89], v[144:147], v[200:203], v[86:89]
	v_mfma_f32_16x16x32_bf16 v[82:85], v[152:155], v[200:203], v[82:85]
	v_mfma_f32_16x16x32_bf16 v[126:129], v[148:151], v[180:183], v[126:129]
	v_mfma_f32_16x16x32_bf16 v[122:125], v[156:159], v[180:183], v[122:125]
	v_mfma_f32_16x16x32_bf16 v[118:121], v[148:151], v[188:191], v[118:121]
	v_mfma_f32_16x16x32_bf16 v[114:117], v[156:159], v[188:191], v[114:117]
	v_mfma_f32_16x16x32_bf16 v[102:105], v[148:151], v[196:199], v[102:105]
	v_mfma_f32_16x16x32_bf16 v[98:101], v[156:159], v[196:199], v[98:101]
	v_mfma_f32_16x16x32_bf16 v[86:89], v[148:151], v[204:207], v[86:89]
	v_mfma_f32_16x16x32_bf16 v[82:85], v[156:159], v[204:207], v[82:85]
	v_mfma_f32_16x16x32_bf16 v[110:113], v[160:163], v[176:179], v[110:113]
	v_mfma_f32_16x16x32_bf16 v[106:109], v[168:171], v[176:179], v[106:109]
	v_mfma_f32_16x16x32_bf16 v[94:97], v[160:163], v[184:187], v[94:97]
	v_mfma_f32_16x16x32_bf16 v[90:93], v[168:171], v[184:187], v[90:93]
	v_mfma_f32_16x16x32_bf16 v[78:81], v[160:163], v[192:195], v[78:81]
	v_mfma_f32_16x16x32_bf16 v[74:77], v[168:171], v[192:195], v[74:77]
	v_mfma_f32_16x16x32_bf16 v[70:73], v[160:163], v[200:203], v[70:73]
	v_mfma_f32_16x16x32_bf16 v[66:69], v[168:171], v[200:203], v[66:69]
	v_mfma_f32_16x16x32_bf16 v[110:113], v[164:167], v[180:183], v[110:113]
	v_mfma_f32_16x16x32_bf16 v[106:109], v[172:175], v[180:183], v[106:109]
	v_mfma_f32_16x16x32_bf16 v[94:97], v[164:167], v[188:191], v[94:97]
	v_mfma_f32_16x16x32_bf16 v[90:93], v[172:175], v[188:191], v[90:93]
	v_mfma_f32_16x16x32_bf16 v[78:81], v[164:167], v[196:199], v[78:81]
	v_mfma_f32_16x16x32_bf16 v[74:77], v[172:175], v[196:199], v[74:77]
	v_mfma_f32_16x16x32_bf16 v[70:73], v[164:167], v[204:207], v[70:73]
	v_mfma_f32_16x16x32_bf16 v[66:69], v[172:175], v[204:207], v[66:69]
	s_barrier
; #define PG8_STAGE(bufoff, gbase, voff) do { _Pragma("unroll") for (int _i = 0; _i < 2; ++_i) \
;         __builtin_amdgcn_global_load_lds((const unsigned*)((const char*)(gbase) + (voff)[_i]), (LAS unsigned*)(lds + (bufoff) + ldsw + _i * 8192), 16, 0, 0); } while (0)
; #define PG8_LDA(dst, b, h) do { _Pragma("unroll") for (int m = 0; m < 4; ++m) _Pragma("unroll") for (int k = 0; k < 2; ++k) dst[m][k] = *(const LAS bf16x8*)(lds + PG8_SA(b, h) + aoff + m * 2048 + k * 1024); } while (0)
; #define PG8_LDB(dst, b, h) do { _Pragma("unroll") for (int n = 0; n < 2; ++n) _Pragma("unroll") for (int k = 0; k < 2; ++k) dst[n][k] = *(const LAS bf16x8*)(lds + PG8_SB(b, h) + boff + n * 2048 + k * 1024); } while (0)
; #define PG8_MMA(ai, bj, At, Bt) do { __builtin_amdgcn_s_setprio(1); _Pragma("unroll") for (int m = 0; m < 4; ++m) _Pragma("unroll") for (int n = 0; n < 2; ++n) _Pragma("unroll") for (int k = 0; k < 2; ++k) \
;         acc[ai][bj][m][n] = __builtin_amdgcn_mfma_f32_16x16x32_bf16(Bt[n][k], At[m][k], acc[ai][bj][m][n], 0, 0, 0); __builtin_amdgcn_s_setprio(0); } while (0)
; #define PG8_WAIT_V(n) asm volatile("s_waitcnt vmcnt(" #n ")" ::: "memory")
; #define PG8_WAIT_L(n) asm volatile("s_waitcnt lgkmcnt(" #n ")" ::: "memory")
; #define PG8_BAR __builtin_amdgcn_s_barrier()
; #define PG8_SCHED __builtin_amdgcn_sched_barrier(0)
; template <class EpiT, class Sched>
; __device__ __forceinline__ void gemm_phase(LAS unsigned char* lds, int tid_in, const GemmDesc g, const Sched& S, const EpiT& E) {
;     ...
;             PG8_LDB(B0, 1, 0); PG8_LDB(B1, 1, 1); PG8_SCHED; PG8_LDA(At, 1, 0); PG8_STAGE(PG8_SA(0, 1), a2 + hA, voffA);
;             PG8_WAIT_V(8); PG8_WAIT_L(0); PG8_BAR; PG8_MMA(0, 0, At, B0); PG8_MMA(0, 1, At, B1); PG8_BAR; PG8_SCHED;
;             PG8_LDA(At, 1, 1); PG8_STAGE(PG8_SB(1, 0), b3, voffB); PG8_STAGE(PG8_SB(1, 1), b3 + hB, voffB); PG8_STAGE(PG8_SA(1, 0), a3, voffA);
;             PG8_WAIT_V(8); PG8_WAIT_L(0); PG8_BAR; PG8_MMA(1, 0, At, B0); PG8_MMA(1, 1, At, B1); PG8_BAR; PG8_SCHED;
	s_add_i32 s10, s63, s71
	v_lshl_add_u64 v[208:209], v[208:209], 0, s[60:61]
	s_mov_b32 m0, s10
	ds_read_b128 v[176:179], v143 offset:49152
	ds_read_b128 v[180:183], v143 offset:50176
	ds_read_b128 v[184:187], v143 offset:51200
	ds_read_b128 v[188:191], v143 offset:52224
	ds_read_b128 v[192:195], v143 offset:53248
	ds_read_b128 v[196:199], v143 offset:54272
	ds_read_b128 v[200:203], v143 offset:55296
	ds_read_b128 v[204:207], v143 offset:56320
	global_load_lds_dwordx4 v[208:209], off
	s_add_i32 m0, s10, 0x2000
	s_add_u32 s10, s92, 0x40080
	v_lshl_add_u64 v[208:209], v[210:211], 0, s[60:61]
	s_addc_u32 s11, s93, 0
	s_add_i32 s63, s90, s71
	global_load_lds_dwordx4 v[208:209], off
	v_lshl_add_u64 v[208:209], s[10:11], 0, v[0:1]
	s_mov_b32 m0, s63
	s_nop 0
	global_load_lds_dwordx4 v[208:209], off
	v_lshl_add_u64 v[208:209], s[10:11], 0, v[130:131]
	s_add_i32 m0, s63, 0x2000
	s_nop 0
	global_load_lds_dwordx4 v[208:209], off
	v_lshl_add_u64 v[208:209], v[212:213], 0, s[60:61]
	s_mov_b32 m0, s58
	s_nop 0
	global_load_lds_dwordx4 v[208:209], off
	v_lshl_add_u64 v[208:209], v[218:219], 0, s[60:61]
	s_mov_b32 m0, s76
	s_nop 0
	global_load_lds_dwordx4 v[208:209], off
	s_waitcnt vmcnt(8)
	s_waitcnt lgkmcnt(0)
	s_barrier
	s_waitcnt lgkmcnt(0)
	v_mfma_f32_16x16x32_bf16 v[62:65], v[144:147], v[176:179], v[62:65]
	v_mfma_f32_16x16x32_bf16 v[58:61], v[152:155], v[176:179], v[58:61]
	v_mfma_f32_16x16x32_bf16 v[54:57], v[144:147], v[184:187], v[54:57]
	v_mfma_f32_16x16x32_bf16 v[50:53], v[152:155], v[184:187], v[50:53]
	v_mfma_f32_16x16x32_bf16 v[38:41], v[144:147], v[192:195], v[38:41]
	v_mfma_f32_16x16x32_bf16 v[34:37], v[152:155], v[192:195], v[34:37]
	v_mfma_f32_16x16x32_bf16 v[22:25], v[144:147], v[200:203], v[22:25]
	v_mfma_f32_16x16x32_bf16 v[18:21], v[152:155], v[200:203], v[18:21]
	v_mfma_f32_16x16x32_bf16 v[62:65], v[148:151], v[180:183], v[62:65]
	v_mfma_f32_16x16x32_bf16 v[58:61], v[156:159], v[180:183], v[58:61]
	v_mfma_f32_16x16x32_bf16 v[54:57], v[148:151], v[188:191], v[54:57]
	v_mfma_f32_16x16x32_bf16 v[50:53], v[156:159], v[188:191], v[50:53]
	v_mfma_f32_16x16x32_bf16 v[38:41], v[148:151], v[196:199], v[38:41]
	v_mfma_f32_16x16x32_bf16 v[34:37], v[156:159], v[196:199], v[34:37]
	v_mfma_f32_16x16x32_bf16 v[22:25], v[148:151], v[204:207], v[22:25]
	v_mfma_f32_16x16x32_bf16 v[18:21], v[156:159], v[204:207], v[18:21]
	v_mfma_f32_16x16x32_bf16 v[46:49], v[160:163], v[176:179], v[46:49]
	v_mfma_f32_16x16x32_bf16 v[42:45], v[168:171], v[176:179], v[42:45]
	v_mfma_f32_16x16x32_bf16 v[30:33], v[160:163], v[184:187], v[30:33]
	v_mfma_f32_16x16x32_bf16 v[26:29], v[168:171], v[184:187], v[26:29]
	v_mfma_f32_16x16x32_bf16 v[14:17], v[160:163], v[192:195], v[14:17]
	v_mfma_f32_16x16x32_bf16 v[10:13], v[168:171], v[192:195], v[10:13]
	v_mfma_f32_16x16x32_bf16 v[6:9], v[160:163], v[200:203], v[6:9]
	v_mfma_f32_16x16x32_bf16 v[2:5], v[168:171], v[200:203], v[2:5]
	v_mfma_f32_16x16x32_bf16 v[46:49], v[164:167], v[180:183], v[46:49]
	v_mfma_f32_16x16x32_bf16 v[42:45], v[172:175], v[180:183], v[42:45]
	v_mfma_f32_16x16x32_bf16 v[30:33], v[164:167], v[188:191], v[30:33]
	v_mfma_f32_16x16x32_bf16 v[26:29], v[172:175], v[188:191], v[26:29]
	v_mfma_f32_16x16x32_bf16 v[14:17], v[164:167], v[196:199], v[14:17]
	v_mfma_f32_16x16x32_bf16 v[10:13], v[172:175], v[196:199], v[10:13]
	v_mfma_f32_16x16x32_bf16 v[6:9], v[164:167], v[204:207], v[6:9]
	v_mfma_f32_16x16x32_bf16 v[2:5], v[172:175], v[204:207], v[2:5]
	s_barrier
	s_add_i32 s62, s62, 2
	s_add_u32 vcc_lo, vcc_lo, 0x100
	s_addc_u32 vcc_hi, vcc_hi, 0
	s_add_u32 s59, s59, 0x100
	s_addc_u32 s81, s81, 0
	s_cmp_gt_u32 s62, 13
	s_cbranch_scc0 .LBB0_411
	s_and_b64 vcc, exec, s[24:25]
	s_cbranch_vccz .LBB0_414
	s_barrier

; #define PG8_STAGE(bufoff, gbase, voff) do { _Pragma("unroll") for (int _i = 0; _i < 2; ++_i) \
;         __builtin_amdgcn_global_load_lds((const unsigned*)((const char*)(gbase) + (voff)[_i]), (LAS unsigned*)(lds + (bufoff) + ldsw + _i * 8192), 16, 0, 0); } while (0)
; #define PG8_LDA(dst, b, h) do { _Pragma("unroll") for (int m = 0; m < 4; ++m) _Pragma("unroll") for (int k = 0; k < 2; ++k) dst[m][k] = *(const LAS bf16x8*)(lds + PG8_SA(b, h) + aoff + m * 2048 + k * 1024); } while (0)
; #define PG8_LDB(dst, b, h) do { _Pragma("unroll") for (int n = 0; n < 2; ++n) _Pragma("unroll") for (int k = 0; k < 2; ++k) dst[n][k] = *(const LAS bf16x8*)(lds + PG8_SB(b, h) + boff + n * 2048 + k * 1024); } while (0)
; #define PG8_MMA(ai, bj, At, Bt) do { __builtin_amdgcn_s_setprio(1); _Pragma("unroll") for (int m = 0; m < 4; ++m) _Pragma("unroll") for (int n = 0; n < 2; ++n) _Pragma("unroll") for (int k = 0; k < 2; ++k) \
;         acc[ai][bj][m][n] = __builtin_amdgcn_mfma_f32_16x16x32_bf16(Bt[n][k], At[m][k], acc[ai][bj][m][n], 0, 0, 0); __builtin_amdgcn_s_setprio(0); } while (0)
; #define PG8_WAIT_V(n) asm volatile("s_waitcnt vmcnt(" #n ")" ::: "memory")
; template <class EpiT, class Sched>
; __device__ __forceinline__ void gemm_phase(LAS unsigned char* lds, int tid_in, const GemmDesc g, const Sched& S, const EpiT& E) {
;     ...
;     for (;;) {
;         const bool has_next = S.next(ui + 1, nxt);
;         const char* nA = has_next ? g.A + nxt.aoff : cA; const char* nB = has_next ? g.Bt + nxt.boff : cB;
;         for (int t = 0; t < nt; t += 2) {
;             const bool last = (t == nt - 2);
;             const char* a1 = cA + (size_t)(t + 1) * kA;
;             const char* a2 = last ? nA : cA + (size_t)(t + 2) * kA; const char* b2 = last ? nB : cB + (size_t)(t + 2) * kB;
;             const char* a3 = a2 + kA; const char* b3 = b2 + kB;
;             PG8_LDB(B0, 0, 0); PG8_LDB(B1, 0, 1); PG8_SCHED; PG8_LDA(At, 0, 0); PG8_STAGE(PG8_SA(1, 1), a1 + hA, voffA);
;             PG8_WAIT_V(8); PG8_WAIT_L(0); PG8_BAR; PG8_MMA(0, 0, At, B0); PG8_MMA(0, 1, At, B1); PG8_BAR; PG8_SCHED;
;             PG8_LDA(At, 0, 1); PG8_STAGE(PG8_SB(0, 0), b2, voffB); PG8_STAGE(PG8_SB(0, 1), b2 + hB, voffB); PG8_STAGE(PG8_SA(0, 0), a2, voffA);
;             PG8_WAIT_V(8); PG8_WAIT_L(0); PG8_BAR; PG8_MMA(1, 0, At, B0); PG8_MMA(1, 1, At, B1); PG8_BAR; PG8_SCHED;
.LBB0_524:
	s_add_u32 s10, s4, s58
	s_addc_u32 s11, s5, s59
	s_add_u32 s18, s4, s2
	s_addc_u32 s19, s5, s3
	s_cmp_eq_u32 s72, 12
	s_cselect_b32 s24, s12, s10
	s_cselect_b32 s25, s13, s11
	s_cselect_b32 s22, s0, s18
	s_cselect_b32 s23, s1, s19
	s_add_u32 s18, s24, 0x1c00
	s_addc_u32 s19, s25, 0
	s_add_i32 s10, 0, 0x10000
	s_add_i32 s62, 0, 0x14000
	v_add_u32_e32 v156, s10, v142
	v_add_u32_e32 v172, s62, v142
	ds_read_b128 v[144:147], v156
	ds_read_b128 v[148:151], v156 offset:1024
	ds_read_b128 v[152:155], v156 offset:2048
	ds_read_b128 v[156:159], v156 offset:3072
	ds_read_b128 v[160:163], v172
	ds_read_b128 v[164:167], v172 offset:1024
	ds_read_b128 v[168:171], v172 offset:2048
	ds_read_b128 v[172:175], v172 offset:3072
	v_lshl_add_u64 v[208:209], s[4:5], 0, v[136:137]
	s_add_i32 m0, s9, 0xc000
	ds_read_b128 v[176:179], v143
	ds_read_b128 v[180:183], v143 offset:1024
	ds_read_b128 v[184:187], v143 offset:2048
	ds_read_b128 v[188:191], v143 offset:3072
	ds_read_b128 v[192:195], v143 offset:4096
	ds_read_b128 v[196:199], v143 offset:5120
	ds_read_b128 v[200:203], v143 offset:6144
	ds_read_b128 v[204:207], v143 offset:7168
	global_load_lds_dwordx4 v[208:209], off
	v_lshl_add_u64 v[208:209], s[4:5], 0, v[138:139]
	s_add_i32 m0, s9, 0xe000
	s_nop 0
	global_load_lds_dwordx4 v[208:209], off
	s_waitcnt vmcnt(8)
	s_waitcnt lgkmcnt(0)
	s_barrier
	s_waitcnt lgkmcnt(0)
	v_mfma_f32_16x16x32_bf16 v[126:129], v[144:147], v[176:179], v[126:129]
	v_mfma_f32_16x16x32_bf16 v[122:125], v[152:155], v[176:179], v[122:125]
	v_mfma_f32_16x16x32_bf16 v[118:121], v[144:147], v[184:187], v[118:121]
	v_mfma_f32_16x16x32_bf16 v[114:117], v[152:155], v[184:187], v[114:117]
	v_mfma_f32_16x16x32_bf16 v[102:105], v[144:147], v[192:195], v[102:105]
	v_mfma_f32_16x16x32_bf16 v[98:101], v[152:155], v[192:195], v[98:101]
	v_mfma_f32_16x16x32_bf16 v[86:89], v[144:147], v[200:203], v[86:89]
	v_mfma_f32_16x16x32_bf16 v[82:85], v[152:155], v[200:203], v[82:85]
	v_mfma_f32_16x16x32_bf16 v[126:129], v[148:151], v[180:183], v[126:129]
	v_mfma_f32_16x16x32_bf16 v[122:125], v[156:159], v[180:183], v[122:125]
	v_mfma_f32_16x16x32_bf16 v[118:121], v[148:151], v[188:191], v[118:121]
	v_mfma_f32_16x16x32_bf16 v[114:117], v[156:159], v[188:191], v[114:117]
	v_mfma_f32_16x16x32_bf16 v[102:105], v[148:151], v[196:199], v[102:105]
	v_mfma_f32_16x16x32_bf16 v[98:101], v[156:159], v[196:199], v[98:101]
	v_mfma_f32_16x16x32_bf16 v[86:89], v[148:151], v[204:207], v[86:89]
	v_mfma_f32_16x16x32_bf16 v[82:85], v[156:159], v[204:207], v[82:85]
	v_mfma_f32_16x16x32_bf16 v[110:113], v[160:163], v[176:179], v[110:113]
	v_mfma_f32_16x16x32_bf16 v[106:109], v[168:171], v[176:179], v[106:109]
	v_mfma_f32_16x16x32_bf16 v[94:97], v[160:163], v[184:187], v[94:97]
	v_mfma_f32_16x16x32_bf16 v[90:93], v[168:171], v[184:187], v[90:93]
	v_mfma_f32_16x16x32_bf16 v[78:81], v[160:163], v[192:195], v[78:81]
	v_mfma_f32_16x16x32_bf16 v[74:77], v[168:171], v[192:195], v[74:77]
	v_mfma_f32_16x16x32_bf16 v[70:73], v[160:163], v[200:203], v[70:73]
	v_mfma_f32_16x16x32_bf16 v[66:69], v[168:171], v[200:203], v[66:69]
	v_mfma_f32_16x16x32_bf16 v[110:113], v[164:167], v[180:183], v[110:113]
	v_mfma_f32_16x16x32_bf16 v[106:109], v[172:175], v[180:183], v[106:109]
	v_mfma_f32_16x16x32_bf16 v[94:97], v[164:167], v[188:191], v[94:97]
	v_mfma_f32_16x16x32_bf16 v[90:93], v[172:175], v[188:191], v[90:93]
	v_mfma_f32_16x16x32_bf16 v[78:81], v[164:167], v[196:199], v[78:81]
	v_mfma_f32_16x16x32_bf16 v[74:77], v[172:175], v[196:199], v[74:77]
	v_mfma_f32_16x16x32_bf16 v[70:73], v[164:167], v[204:207], v[70:73]
	v_mfma_f32_16x16x32_bf16 v[66:69], v[172:175], v[204:207], v[66:69]
	s_barrier
	s_add_i32 s10, s10, s8
	v_lshl_add_u64 v[208:209], s[22:23], 0, v[0:1]
	s_mov_b32 m0, s10
	ds_read_b128 v[176:179], v143 offset:16384
	ds_read_b128 v[180:183], v143 offset:17408
	ds_read_b128 v[184:187], v143 offset:18432
	ds_read_b128 v[188:191], v143 offset:19456
	ds_read_b128 v[192:195], v143 offset:20480
	ds_read_b128 v[196:199], v143 offset:21504
	ds_read_b128 v[200:203], v143 offset:22528
	ds_read_b128 v[204:207], v143 offset:23552
	global_load_lds_dwordx4 v[208:209], off
	s_add_i32 m0, s10, 0x2000
	s_add_u32 s10, s22, 0x80000
	v_lshl_add_u64 v[210:211], s[22:23], 0, v[130:131]
	s_addc_u32 s11, s23, 0
	s_add_i32 s62, s62, s8
	global_load_lds_dwordx4 v[210:211], off
	v_lshl_add_u64 v[212:213], s[10:11], 0, v[0:1]
	s_mov_b32 m0, s62
	s_nop 0
	global_load_lds_dwordx4 v[212:213], off
	v_lshl_add_u64 v[212:213], s[10:11], 0, v[130:131]
	s_add_i32 m0, s62, 0x2000
	s_nop 0
	global_load_lds_dwordx4 v[212:213], off
	v_lshl_add_u64 v[212:213], s[24:25], 0, v[134:135]
	s_mov_b32 m0, s9
	s_nop 0
	global_load_lds_dwordx4 v[212:213], off
	v_lshl_add_u64 v[212:213], s[24:25], 0, v[132:133]
	s_mov_b32 m0, s16
	s_nop 0
	global_load_lds_dwordx4 v[212:213], off
	s_waitcnt vmcnt(8)
	s_waitcnt lgkmcnt(0)
	s_barrier
; #define PG8_STAGE(bufoff, gbase, voff) do { _Pragma("unroll") for (int _i = 0; _i < 2; ++_i) \
;         __builtin_amdgcn_global_load_lds((const unsigned*)((const char*)(gbase) + (voff)[_i]), (LAS unsigned*)(lds + (bufoff) + ldsw + _i * 8192), 16, 0, 0); } while (0)
; #define PG8_LDA(dst, b, h) do { _Pragma("unroll") for (int m = 0; m < 4; ++m) _Pragma("unroll") for (int k = 0; k < 2; ++k) dst[m][k] = *(const LAS bf16x8*)(lds + PG8_SA(b, h) + aoff + m * 2048 + k * 1024); } while (0)
; #define PG8_LDB(dst, b, h) do { _Pragma("unroll") for (int n = 0; n < 2; ++n) _Pragma("unroll") for (int k = 0; k < 2; ++k) dst[n][k] = *(const LAS bf16x8*)(lds + PG8_SB(b, h) + boff + n * 2048 + k * 1024); } while (0)
; #define PG8_MMA(ai, bj, At, Bt) do { __builtin_amdgcn_s_setprio(1); _Pragma("unroll") for (int m = 0; m < 4; ++m) _Pragma("unroll") for (int n = 0; n < 2; ++n) _Pragma("unroll") for (int k = 0; k < 2; ++k) \
;         acc[ai][bj][m][n] = __builtin_amdgcn_mfma_f32_16x16x32_bf16(Bt[n][k], At[m][k], acc[ai][bj][m][n], 0, 0, 0); __builtin_amdgcn_s_setprio(0); } while (0)
; #define PG8_WAIT_V(n) asm volatile("s_waitcnt vmcnt(" #n ")" ::: "memory")
; #define PG8_WAIT_L(n) asm volatile("s_waitcnt lgkmcnt(" #n ")" ::: "memory")
; #define PG8_BAR __builtin_amdgcn_s_barrier()
; #define PG8_SCHED __builtin_amdgcn_sched_barrier(0)
; template <class EpiT, class Sched>
; __device__ __forceinline__ void gemm_phase(LAS unsigned char* lds, int tid_in, const GemmDesc g, const Sched& S, const EpiT& E) {
;     ...
;             PG8_WAIT_V(8); PG8_WAIT_L(0); PG8_BAR; PG8_MMA(1, 0, At, B0); PG8_MMA(1, 1, At, B1); PG8_BAR; PG8_SCHED;
;             PG8_LDB(B0, 1, 0); PG8_LDB(B1, 1, 1); PG8_SCHED; PG8_LDA(At, 1, 0); PG8_STAGE(PG8_SA(0, 1), a2 + hA, voffA);
;             PG8_WAIT_V(8); PG8_WAIT_L(0); PG8_BAR; PG8_MMA(0, 0, At, B0); PG8_MMA(0, 1, At, B1); PG8_BAR; PG8_SCHED;
	s_waitcnt lgkmcnt(0)
	v_mfma_f32_16x16x32_bf16 v[62:65], v[144:147], v[176:179], v[62:65]
	v_mfma_f32_16x16x32_bf16 v[58:61], v[152:155], v[176:179], v[58:61]
	v_mfma_f32_16x16x32_bf16 v[54:57], v[144:147], v[184:187], v[54:57]
	v_mfma_f32_16x16x32_bf16 v[50:53], v[152:155], v[184:187], v[50:53]
	v_mfma_f32_16x16x32_bf16 v[38:41], v[144:147], v[192:195], v[38:41]
	v_mfma_f32_16x16x32_bf16 v[34:37], v[152:155], v[192:195], v[34:37]
	v_mfma_f32_16x16x32_bf16 v[22:25], v[144:147], v[200:203], v[22:25]
	v_mfma_f32_16x16x32_bf16 v[18:21], v[152:155], v[200:203], v[18:21]
	v_mfma_f32_16x16x32_bf16 v[62:65], v[148:151], v[180:183], v[62:65]
	v_mfma_f32_16x16x32_bf16 v[58:61], v[156:159], v[180:183], v[58:61]
	v_mfma_f32_16x16x32_bf16 v[54:57], v[148:151], v[188:191], v[54:57]
	v_mfma_f32_16x16x32_bf16 v[50:53], v[156:159], v[188:191], v[50:53]
	v_mfma_f32_16x16x32_bf16 v[38:41], v[148:151], v[196:199], v[38:41]
	v_mfma_f32_16x16x32_bf16 v[34:37], v[156:159], v[196:199], v[34:37]
	v_mfma_f32_16x16x32_bf16 v[22:25], v[148:151], v[204:207], v[22:25]
	v_mfma_f32_16x16x32_bf16 v[18:21], v[156:159], v[204:207], v[18:21]
	v_mfma_f32_16x16x32_bf16 v[46:49], v[160:163], v[176:179], v[46:49]
	v_mfma_f32_16x16x32_bf16 v[42:45], v[168:171], v[176:179], v[42:45]
	v_mfma_f32_16x16x32_bf16 v[30:33], v[160:163], v[184:187], v[30:33]
	v_mfma_f32_16x16x32_bf16 v[26:29], v[168:171], v[184:187], v[26:29]
	v_mfma_f32_16x16x32_bf16 v[14:17], v[160:163], v[192:195], v[14:17]
	v_mfma_f32_16x16x32_bf16 v[10:13], v[168:171], v[192:195], v[10:13]
	v_mfma_f32_16x16x32_bf16 v[6:9], v[160:163], v[200:203], v[6:9]
	v_mfma_f32_16x16x32_bf16 v[2:5], v[168:171], v[200:203], v[2:5]
	v_mfma_f32_16x16x32_bf16 v[46:49], v[164:167], v[180:183], v[46:49]
	v_mfma_f32_16x16x32_bf16 v[42:45], v[172:175], v[180:183], v[42:45]
	v_mfma_f32_16x16x32_bf16 v[30:33], v[164:167], v[188:191], v[30:33]
	v_mfma_f32_16x16x32_bf16 v[26:29], v[172:175], v[188:191], v[26:29]
	v_mfma_f32_16x16x32_bf16 v[14:17], v[164:167], v[196:199], v[14:17]
	v_mfma_f32_16x16x32_bf16 v[10:13], v[172:175], v[196:199], v[10:13]
	v_mfma_f32_16x16x32_bf16 v[6:9], v[164:167], v[204:207], v[6:9]
	v_mfma_f32_16x16x32_bf16 v[2:5], v[172:175], v[204:207], v[2:5]
	s_barrier
	s_add_i32 s62, 0, 0x18000
	s_add_i32 s63, 0, 0x1c000
	v_add_u32_e32 v156, s62, v142
	v_add_u32_e32 v172, s63, v142
	ds_read_b128 v[144:147], v156
	ds_read_b128 v[148:151], v156 offset:1024
	ds_read_b128 v[152:155], v156 offset:2048
	ds_read_b128 v[156:159], v156 offset:3072
	ds_read_b128 v[160:163], v172
	ds_read_b128 v[164:167], v172 offset:1024
	ds_read_b128 v[168:171], v172 offset:2048
	ds_read_b128 v[172:175], v172 offset:3072
	s_add_u32 s10, s24, 0xe00000
	s_addc_u32 s11, s25, 0
	s_mov_b32 m0, s17
	v_lshl_add_u64 v[212:213], s[10:11], 0, v[134:135]
	ds_read_b128 v[176:179], v143 offset:32768
	ds_read_b128 v[180:183], v143 offset:33792
	ds_read_b128 v[184:187], v143 offset:34816
	ds_read_b128 v[188:191], v143 offset:35840
	ds_read_b128 v[192:195], v143 offset:36864
	ds_read_b128 v[196:199], v143 offset:37888
	ds_read_b128 v[200:203], v143 offset:38912
	ds_read_b128 v[204:207], v143 offset:39936
	global_load_lds_dwordx4 v[212:213], off
	v_lshl_add_u64 v[212:213], s[10:11], 0, v[132:133]
	s_mov_b32 m0, s30
	s_nop 0
	global_load_lds_dwordx4 v[212:213], off
	s_waitcnt vmcnt(8)
	s_waitcnt lgkmcnt(0)
	s_barrier
	s_waitcnt lgkmcnt(0)
	v_mfma_f32_16x16x32_bf16 v[126:129], v[144:147], v[176:179], v[126:129]
	v_mfma_f32_16x16x32_bf16 v[122:125], v[152:155], v[176:179], v[122:125]
	v_mfma_f32_16x16x32_bf16 v[118:121], v[144:147], v[184:187], v[118:121]
	v_mfma_f32_16x16x32_bf16 v[114:117], v[152:155], v[184:187], v[114:117]
	v_mfma_f32_16x16x32_bf16 v[102:105], v[144:147], v[192:195], v[102:105]
	v_mfma_f32_16x16x32_bf16 v[98:101], v[152:155], v[192:195], v[98:101]
	v_mfma_f32_16x16x32_bf16 v[86:89], v[144:147], v[200:203], v[86:89]
	v_mfma_f32_16x16x32_bf16 v[82:85], v[152:155], v[200:203], v[82:85]
	v_mfma_f32_16x16x32_bf16 v[126:129], v[148:151], v[180:183], v[126:129]
	v_mfma_f32_16x16x32_bf16 v[122:125], v[156:159], v[180:183], v[122:125]
	v_mfma_f32_16x16x32_bf16 v[118:121], v[148:151], v[188:191], v[118:121]
	v_mfma_f32_16x16x32_bf16 v[114:117], v[156:159], v[188:191], v[114:117]
	v_mfma_f32_16x16x32_bf16 v[102:105], v[148:151], v[196:199], v[102:105]
	v_mfma_f32_16x16x32_bf16 v[98:101], v[156:159], v[196:199], v[98:101]
	v_mfma_f32_16x16x32_bf16 v[86:89], v[148:151], v[204:207], v[86:89]
	v_mfma_f32_16x16x32_bf16 v[82:85], v[156:159], v[204:207], v[82:85]
	v_mfma_f32_16x16x32_bf16 v[110:113], v[160:163], v[176:179], v[110:113]
	v_mfma_f32_16x16x32_bf16 v[106:109], v[168:171], v[176:179], v[106:109]
	v_mfma_f32_16x16x32_bf16 v[94:97], v[160:163], v[184:187], v[94:97]
	v_mfma_f32_16x16x32_bf16 v[90:93], v[168:171], v[184:187], v[90:93]
	v_mfma_f32_16x16x32_bf16 v[78:81], v[160:163], v[192:195], v[78:81]
	v_mfma_f32_16x16x32_bf16 v[74:77], v[168:171], v[192:195], v[74:77]
	v_mfma_f32_16x16x32_bf16 v[70:73], v[160:163], v[200:203], v[70:73]
	v_mfma_f32_16x16x32_bf16 v[66:69], v[168:171], v[200:203], v[66:69]
	v_mfma_f32_16x16x32_bf16 v[110:113], v[164:167], v[180:183], v[110:113]
	v_mfma_f32_16x16x32_bf16 v[106:109], v[172:175], v[180:183], v[106:109]
	v_mfma_f32_16x16x32_bf16 v[94:97], v[164:167], v[188:191], v[94:97]
	v_mfma_f32_16x16x32_bf16 v[90:93], v[172:175], v[188:191], v[90:93]
	v_mfma_f32_16x16x32_bf16 v[78:81], v[164:167], v[196:199], v[78:81]
	v_mfma_f32_16x16x32_bf16 v[74:77], v[172:175], v[196:199], v[74:77]
	v_mfma_f32_16x16x32_bf16 v[70:73], v[164:167], v[204:207], v[70:73]
	v_mfma_f32_16x16x32_bf16 v[66:69], v[172:175], v[204:207], v[66:69]
	s_barrier
; #define PG8_STAGE(bufoff, gbase, voff) do { _Pragma("unroll") for (int _i = 0; _i < 2; ++_i) \
;         __builtin_amdgcn_global_load_lds((const unsigned*)((const char*)(gbase) + (voff)[_i]), (LAS unsigned*)(lds + (bufoff) + ldsw + _i * 8192), 16, 0, 0); } while (0)
; #define PG8_LDA(dst, b, h) do { _Pragma("unroll") for (int m = 0; m < 4; ++m) _Pragma("unroll") for (int k = 0; k < 2; ++k) dst[m][k] = *(const LAS bf16x8*)(lds + PG8_SA(b, h) + aoff + m * 2048 + k * 1024); } while (0)
; #define PG8_MMA(ai, bj, At, Bt) do { __builtin_amdgcn_s_setprio(1); _Pragma("unroll") for (int m = 0; m < 4; ++m) _Pragma("unroll") for (int n = 0; n < 2; ++n) _Pragma("unroll") for (int k = 0; k < 2; ++k) \
;         acc[ai][bj][m][n] = __builtin_amdgcn_mfma_f32_16x16x32_bf16(Bt[n][k], At[m][k], acc[ai][bj][m][n], 0, 0, 0); __builtin_amdgcn_s_setprio(0); } while (0)
; #define PG8_WAIT_V(n) asm volatile("s_waitcnt vmcnt(" #n ")" ::: "memory")
; #define PG8_WAIT_L(n) asm volatile("s_waitcnt lgkmcnt(" #n ")" ::: "memory")
; #define PG8_BAR __builtin_amdgcn_s_barrier()
; #define PG8_SCHED __builtin_amdgcn_sched_barrier(0)
; template <class EpiT, class Sched>
; __device__ __forceinline__ void gemm_phase(LAS unsigned char* lds, int tid_in, const GemmDesc g, const Sched& S, const EpiT& E) {
;     ...
;             PG8_LDA(At, 1, 1); PG8_STAGE(PG8_SB(1, 0), b3, voffB); PG8_STAGE(PG8_SB(1, 1), b3 + hB, voffB); PG8_STAGE(PG8_SA(1, 0), a3, voffA);
;             PG8_WAIT_V(8); PG8_WAIT_L(0); PG8_BAR; PG8_MMA(1, 0, At, B0); PG8_MMA(1, 1, At, B1); PG8_BAR; PG8_SCHED;
;         }
;         if (wr == 0) PG8_BAR;
	s_add_i32 s10, s62, s8
	v_lshl_add_u64 v[208:209], v[208:209], 0, s[60:61]
	s_mov_b32 m0, s10
	ds_read_b128 v[176:179], v143 offset:49152
	ds_read_b128 v[180:183], v143 offset:50176
	ds_read_b128 v[184:187], v143 offset:51200
	ds_read_b128 v[188:191], v143 offset:52224
	ds_read_b128 v[192:195], v143 offset:53248
	ds_read_b128 v[196:199], v143 offset:54272
	ds_read_b128 v[200:203], v143 offset:55296
	ds_read_b128 v[204:207], v143 offset:56320
	global_load_lds_dwordx4 v[208:209], off
	s_add_i32 m0, s10, 0x2000
	s_add_u32 s10, s22, 0x80080
	v_lshl_add_u64 v[208:209], v[210:211], 0, s[60:61]
	s_addc_u32 s11, s23, 0
	s_add_i32 s22, s63, s8
	global_load_lds_dwordx4 v[208:209], off
	v_lshl_add_u64 v[208:209], s[10:11], 0, v[0:1]
	s_mov_b32 m0, s22
	s_nop 0
	global_load_lds_dwordx4 v[208:209], off
	v_lshl_add_u64 v[208:209], s[10:11], 0, v[130:131]
	s_add_i32 m0, s22, 0x2000
	s_nop 0
	global_load_lds_dwordx4 v[208:209], off
	v_lshl_add_u64 v[208:209], s[18:19], 0, v[134:135]
	s_mov_b32 m0, s34
	s_nop 0
	global_load_lds_dwordx4 v[208:209], off
	v_lshl_add_u64 v[208:209], s[18:19], 0, v[132:133]
	s_mov_b32 m0, s35
	s_nop 0
	global_load_lds_dwordx4 v[208:209], off
	s_waitcnt vmcnt(8)
	s_waitcnt lgkmcnt(0)
	s_barrier
	s_waitcnt lgkmcnt(0)
	v_mfma_f32_16x16x32_bf16 v[62:65], v[144:147], v[176:179], v[62:65]
	v_mfma_f32_16x16x32_bf16 v[58:61], v[152:155], v[176:179], v[58:61]
	v_mfma_f32_16x16x32_bf16 v[54:57], v[144:147], v[184:187], v[54:57]
	v_mfma_f32_16x16x32_bf16 v[50:53], v[152:155], v[184:187], v[50:53]
	v_mfma_f32_16x16x32_bf16 v[38:41], v[144:147], v[192:195], v[38:41]
	v_mfma_f32_16x16x32_bf16 v[34:37], v[152:155], v[192:195], v[34:37]
	v_mfma_f32_16x16x32_bf16 v[22:25], v[144:147], v[200:203], v[22:25]
	v_mfma_f32_16x16x32_bf16 v[18:21], v[152:155], v[200:203], v[18:21]
	v_mfma_f32_16x16x32_bf16 v[62:65], v[148:151], v[180:183], v[62:65]
	v_mfma_f32_16x16x32_bf16 v[58:61], v[156:159], v[180:183], v[58:61]
	v_mfma_f32_16x16x32_bf16 v[54:57], v[148:151], v[188:191], v[54:57]
	v_mfma_f32_16x16x32_bf16 v[50:53], v[156:159], v[188:191], v[50:53]
	v_mfma_f32_16x16x32_bf16 v[38:41], v[148:151], v[196:199], v[38:41]
	v_mfma_f32_16x16x32_bf16 v[34:37], v[156:159], v[196:199], v[34:37]
	v_mfma_f32_16x16x32_bf16 v[22:25], v[148:151], v[204:207], v[22:25]
	v_mfma_f32_16x16x32_bf16 v[18:21], v[156:159], v[204:207], v[18:21]
	v_mfma_f32_16x16x32_bf16 v[46:49], v[160:163], v[176:179], v[46:49]
	v_mfma_f32_16x16x32_bf16 v[42:45], v[168:171], v[176:179], v[42:45]
	v_mfma_f32_16x16x32_bf16 v[30:33], v[160:163], v[184:187], v[30:33]
	v_mfma_f32_16x16x32_bf16 v[26:29], v[168:171], v[184:187], v[26:29]
	v_mfma_f32_16x16x32_bf16 v[14:17], v[160:163], v[192:195], v[14:17]
	v_mfma_f32_16x16x32_bf16 v[10:13], v[168:171], v[192:195], v[10:13]
	v_mfma_f32_16x16x32_bf16 v[6:9], v[160:163], v[200:203], v[6:9]
	v_mfma_f32_16x16x32_bf16 v[2:5], v[168:171], v[200:203], v[2:5]
	v_mfma_f32_16x16x32_bf16 v[46:49], v[164:167], v[180:183], v[46:49]
	v_mfma_f32_16x16x32_bf16 v[42:45], v[172:175], v[180:183], v[42:45]
	v_mfma_f32_16x16x32_bf16 v[30:33], v[164:167], v[188:191], v[30:33]
	v_mfma_f32_16x16x32_bf16 v[26:29], v[172:175], v[188:191], v[26:29]
	v_mfma_f32_16x16x32_bf16 v[14:17], v[164:167], v[196:199], v[14:17]
	v_mfma_f32_16x16x32_bf16 v[10:13], v[172:175], v[196:199], v[10:13]
	v_mfma_f32_16x16x32_bf16 v[6:9], v[164:167], v[204:207], v[6:9]
	v_mfma_f32_16x16x32_bf16 v[2:5], v[172:175], v[204:207], v[2:5]
	s_barrier
	s_add_i32 s72, s72, 2
	s_add_u32 s2, s2, 0x100
	s_addc_u32 s3, s3, 0
	s_add_u32 s58, s58, 0x3800
	s_addc_u32 s59, s59, 0
	v_lshl_add_u64 v[136:137], v[136:137], 0, s[28:29]
	s_cmp_gt_u32 s72, 13
	v_lshl_add_u64 v[138:139], v[138:139], 0, s[28:29]
	s_cbranch_scc0 .LBB0_524
	s_cmpk_lt_u32 s6, 0x100
	s_cbranch_scc0 .LBB0_527
	s_barrier

; #define PG8_STAGE(bufoff, gbase, voff) do { _Pragma("unroll") for (int _i = 0; _i < 2; ++_i) \
;         __builtin_amdgcn_global_load_lds((const unsigned*)((const char*)(gbase) + (voff)[_i]), (LAS unsigned*)(lds + (bufoff) + ldsw + _i * 8192), 16, 0, 0); } while (0)
; #define PG8_LDA(dst, b, h) do { _Pragma("unroll") for (int m = 0; m < 4; ++m) _Pragma("unroll") for (int k = 0; k < 2; ++k) dst[m][k] = *(const LAS bf16x8*)(lds + PG8_SA(b, h) + aoff + m * 2048 + k * 1024); } while (0)
; #define PG8_LDB(dst, b, h) do { _Pragma("unroll") for (int n = 0; n < 2; ++n) _Pragma("unroll") for (int k = 0; k < 2; ++k) dst[n][k] = *(const LAS bf16x8*)(lds + PG8_SB(b, h) + boff + n * 2048 + k * 1024); } while (0)
; #define PG8_MMA(ai, bj, At, Bt) do { __builtin_amdgcn_s_setprio(1); _Pragma("unroll") for (int m = 0; m < 4; ++m) _Pragma("unroll") for (int n = 0; n < 2; ++n) _Pragma("unroll") for (int k = 0; k < 2; ++k) \
;         acc[ai][bj][m][n] = __builtin_amdgcn_mfma_f32_16x16x32_bf16(Bt[n][k], At[m][k], acc[ai][bj][m][n], 0, 0, 0); __builtin_amdgcn_s_setprio(0); } while (0)
; #define PG8_WAIT_V(n) asm volatile("s_waitcnt vmcnt(" #n ")" ::: "memory")
; #define PG8_WAIT_L(n) asm volatile("s_waitcnt lgkmcnt(" #n ")" ::: "memory")
; #define PG8_BAR __builtin_amdgcn_s_barrier()
; #define PG8_SCHED __builtin_amdgcn_sched_barrier(0)
; template <class EpiT, class Sched>
; __device__ __forceinline__ void gemm_phase(LAS unsigned char* lds, int tid_in, const GemmDesc g, const Sched& S, const EpiT& E) {
;     ...
;             const bool last = (t == nt - 2);
;             const char* a1 = cA + (size_t)(t + 1) * kA;
;             const char* a2 = last ? nA : cA + (size_t)(t + 2) * kA; const char* b2 = last ? nB : cB + (size_t)(t + 2) * kB;
;             const char* a3 = a2 + kA; const char* b3 = b2 + kB;
;             PG8_LDB(B0, 0, 0); PG8_LDB(B1, 0, 1); PG8_SCHED; PG8_LDA(At, 0, 0); PG8_STAGE(PG8_SA(1, 1), a1 + hA, voffA);
;             PG8_WAIT_V(8); PG8_WAIT_L(0); PG8_BAR; PG8_MMA(0, 0, At, B0); PG8_MMA(0, 1, At, B1); PG8_BAR; PG8_SCHED;
;             PG8_LDA(At, 0, 1); PG8_STAGE(PG8_SB(0, 0), b2, voffB); PG8_STAGE(PG8_SB(0, 1), b2 + hB, voffB); PG8_STAGE(PG8_SA(0, 0), a2, voffA);
.LBB0_947:
	s_add_u32 s10, vcc_lo, 0xfffc0080
	s_addc_u32 s11, vcc_hi, -1
	s_add_i32 s63, 0, 0x10000
	s_cmp_eq_u32 s62, 12
	s_cselect_b32 s95, s2, s11
	s_cselect_b32 s94, s3, s10
	s_cselect_b32 s93, s25, s89
	s_cselect_b32 s92, s59, s81
	s_add_i32 s90, 0, 0x14000
	v_add_u32_e32 v156, s63, v141
	v_add_u32_e32 v172, s90, v141
	ds_read_b128 v[144:147], v156
	ds_read_b128 v[148:151], v156 offset:1024
	ds_read_b128 v[152:155], v156 offset:2048
	ds_read_b128 v[156:159], v156 offset:3072
	ds_read_b128 v[160:163], v172
	ds_read_b128 v[164:167], v172 offset:1024
	ds_read_b128 v[168:171], v172 offset:2048
	ds_read_b128 v[172:175], v172 offset:3072
	v_lshl_add_u64 v[208:209], vcc, 0, v[136:137]
	s_add_i32 m0, s31, 0xc000
	ds_read_b128 v[176:179], v143
	ds_read_b128 v[180:183], v143 offset:1024
	ds_read_b128 v[184:187], v143 offset:2048
	ds_read_b128 v[188:191], v143 offset:3072
	ds_read_b128 v[192:195], v143 offset:4096
	ds_read_b128 v[196:199], v143 offset:5120
	ds_read_b128 v[200:203], v143 offset:6144
	ds_read_b128 v[204:207], v143 offset:7168
	global_load_lds_dwordx4 v[208:209], off
	v_lshl_add_u64 v[208:209], vcc, 0, v[138:139]
	s_add_i32 m0, s31, 0xe000
	s_nop 0
	global_load_lds_dwordx4 v[208:209], off
	s_waitcnt vmcnt(8)
	s_waitcnt lgkmcnt(0)
	s_barrier
	s_waitcnt lgkmcnt(0)
	v_mfma_f32_16x16x32_bf16 v[126:129], v[144:147], v[176:179], v[126:129]
	v_mfma_f32_16x16x32_bf16 v[122:125], v[152:155], v[176:179], v[122:125]
	v_mfma_f32_16x16x32_bf16 v[110:113], v[144:147], v[184:187], v[110:113]
	v_mfma_f32_16x16x32_bf16 v[106:109], v[152:155], v[184:187], v[106:109]
	v_mfma_f32_16x16x32_bf16 v[94:97], v[144:147], v[192:195], v[94:97]
	v_mfma_f32_16x16x32_bf16 v[90:93], v[152:155], v[192:195], v[90:93]
	v_mfma_f32_16x16x32_bf16 v[78:81], v[144:147], v[200:203], v[78:81]
	v_mfma_f32_16x16x32_bf16 v[74:77], v[152:155], v[200:203], v[74:77]
	v_mfma_f32_16x16x32_bf16 v[126:129], v[148:151], v[180:183], v[126:129]
	v_mfma_f32_16x16x32_bf16 v[122:125], v[156:159], v[180:183], v[122:125]
	v_mfma_f32_16x16x32_bf16 v[110:113], v[148:151], v[188:191], v[110:113]
	v_mfma_f32_16x16x32_bf16 v[106:109], v[156:159], v[188:191], v[106:109]
	v_mfma_f32_16x16x32_bf16 v[94:97], v[148:151], v[196:199], v[94:97]
	v_mfma_f32_16x16x32_bf16 v[90:93], v[156:159], v[196:199], v[90:93]
	v_mfma_f32_16x16x32_bf16 v[78:81], v[148:151], v[204:207], v[78:81]
	v_mfma_f32_16x16x32_bf16 v[74:77], v[156:159], v[204:207], v[74:77]
	v_mfma_f32_16x16x32_bf16 v[118:121], v[160:163], v[176:179], v[118:121]
	v_mfma_f32_16x16x32_bf16 v[114:117], v[168:171], v[176:179], v[114:117]
	v_mfma_f32_16x16x32_bf16 v[102:105], v[160:163], v[184:187], v[102:105]
	v_mfma_f32_16x16x32_bf16 v[98:101], v[168:171], v[184:187], v[98:101]
	v_mfma_f32_16x16x32_bf16 v[86:89], v[160:163], v[192:195], v[86:89]
	v_mfma_f32_16x16x32_bf16 v[82:85], v[168:171], v[192:195], v[82:85]
	v_mfma_f32_16x16x32_bf16 v[70:73], v[160:163], v[200:203], v[70:73]
	v_mfma_f32_16x16x32_bf16 v[66:69], v[168:171], v[200:203], v[66:69]
	v_mfma_f32_16x16x32_bf16 v[118:121], v[164:167], v[180:183], v[118:121]
	v_mfma_f32_16x16x32_bf16 v[114:117], v[172:175], v[180:183], v[114:117]
	v_mfma_f32_16x16x32_bf16 v[102:105], v[164:167], v[188:191], v[102:105]
	v_mfma_f32_16x16x32_bf16 v[98:101], v[172:175], v[188:191], v[98:101]
	v_mfma_f32_16x16x32_bf16 v[86:89], v[164:167], v[196:199], v[86:89]
	v_mfma_f32_16x16x32_bf16 v[82:85], v[172:175], v[196:199], v[82:85]
	v_mfma_f32_16x16x32_bf16 v[70:73], v[164:167], v[204:207], v[70:73]
	v_mfma_f32_16x16x32_bf16 v[66:69], v[172:175], v[204:207], v[66:69]
	s_barrier
	s_add_i32 s10, s63, s71
	v_lshl_add_u64 v[208:209], s[92:93], 0, v[0:1]
	s_mov_b32 m0, s10
	ds_read_b128 v[176:179], v143 offset:16384
	ds_read_b128 v[180:183], v143 offset:17408
	ds_read_b128 v[184:187], v143 offset:18432
	ds_read_b128 v[188:191], v143 offset:19456
	ds_read_b128 v[192:195], v143 offset:20480
	ds_read_b128 v[196:199], v143 offset:21504
	ds_read_b128 v[200:203], v143 offset:22528
	ds_read_b128 v[204:207], v143 offset:23552
	global_load_lds_dwordx4 v[208:209], off
	s_add_i32 m0, s10, 0x2000
	s_add_u32 s10, s92, 0x40000
	v_lshl_add_u64 v[210:211], s[92:93], 0, v[130:131]
	s_addc_u32 s11, s93, 0
	s_add_i32 s63, s90, s71
	global_load_lds_dwordx4 v[210:211], off
	v_lshl_add_u64 v[212:213], s[10:11], 0, v[0:1]
	s_mov_b32 m0, s63
	v_lshl_add_u64 v[218:219], s[94:95], 0, v[132:133]
	global_load_lds_dwordx4 v[212:213], off
	v_lshl_add_u64 v[212:213], s[10:11], 0, v[130:131]
	s_add_i32 m0, s63, 0x2000
	s_nop 0
	global_load_lds_dwordx4 v[212:213], off
	v_lshl_add_u64 v[212:213], s[94:95], 0, v[134:135]
	s_mov_b32 m0, s31
	s_nop 0
	global_load_lds_dwordx4 v[212:213], off
	s_mov_b32 m0, s73
	s_nop 0
	global_load_lds_dwordx4 v[218:219], off
	s_waitcnt vmcnt(8)
	s_waitcnt lgkmcnt(0)
	s_barrier
; #define PG8_STAGE(bufoff, gbase, voff) do { _Pragma("unroll") for (int _i = 0; _i < 2; ++_i) \
;         __builtin_amdgcn_global_load_lds((const unsigned*)((const char*)(gbase) + (voff)[_i]), (LAS unsigned*)(lds + (bufoff) + ldsw + _i * 8192), 16, 0, 0); } while (0)
; #define PG8_LDA(dst, b, h) do { _Pragma("unroll") for (int m = 0; m < 4; ++m) _Pragma("unroll") for (int k = 0; k < 2; ++k) dst[m][k] = *(const LAS bf16x8*)(lds + PG8_SA(b, h) + aoff + m * 2048 + k * 1024); } while (0)
; #define PG8_LDB(dst, b, h) do { _Pragma("unroll") for (int n = 0; n < 2; ++n) _Pragma("unroll") for (int k = 0; k < 2; ++k) dst[n][k] = *(const LAS bf16x8*)(lds + PG8_SB(b, h) + boff + n * 2048 + k * 1024); } while (0)
; #define PG8_MMA(ai, bj, At, Bt) do { __builtin_amdgcn_s_setprio(1); _Pragma("unroll") for (int m = 0; m < 4; ++m) _Pragma("unroll") for (int n = 0; n < 2; ++n) _Pragma("unroll") for (int k = 0; k < 2; ++k) \
;         acc[ai][bj][m][n] = __builtin_amdgcn_mfma_f32_16x16x32_bf16(Bt[n][k], At[m][k], acc[ai][bj][m][n], 0, 0, 0); __builtin_amdgcn_s_setprio(0); } while (0)
; #define PG8_WAIT_V(n) asm volatile("s_waitcnt vmcnt(" #n ")" ::: "memory")
; #define PG8_WAIT_L(n) asm volatile("s_waitcnt lgkmcnt(" #n ")" ::: "memory")
; #define PG8_BAR __builtin_amdgcn_s_barrier()
; #define PG8_SCHED __builtin_amdgcn_sched_barrier(0)
; template <class EpiT, class Sched>
; __device__ __forceinline__ void gemm_phase(LAS unsigned char* lds, int tid_in, const GemmDesc g, const Sched& S, const EpiT& E) {
;     ...
;             PG8_WAIT_V(8); PG8_WAIT_L(0); PG8_BAR; PG8_MMA(1, 0, At, B0); PG8_MMA(1, 1, At, B1); PG8_BAR; PG8_SCHED;
;             PG8_LDB(B0, 1, 0); PG8_LDB(B1, 1, 1); PG8_SCHED; PG8_LDA(At, 1, 0); PG8_STAGE(PG8_SA(0, 1), a2 + hA, voffA);
;             PG8_WAIT_V(8); PG8_WAIT_L(0); PG8_BAR; PG8_MMA(0, 0, At, B0); PG8_MMA(0, 1, At, B1); PG8_BAR; PG8_SCHED;
	s_waitcnt lgkmcnt(0)
	v_mfma_f32_16x16x32_bf16 v[62:65], v[144:147], v[176:179], v[62:65]
	v_mfma_f32_16x16x32_bf16 v[58:61], v[152:155], v[176:179], v[58:61]
	v_mfma_f32_16x16x32_bf16 v[46:49], v[144:147], v[184:187], v[46:49]
	v_mfma_f32_16x16x32_bf16 v[42:45], v[152:155], v[184:187], v[42:45]
	v_mfma_f32_16x16x32_bf16 v[30:33], v[144:147], v[192:195], v[30:33]
	v_mfma_f32_16x16x32_bf16 v[26:29], v[152:155], v[192:195], v[26:29]
	v_mfma_f32_16x16x32_bf16 v[14:17], v[144:147], v[200:203], v[14:17]
	v_mfma_f32_16x16x32_bf16 v[10:13], v[152:155], v[200:203], v[10:13]
	v_mfma_f32_16x16x32_bf16 v[62:65], v[148:151], v[180:183], v[62:65]
	v_mfma_f32_16x16x32_bf16 v[58:61], v[156:159], v[180:183], v[58:61]
	v_mfma_f32_16x16x32_bf16 v[46:49], v[148:151], v[188:191], v[46:49]
	v_mfma_f32_16x16x32_bf16 v[42:45], v[156:159], v[188:191], v[42:45]
	v_mfma_f32_16x16x32_bf16 v[30:33], v[148:151], v[196:199], v[30:33]
	v_mfma_f32_16x16x32_bf16 v[26:29], v[156:159], v[196:199], v[26:29]
	v_mfma_f32_16x16x32_bf16 v[14:17], v[148:151], v[204:207], v[14:17]
	v_mfma_f32_16x16x32_bf16 v[10:13], v[156:159], v[204:207], v[10:13]
	v_mfma_f32_16x16x32_bf16 v[54:57], v[160:163], v[176:179], v[54:57]
	v_mfma_f32_16x16x32_bf16 v[50:53], v[168:171], v[176:179], v[50:53]
	v_mfma_f32_16x16x32_bf16 v[38:41], v[160:163], v[184:187], v[38:41]
	v_mfma_f32_16x16x32_bf16 v[34:37], v[168:171], v[184:187], v[34:37]
	v_mfma_f32_16x16x32_bf16 v[22:25], v[160:163], v[192:195], v[22:25]
	v_mfma_f32_16x16x32_bf16 v[18:21], v[168:171], v[192:195], v[18:21]
	v_mfma_f32_16x16x32_bf16 v[6:9], v[160:163], v[200:203], v[6:9]
	v_mfma_f32_16x16x32_bf16 v[2:5], v[168:171], v[200:203], v[2:5]
	v_mfma_f32_16x16x32_bf16 v[54:57], v[164:167], v[180:183], v[54:57]
	v_mfma_f32_16x16x32_bf16 v[50:53], v[172:175], v[180:183], v[50:53]
	v_mfma_f32_16x16x32_bf16 v[38:41], v[164:167], v[188:191], v[38:41]
	v_mfma_f32_16x16x32_bf16 v[34:37], v[172:175], v[188:191], v[34:37]
	v_mfma_f32_16x16x32_bf16 v[22:25], v[164:167], v[196:199], v[22:25]
	v_mfma_f32_16x16x32_bf16 v[18:21], v[172:175], v[196:199], v[18:21]
	v_mfma_f32_16x16x32_bf16 v[6:9], v[164:167], v[204:207], v[6:9]
	v_mfma_f32_16x16x32_bf16 v[2:5], v[172:175], v[204:207], v[2:5]
	s_barrier
	s_add_i32 s63, 0, 0x18000
	s_add_i32 s90, 0, 0x1c000
	v_add_u32_e32 v156, s63, v141
	v_add_u32_e32 v172, s90, v141
	ds_read_b128 v[144:147], v156
	ds_read_b128 v[148:151], v156 offset:1024
	ds_read_b128 v[152:155], v156 offset:2048
	ds_read_b128 v[156:159], v156 offset:3072
	ds_read_b128 v[160:163], v172
	ds_read_b128 v[164:167], v172 offset:1024
	ds_read_b128 v[168:171], v172 offset:2048
	ds_read_b128 v[172:175], v172 offset:3072
	s_add_u32 s10, s94, 0x40000
	s_addc_u32 s11, s95, 0
	s_mov_b32 m0, s74
	v_lshl_add_u64 v[220:221], s[10:11], 0, v[134:135]
	ds_read_b128 v[176:179], v143 offset:32768
	ds_read_b128 v[180:183], v143 offset:33792
	ds_read_b128 v[184:187], v143 offset:34816
	ds_read_b128 v[188:191], v143 offset:35840
	ds_read_b128 v[192:195], v143 offset:36864
	ds_read_b128 v[196:199], v143 offset:37888
	ds_read_b128 v[200:203], v143 offset:38912
	ds_read_b128 v[204:207], v143 offset:39936
	global_load_lds_dwordx4 v[220:221], off
	v_lshl_add_u64 v[220:221], s[10:11], 0, v[132:133]
	s_mov_b32 m0, s75
	s_nop 0
	global_load_lds_dwordx4 v[220:221], off
	s_waitcnt vmcnt(8)
	s_waitcnt lgkmcnt(0)
	s_barrier
	s_waitcnt lgkmcnt(0)
	v_mfma_f32_16x16x32_bf16 v[126:129], v[144:147], v[176:179], v[126:129]
	v_mfma_f32_16x16x32_bf16 v[122:125], v[152:155], v[176:179], v[122:125]
	v_mfma_f32_16x16x32_bf16 v[110:113], v[144:147], v[184:187], v[110:113]
	v_mfma_f32_16x16x32_bf16 v[106:109], v[152:155], v[184:187], v[106:109]
	v_mfma_f32_16x16x32_bf16 v[94:97], v[144:147], v[192:195], v[94:97]
	v_mfma_f32_16x16x32_bf16 v[90:93], v[152:155], v[192:195], v[90:93]
	v_mfma_f32_16x16x32_bf16 v[78:81], v[144:147], v[200:203], v[78:81]
	v_mfma_f32_16x16x32_bf16 v[74:77], v[152:155], v[200:203], v[74:77]
	v_mfma_f32_16x16x32_bf16 v[126:129], v[148:151], v[180:183], v[126:129]
	v_mfma_f32_16x16x32_bf16 v[122:125], v[156:159], v[180:183], v[122:125]
	v_mfma_f32_16x16x32_bf16 v[110:113], v[148:151], v[188:191], v[110:113]
	v_mfma_f32_16x16x32_bf16 v[106:109], v[156:159], v[188:191], v[106:109]
	v_mfma_f32_16x16x32_bf16 v[94:97], v[148:151], v[196:199], v[94:97]
	v_mfma_f32_16x16x32_bf16 v[90:93], v[156:159], v[196:199], v[90:93]
	v_mfma_f32_16x16x32_bf16 v[78:81], v[148:151], v[204:207], v[78:81]
	v_mfma_f32_16x16x32_bf16 v[74:77], v[156:159], v[204:207], v[74:77]
	v_mfma_f32_16x16x32_bf16 v[118:121], v[160:163], v[176:179], v[118:121]
	v_mfma_f32_16x16x32_bf16 v[114:117], v[168:171], v[176:179], v[114:117]
	v_mfma_f32_16x16x32_bf16 v[102:105], v[160:163], v[184:187], v[102:105]
	v_mfma_f32_16x16x32_bf16 v[98:101], v[168:171], v[184:187], v[98:101]
	v_mfma_f32_16x16x32_bf16 v[86:89], v[160:163], v[192:195], v[86:89]
	v_mfma_f32_16x16x32_bf16 v[82:85], v[168:171], v[192:195], v[82:85]
	v_mfma_f32_16x16x32_bf16 v[70:73], v[160:163], v[200:203], v[70:73]
	v_mfma_f32_16x16x32_bf16 v[66:69], v[168:171], v[200:203], v[66:69]
	v_mfma_f32_16x16x32_bf16 v[118:121], v[164:167], v[180:183], v[118:121]
	v_mfma_f32_16x16x32_bf16 v[114:117], v[172:175], v[180:183], v[114:117]
	v_mfma_f32_16x16x32_bf16 v[102:105], v[164:167], v[188:191], v[102:105]
	v_mfma_f32_16x16x32_bf16 v[98:101], v[172:175], v[188:191], v[98:101]
	v_mfma_f32_16x16x32_bf16 v[86:89], v[164:167], v[196:199], v[86:89]
	v_mfma_f32_16x16x32_bf16 v[82:85], v[172:175], v[196:199], v[82:85]
	v_mfma_f32_16x16x32_bf16 v[70:73], v[164:167], v[204:207], v[70:73]
	v_mfma_f32_16x16x32_bf16 v[66:69], v[172:175], v[204:207], v[66:69]
	s_barrier
; #define PG8_STAGE(bufoff, gbase, voff) do { _Pragma("unroll") for (int _i = 0; _i < 2; ++_i) \
;         __builtin_amdgcn_global_load_lds((const unsigned*)((const char*)(gbase) + (voff)[_i]), (LAS unsigned*)(lds + (bufoff) + ldsw + _i * 8192), 16, 0, 0); } while (0)
; #define PG8_LDA(dst, b, h) do { _Pragma("unroll") for (int m = 0; m < 4; ++m) _Pragma("unroll") for (int k = 0; k < 2; ++k) dst[m][k] = *(const LAS bf16x8*)(lds + PG8_SA(b, h) + aoff + m * 2048 + k * 1024); } while (0)
; #define PG8_MMA(ai, bj, At, Bt) do { __builtin_amdgcn_s_setprio(1); _Pragma("unroll") for (int m = 0; m < 4; ++m) _Pragma("unroll") for (int n = 0; n < 2; ++n) _Pragma("unroll") for (int k = 0; k < 2; ++k) \
;         acc[ai][bj][m][n] = __builtin_amdgcn_mfma_f32_16x16x32_bf16(Bt[n][k], At[m][k], acc[ai][bj][m][n], 0, 0, 0); __builtin_amdgcn_s_setprio(0); } while (0)
; #define PG8_WAIT_V(n) asm volatile("s_waitcnt vmcnt(" #n ")" ::: "memory")
; #define PG8_WAIT_L(n) asm volatile("s_waitcnt lgkmcnt(" #n ")" ::: "memory")
; #define PG8_BAR __builtin_amdgcn_s_barrier()
; #define PG8_SCHED __builtin_amdgcn_sched_barrier(0)
; template <class EpiT, class Sched>
; __device__ __forceinline__ void gemm_phase(LAS unsigned char* lds, int tid_in, const GemmDesc g, const Sched& S, const EpiT& E) {
;     ...
;             PG8_LDA(At, 1, 1); PG8_STAGE(PG8_SB(1, 0), b3, voffB); PG8_STAGE(PG8_SB(1, 1), b3 + hB, voffB); PG8_STAGE(PG8_SA(1, 0), a3, voffA);
;             PG8_WAIT_V(8); PG8_WAIT_L(0); PG8_BAR; PG8_MMA(1, 0, At, B0); PG8_MMA(1, 1, At, B1); PG8_BAR; PG8_SCHED;
;         }
;         if (wr == 0) PG8_BAR;
	s_add_i32 s10, s63, s71
	v_lshl_add_u64 v[208:209], v[208:209], 0, s[60:61]
	s_mov_b32 m0, s10
	ds_read_b128 v[176:179], v143 offset:49152
	ds_read_b128 v[180:183], v143 offset:50176
	ds_read_b128 v[184:187], v143 offset:51200
	ds_read_b128 v[188:191], v143 offset:52224
	ds_read_b128 v[192:195], v143 offset:53248
	ds_read_b128 v[196:199], v143 offset:54272
	ds_read_b128 v[200:203], v143 offset:55296
	ds_read_b128 v[204:207], v143 offset:56320
	global_load_lds_dwordx4 v[208:209], off
	s_add_i32 m0, s10, 0x2000
	s_add_u32 s10, s92, 0x40080
	v_lshl_add_u64 v[208:209], v[210:211], 0, s[60:61]
	s_addc_u32 s11, s93, 0
	s_add_i32 s63, s90, s71
	global_load_lds_dwordx4 v[208:209], off
	v_lshl_add_u64 v[208:209], s[10:11], 0, v[0:1]
	s_mov_b32 m0, s63
	s_nop 0
	global_load_lds_dwordx4 v[208:209], off
	v_lshl_add_u64 v[208:209], s[10:11], 0, v[130:131]
	s_add_i32 m0, s63, 0x2000
	s_nop 0
	global_load_lds_dwordx4 v[208:209], off
	v_lshl_add_u64 v[208:209], v[212:213], 0, s[60:61]
	s_mov_b32 m0, s76
	s_nop 0
	global_load_lds_dwordx4 v[208:209], off
	v_lshl_add_u64 v[208:209], v[218:219], 0, s[60:61]
	s_mov_b32 m0, s77
	s_nop 0
	global_load_lds_dwordx4 v[208:209], off
	s_waitcnt vmcnt(8)
	s_waitcnt lgkmcnt(0)
	s_barrier
	s_waitcnt lgkmcnt(0)
	v_mfma_f32_16x16x32_bf16 v[62:65], v[144:147], v[176:179], v[62:65]
	v_mfma_f32_16x16x32_bf16 v[58:61], v[152:155], v[176:179], v[58:61]
	v_mfma_f32_16x16x32_bf16 v[46:49], v[144:147], v[184:187], v[46:49]
	v_mfma_f32_16x16x32_bf16 v[42:45], v[152:155], v[184:187], v[42:45]
	v_mfma_f32_16x16x32_bf16 v[30:33], v[144:147], v[192:195], v[30:33]
	v_mfma_f32_16x16x32_bf16 v[26:29], v[152:155], v[192:195], v[26:29]
	v_mfma_f32_16x16x32_bf16 v[14:17], v[144:147], v[200:203], v[14:17]
	v_mfma_f32_16x16x32_bf16 v[10:13], v[152:155], v[200:203], v[10:13]
	v_mfma_f32_16x16x32_bf16 v[62:65], v[148:151], v[180:183], v[62:65]
	v_mfma_f32_16x16x32_bf16 v[58:61], v[156:159], v[180:183], v[58:61]
	v_mfma_f32_16x16x32_bf16 v[46:49], v[148:151], v[188:191], v[46:49]
	v_mfma_f32_16x16x32_bf16 v[42:45], v[156:159], v[188:191], v[42:45]
	v_mfma_f32_16x16x32_bf16 v[30:33], v[148:151], v[196:199], v[30:33]
	v_mfma_f32_16x16x32_bf16 v[26:29], v[156:159], v[196:199], v[26:29]
	v_mfma_f32_16x16x32_bf16 v[14:17], v[148:151], v[204:207], v[14:17]
	v_mfma_f32_16x16x32_bf16 v[10:13], v[156:159], v[204:207], v[10:13]
	v_mfma_f32_16x16x32_bf16 v[54:57], v[160:163], v[176:179], v[54:57]
	v_mfma_f32_16x16x32_bf16 v[50:53], v[168:171], v[176:179], v[50:53]
	v_mfma_f32_16x16x32_bf16 v[38:41], v[160:163], v[184:187], v[38:41]
	v_mfma_f32_16x16x32_bf16 v[34:37], v[168:171], v[184:187], v[34:37]
	v_mfma_f32_16x16x32_bf16 v[22:25], v[160:163], v[192:195], v[22:25]
	v_mfma_f32_16x16x32_bf16 v[18:21], v[168:171], v[192:195], v[18:21]
	v_mfma_f32_16x16x32_bf16 v[6:9], v[160:163], v[200:203], v[6:9]
	v_mfma_f32_16x16x32_bf16 v[2:5], v[168:171], v[200:203], v[2:5]
	v_mfma_f32_16x16x32_bf16 v[54:57], v[164:167], v[180:183], v[54:57]
	v_mfma_f32_16x16x32_bf16 v[50:53], v[172:175], v[180:183], v[50:53]
	v_mfma_f32_16x16x32_bf16 v[38:41], v[164:167], v[188:191], v[38:41]
	v_mfma_f32_16x16x32_bf16 v[34:37], v[172:175], v[188:191], v[34:37]
	v_mfma_f32_16x16x32_bf16 v[22:25], v[164:167], v[196:199], v[22:25]
	v_mfma_f32_16x16x32_bf16 v[18:21], v[172:175], v[196:199], v[18:21]
	v_mfma_f32_16x16x32_bf16 v[6:9], v[164:167], v[204:207], v[6:9]
	v_mfma_f32_16x16x32_bf16 v[2:5], v[172:175], v[204:207], v[2:5]
	s_barrier
	s_add_i32 s62, s62, 2
	s_add_u32 vcc_lo, vcc_lo, 0x100
	s_addc_u32 vcc_hi, vcc_hi, 0
	s_add_u32 s81, s81, 0x100
	s_addc_u32 s89, s89, 0
	s_cmp_gt_u32 s62, 13
	s_cbranch_scc0 .LBB0_947
	s_and_b64 vcc, exec, s[22:23]
	s_cbranch_vccz .LBB0_950
	s_barrier

; #define PG8_STAGE(bufoff, gbase, voff) do { _Pragma("unroll") for (int _i = 0; _i < 2; ++_i) \
;         __builtin_amdgcn_global_load_lds((const unsigned*)((const char*)(gbase) + (voff)[_i]), (LAS unsigned*)(lds + (bufoff) + ldsw + _i * 8192), 16, 0, 0); } while (0)
; #define PG8_LDA(dst, b, h) do { _Pragma("unroll") for (int m = 0; m < 4; ++m) _Pragma("unroll") for (int k = 0; k < 2; ++k) dst[m][k] = *(const LAS bf16x8*)(lds + PG8_SA(b, h) + aoff + m * 2048 + k * 1024); } while (0)
; #define PG8_LDB(dst, b, h) do { _Pragma("unroll") for (int n = 0; n < 2; ++n) _Pragma("unroll") for (int k = 0; k < 2; ++k) dst[n][k] = *(const LAS bf16x8*)(lds + PG8_SB(b, h) + boff + n * 2048 + k * 1024); } while (0)
; #define PG8_MMA(ai, bj, At, Bt) do { __builtin_amdgcn_s_setprio(1); _Pragma("unroll") for (int m = 0; m < 4; ++m) _Pragma("unroll") for (int n = 0; n < 2; ++n) _Pragma("unroll") for (int k = 0; k < 2; ++k) \
;         acc[ai][bj][m][n] = __builtin_amdgcn_mfma_f32_16x16x32_bf16(Bt[n][k], At[m][k], acc[ai][bj][m][n], 0, 0, 0); __builtin_amdgcn_s_setprio(0); } while (0)
; #define PG8_WAIT_V(n) asm volatile("s_waitcnt vmcnt(" #n ")" ::: "memory")
; #define PG8_WAIT_L(n) asm volatile("s_waitcnt lgkmcnt(" #n ")" ::: "memory")
; #define PG8_BAR __builtin_amdgcn_s_barrier()
; #define PG8_SCHED __builtin_amdgcn_sched_barrier(0)
; template <class EpiT, class Sched>
; __device__ __forceinline__ void gemm_phase(LAS unsigned char* lds, int tid_in, const GemmDesc g, const Sched& S, const EpiT& E) {
;     ...
;             const bool last = (t == nt - 2);
;             const char* a1 = cA + (size_t)(t + 1) * kA;
;             const char* a2 = last ? nA : cA + (size_t)(t + 2) * kA; const char* b2 = last ? nB : cB + (size_t)(t + 2) * kB;
;             const char* a3 = a2 + kA; const char* b3 = b2 + kB;
;             PG8_LDB(B0, 0, 0); PG8_LDB(B1, 0, 1); PG8_SCHED; PG8_LDA(At, 0, 0); PG8_STAGE(PG8_SA(1, 1), a1 + hA, voffA);
;             PG8_WAIT_V(8); PG8_WAIT_L(0); PG8_BAR; PG8_MMA(0, 0, At, B0); PG8_MMA(0, 1, At, B1); PG8_BAR; PG8_SCHED;
;             PG8_LDA(At, 0, 1); PG8_STAGE(PG8_SB(0, 0), b2, voffB); PG8_STAGE(PG8_SB(0, 1), b2 + hB, voffB); PG8_STAGE(PG8_SA(0, 0), a2, voffA);
.LBB0_1025:
	s_add_u32 s86, s4, 0x100
	s_addc_u32 s87, s5, 0
	s_add_i32 s11, 0, 0x10000
	s_cmp_eq_u32 s10, 4
	s_cselect_b32 s93, s2, s87
	s_cselect_b32 s92, s3, s86
	s_cselect_b32 s89, vcc_lo, s63
	s_cselect_b32 s88, vcc_hi, s62
	s_add_i32 s28, 0, 0x14000
	v_add_u32_e32 v142, s11, v211
	v_add_u32_e32 v158, s28, v211
	ds_read_b128 v[130:133], v142
	ds_read_b128 v[134:137], v142 offset:1024
	ds_read_b128 v[138:141], v142 offset:2048
	ds_read_b128 v[142:145], v142 offset:3072
	ds_read_b128 v[146:149], v158
	ds_read_b128 v[150:153], v158 offset:1024
	ds_read_b128 v[154:157], v158 offset:2048
	ds_read_b128 v[158:161], v158 offset:3072
	v_lshl_add_u64 v[194:195], s[4:5], 0, v[202:203]
	s_add_i32 m0, s74, 0xc000
	ds_read_b128 v[162:165], v229
	ds_read_b128 v[166:169], v229 offset:1024
	ds_read_b128 v[170:173], v229 offset:2048
	ds_read_b128 v[174:177], v229 offset:3072
	ds_read_b128 v[178:181], v229 offset:4096
	ds_read_b128 v[182:185], v229 offset:5120
	ds_read_b128 v[186:189], v229 offset:6144
	ds_read_b128 v[190:193], v229 offset:7168
	global_load_lds_dwordx4 v[194:195], off
	v_lshl_add_u64 v[194:195], s[4:5], 0, v[204:205]
	s_add_i32 m0, s74, 0xe000
	s_nop 0
	global_load_lds_dwordx4 v[194:195], off
	s_waitcnt vmcnt(8)
	s_waitcnt lgkmcnt(0)
	s_barrier
	s_waitcnt lgkmcnt(0)
	v_mfma_f32_16x16x32_bf16 v[126:129], v[130:133], v[162:165], v[126:129]
	v_mfma_f32_16x16x32_bf16 v[122:125], v[138:141], v[162:165], v[122:125]
	v_mfma_f32_16x16x32_bf16 v[110:113], v[130:133], v[170:173], v[110:113]
	v_mfma_f32_16x16x32_bf16 v[106:109], v[138:141], v[170:173], v[106:109]
	v_mfma_f32_16x16x32_bf16 v[94:97], v[130:133], v[178:181], v[94:97]
	v_mfma_f32_16x16x32_bf16 v[90:93], v[138:141], v[178:181], v[90:93]
	v_mfma_f32_16x16x32_bf16 v[78:81], v[130:133], v[186:189], v[78:81]
	v_mfma_f32_16x16x32_bf16 v[74:77], v[138:141], v[186:189], v[74:77]
	v_mfma_f32_16x16x32_bf16 v[126:129], v[134:137], v[166:169], v[126:129]
	v_mfma_f32_16x16x32_bf16 v[122:125], v[142:145], v[166:169], v[122:125]
	v_mfma_f32_16x16x32_bf16 v[110:113], v[134:137], v[174:177], v[110:113]
	v_mfma_f32_16x16x32_bf16 v[106:109], v[142:145], v[174:177], v[106:109]
	v_mfma_f32_16x16x32_bf16 v[94:97], v[134:137], v[182:185], v[94:97]
	v_mfma_f32_16x16x32_bf16 v[90:93], v[142:145], v[182:185], v[90:93]
	v_mfma_f32_16x16x32_bf16 v[78:81], v[134:137], v[190:193], v[78:81]
	v_mfma_f32_16x16x32_bf16 v[74:77], v[142:145], v[190:193], v[74:77]
	v_mfma_f32_16x16x32_bf16 v[118:121], v[146:149], v[162:165], v[118:121]
	v_mfma_f32_16x16x32_bf16 v[114:117], v[154:157], v[162:165], v[114:117]
	v_mfma_f32_16x16x32_bf16 v[102:105], v[146:149], v[170:173], v[102:105]
	v_mfma_f32_16x16x32_bf16 v[98:101], v[154:157], v[170:173], v[98:101]
	v_mfma_f32_16x16x32_bf16 v[86:89], v[146:149], v[178:181], v[86:89]
	v_mfma_f32_16x16x32_bf16 v[82:85], v[154:157], v[178:181], v[82:85]
	v_mfma_f32_16x16x32_bf16 v[70:73], v[146:149], v[186:189], v[70:73]
	v_mfma_f32_16x16x32_bf16 v[66:69], v[154:157], v[186:189], v[66:69]
	v_mfma_f32_16x16x32_bf16 v[118:121], v[150:153], v[166:169], v[118:121]
	v_mfma_f32_16x16x32_bf16 v[114:117], v[158:161], v[166:169], v[114:117]
	v_mfma_f32_16x16x32_bf16 v[102:105], v[150:153], v[174:177], v[102:105]
	v_mfma_f32_16x16x32_bf16 v[98:101], v[158:161], v[174:177], v[98:101]
	v_mfma_f32_16x16x32_bf16 v[86:89], v[150:153], v[182:185], v[86:89]
	v_mfma_f32_16x16x32_bf16 v[82:85], v[158:161], v[182:185], v[82:85]
	v_mfma_f32_16x16x32_bf16 v[70:73], v[150:153], v[190:193], v[70:73]
	v_mfma_f32_16x16x32_bf16 v[66:69], v[158:161], v[190:193], v[66:69]
	s_barrier
	s_add_i32 s4, s11, s17
	v_lshl_add_u64 v[194:195], s[88:89], 0, v[0:1]
	s_mov_b32 m0, s4
	ds_read_b128 v[162:165], v229 offset:16384
	ds_read_b128 v[166:169], v229 offset:17408
	ds_read_b128 v[170:173], v229 offset:18432
	ds_read_b128 v[174:177], v229 offset:19456
	ds_read_b128 v[178:181], v229 offset:20480
	ds_read_b128 v[182:185], v229 offset:21504
	ds_read_b128 v[186:189], v229 offset:22528
	ds_read_b128 v[190:193], v229 offset:23552
	global_load_lds_dwordx4 v[194:195], off
	s_add_i32 m0, s4, 0x2000
	s_add_u32 s4, s88, 0x60000
	v_lshl_add_u64 v[206:207], s[88:89], 0, v[200:201]
	s_addc_u32 s5, s89, 0
	s_add_i32 s11, s28, s17
	global_load_lds_dwordx4 v[206:207], off
	v_lshl_add_u64 v[208:209], s[4:5], 0, v[0:1]
	s_mov_b32 m0, s11
	v_lshl_add_u64 v[212:213], s[92:93], 0, v[198:199]
	global_load_lds_dwordx4 v[208:209], off
	v_lshl_add_u64 v[208:209], s[4:5], 0, v[200:201]
	s_add_i32 m0, s11, 0x2000
	s_nop 0
	global_load_lds_dwordx4 v[208:209], off
	v_lshl_add_u64 v[208:209], s[92:93], 0, v[196:197]
	s_mov_b32 m0, s74
	s_nop 0
	global_load_lds_dwordx4 v[208:209], off
	s_mov_b32 m0, s75
	s_nop 0
	global_load_lds_dwordx4 v[212:213], off
	s_waitcnt vmcnt(8)
	s_waitcnt lgkmcnt(0)
	s_barrier
; #define PG8_STAGE(bufoff, gbase, voff) do { _Pragma("unroll") for (int _i = 0; _i < 2; ++_i) \
;         __builtin_amdgcn_global_load_lds((const unsigned*)((const char*)(gbase) + (voff)[_i]), (LAS unsigned*)(lds + (bufoff) + ldsw + _i * 8192), 16, 0, 0); } while (0)
; #define PG8_LDA(dst, b, h) do { _Pragma("unroll") for (int m = 0; m < 4; ++m) _Pragma("unroll") for (int k = 0; k < 2; ++k) dst[m][k] = *(const LAS bf16x8*)(lds + PG8_SA(b, h) + aoff + m * 2048 + k * 1024); } while (0)
; #define PG8_LDB(dst, b, h) do { _Pragma("unroll") for (int n = 0; n < 2; ++n) _Pragma("unroll") for (int k = 0; k < 2; ++k) dst[n][k] = *(const LAS bf16x8*)(lds + PG8_SB(b, h) + boff + n * 2048 + k * 1024); } while (0)
; #define PG8_MMA(ai, bj, At, Bt) do { __builtin_amdgcn_s_setprio(1); _Pragma("unroll") for (int m = 0; m < 4; ++m) _Pragma("unroll") for (int n = 0; n < 2; ++n) _Pragma("unroll") for (int k = 0; k < 2; ++k) \
;         acc[ai][bj][m][n] = __builtin_amdgcn_mfma_f32_16x16x32_bf16(Bt[n][k], At[m][k], acc[ai][bj][m][n], 0, 0, 0); __builtin_amdgcn_s_setprio(0); } while (0)
; #define PG8_WAIT_V(n) asm volatile("s_waitcnt vmcnt(" #n ")" ::: "memory")
; #define PG8_WAIT_L(n) asm volatile("s_waitcnt lgkmcnt(" #n ")" ::: "memory")
; #define PG8_BAR __builtin_amdgcn_s_barrier()
; #define PG8_SCHED __builtin_amdgcn_sched_barrier(0)
; template <class EpiT, class Sched>
; __device__ __forceinline__ void gemm_phase(LAS unsigned char* lds, int tid_in, const GemmDesc g, const Sched& S, const EpiT& E) {
;     ...
;             PG8_WAIT_V(8); PG8_WAIT_L(0); PG8_BAR; PG8_MMA(1, 0, At, B0); PG8_MMA(1, 1, At, B1); PG8_BAR; PG8_SCHED;
;             PG8_LDB(B0, 1, 0); PG8_LDB(B1, 1, 1); PG8_SCHED; PG8_LDA(At, 1, 0); PG8_STAGE(PG8_SA(0, 1), a2 + hA, voffA);
;             PG8_WAIT_V(8); PG8_WAIT_L(0); PG8_BAR; PG8_MMA(0, 0, At, B0); PG8_MMA(0, 1, At, B1); PG8_BAR; PG8_SCHED;
	s_waitcnt lgkmcnt(0)
	v_mfma_f32_16x16x32_bf16 v[62:65], v[130:133], v[162:165], v[62:65]
	v_mfma_f32_16x16x32_bf16 v[58:61], v[138:141], v[162:165], v[58:61]
	v_mfma_f32_16x16x32_bf16 v[46:49], v[130:133], v[170:173], v[46:49]
	v_mfma_f32_16x16x32_bf16 v[42:45], v[138:141], v[170:173], v[42:45]
	v_mfma_f32_16x16x32_bf16 v[30:33], v[130:133], v[178:181], v[30:33]
	v_mfma_f32_16x16x32_bf16 v[26:29], v[138:141], v[178:181], v[26:29]
	v_mfma_f32_16x16x32_bf16 v[14:17], v[130:133], v[186:189], v[14:17]
	v_mfma_f32_16x16x32_bf16 v[10:13], v[138:141], v[186:189], v[10:13]
	v_mfma_f32_16x16x32_bf16 v[62:65], v[134:137], v[166:169], v[62:65]
	v_mfma_f32_16x16x32_bf16 v[58:61], v[142:145], v[166:169], v[58:61]
	v_mfma_f32_16x16x32_bf16 v[46:49], v[134:137], v[174:177], v[46:49]
	v_mfma_f32_16x16x32_bf16 v[42:45], v[142:145], v[174:177], v[42:45]
	v_mfma_f32_16x16x32_bf16 v[30:33], v[134:137], v[182:185], v[30:33]
	v_mfma_f32_16x16x32_bf16 v[26:29], v[142:145], v[182:185], v[26:29]
	v_mfma_f32_16x16x32_bf16 v[14:17], v[134:137], v[190:193], v[14:17]
	v_mfma_f32_16x16x32_bf16 v[10:13], v[142:145], v[190:193], v[10:13]
	v_mfma_f32_16x16x32_bf16 v[54:57], v[146:149], v[162:165], v[54:57]
	v_mfma_f32_16x16x32_bf16 v[50:53], v[154:157], v[162:165], v[50:53]
	v_mfma_f32_16x16x32_bf16 v[38:41], v[146:149], v[170:173], v[38:41]
	v_mfma_f32_16x16x32_bf16 v[34:37], v[154:157], v[170:173], v[34:37]
	v_mfma_f32_16x16x32_bf16 v[22:25], v[146:149], v[178:181], v[22:25]
	v_mfma_f32_16x16x32_bf16 v[18:21], v[154:157], v[178:181], v[18:21]
	v_mfma_f32_16x16x32_bf16 v[6:9], v[146:149], v[186:189], v[6:9]
	v_mfma_f32_16x16x32_bf16 v[2:5], v[154:157], v[186:189], v[2:5]
	v_mfma_f32_16x16x32_bf16 v[54:57], v[150:153], v[166:169], v[54:57]
	v_mfma_f32_16x16x32_bf16 v[50:53], v[158:161], v[166:169], v[50:53]
	v_mfma_f32_16x16x32_bf16 v[38:41], v[150:153], v[174:177], v[38:41]
	v_mfma_f32_16x16x32_bf16 v[34:37], v[158:161], v[174:177], v[34:37]
	v_mfma_f32_16x16x32_bf16 v[22:25], v[150:153], v[182:185], v[22:25]
	v_mfma_f32_16x16x32_bf16 v[18:21], v[158:161], v[182:185], v[18:21]
	v_mfma_f32_16x16x32_bf16 v[6:9], v[150:153], v[190:193], v[6:9]
	v_mfma_f32_16x16x32_bf16 v[2:5], v[158:161], v[190:193], v[2:5]
	s_barrier
	s_add_i32 s11, 0, 0x18000
	s_add_i32 s28, 0, 0x1c000
	v_add_u32_e32 v142, s11, v211
	v_add_u32_e32 v158, s28, v211
	ds_read_b128 v[130:133], v142
	ds_read_b128 v[134:137], v142 offset:1024
	ds_read_b128 v[138:141], v142 offset:2048
	ds_read_b128 v[142:145], v142 offset:3072
	ds_read_b128 v[146:149], v158
	ds_read_b128 v[150:153], v158 offset:1024
	ds_read_b128 v[154:157], v158 offset:2048
	ds_read_b128 v[158:161], v158 offset:3072
	s_add_u32 s4, s92, 0x60000
	s_addc_u32 s5, s93, 0
	s_mov_b32 m0, s76
	v_lshl_add_u64 v[218:219], s[4:5], 0, v[196:197]
	ds_read_b128 v[162:165], v229 offset:32768
	ds_read_b128 v[166:169], v229 offset:33792
	ds_read_b128 v[170:173], v229 offset:34816
	ds_read_b128 v[174:177], v229 offset:35840
	ds_read_b128 v[178:181], v229 offset:36864
	ds_read_b128 v[182:185], v229 offset:37888
	ds_read_b128 v[186:189], v229 offset:38912
	ds_read_b128 v[190:193], v229 offset:39936
	global_load_lds_dwordx4 v[218:219], off
	v_lshl_add_u64 v[218:219], s[4:5], 0, v[198:199]
	s_mov_b32 m0, s77
	s_nop 0
	global_load_lds_dwordx4 v[218:219], off
	s_waitcnt vmcnt(8)
	s_waitcnt lgkmcnt(0)
	s_barrier
	s_waitcnt lgkmcnt(0)
	v_mfma_f32_16x16x32_bf16 v[126:129], v[130:133], v[162:165], v[126:129]
	v_mfma_f32_16x16x32_bf16 v[122:125], v[138:141], v[162:165], v[122:125]
	v_mfma_f32_16x16x32_bf16 v[110:113], v[130:133], v[170:173], v[110:113]
	v_mfma_f32_16x16x32_bf16 v[106:109], v[138:141], v[170:173], v[106:109]
	v_mfma_f32_16x16x32_bf16 v[94:97], v[130:133], v[178:181], v[94:97]
	v_mfma_f32_16x16x32_bf16 v[90:93], v[138:141], v[178:181], v[90:93]
	v_mfma_f32_16x16x32_bf16 v[78:81], v[130:133], v[186:189], v[78:81]
	v_mfma_f32_16x16x32_bf16 v[74:77], v[138:141], v[186:189], v[74:77]
	v_mfma_f32_16x16x32_bf16 v[126:129], v[134:137], v[166:169], v[126:129]
	v_mfma_f32_16x16x32_bf16 v[122:125], v[142:145], v[166:169], v[122:125]
	v_mfma_f32_16x16x32_bf16 v[110:113], v[134:137], v[174:177], v[110:113]
	v_mfma_f32_16x16x32_bf16 v[106:109], v[142:145], v[174:177], v[106:109]
	v_mfma_f32_16x16x32_bf16 v[94:97], v[134:137], v[182:185], v[94:97]
	v_mfma_f32_16x16x32_bf16 v[90:93], v[142:145], v[182:185], v[90:93]
	v_mfma_f32_16x16x32_bf16 v[78:81], v[134:137], v[190:193], v[78:81]
	v_mfma_f32_16x16x32_bf16 v[74:77], v[142:145], v[190:193], v[74:77]
	v_mfma_f32_16x16x32_bf16 v[118:121], v[146:149], v[162:165], v[118:121]
	v_mfma_f32_16x16x32_bf16 v[114:117], v[154:157], v[162:165], v[114:117]
	v_mfma_f32_16x16x32_bf16 v[102:105], v[146:149], v[170:173], v[102:105]
	v_mfma_f32_16x16x32_bf16 v[98:101], v[154:157], v[170:173], v[98:101]
	v_mfma_f32_16x16x32_bf16 v[86:89], v[146:149], v[178:181], v[86:89]
	v_mfma_f32_16x16x32_bf16 v[82:85], v[154:157], v[178:181], v[82:85]
	v_mfma_f32_16x16x32_bf16 v[70:73], v[146:149], v[186:189], v[70:73]
	v_mfma_f32_16x16x32_bf16 v[66:69], v[154:157], v[186:189], v[66:69]
	v_mfma_f32_16x16x32_bf16 v[118:121], v[150:153], v[166:169], v[118:121]
	v_mfma_f32_16x16x32_bf16 v[114:117], v[158:161], v[166:169], v[114:117]
	v_mfma_f32_16x16x32_bf16 v[102:105], v[150:153], v[174:177], v[102:105]
	v_mfma_f32_16x16x32_bf16 v[98:101], v[158:161], v[174:177], v[98:101]
	v_mfma_f32_16x16x32_bf16 v[86:89], v[150:153], v[182:185], v[86:89]
	v_mfma_f32_16x16x32_bf16 v[82:85], v[158:161], v[182:185], v[82:85]
	v_mfma_f32_16x16x32_bf16 v[70:73], v[150:153], v[190:193], v[70:73]
	v_mfma_f32_16x16x32_bf16 v[66:69], v[158:161], v[190:193], v[66:69]
	s_barrier
; #define PG8_STAGE(bufoff, gbase, voff) do { _Pragma("unroll") for (int _i = 0; _i < 2; ++_i) \
;         __builtin_amdgcn_global_load_lds((const unsigned*)((const char*)(gbase) + (voff)[_i]), (LAS unsigned*)(lds + (bufoff) + ldsw + _i * 8192), 16, 0, 0); } while (0)
; #define PG8_LDA(dst, b, h) do { _Pragma("unroll") for (int m = 0; m < 4; ++m) _Pragma("unroll") for (int k = 0; k < 2; ++k) dst[m][k] = *(const LAS bf16x8*)(lds + PG8_SA(b, h) + aoff + m * 2048 + k * 1024); } while (0)
; #define PG8_MMA(ai, bj, At, Bt) do { __builtin_amdgcn_s_setprio(1); _Pragma("unroll") for (int m = 0; m < 4; ++m) _Pragma("unroll") for (int n = 0; n < 2; ++n) _Pragma("unroll") for (int k = 0; k < 2; ++k) \
;         acc[ai][bj][m][n] = __builtin_amdgcn_mfma_f32_16x16x32_bf16(Bt[n][k], At[m][k], acc[ai][bj][m][n], 0, 0, 0); __builtin_amdgcn_s_setprio(0); } while (0)
; #define PG8_WAIT_V(n) asm volatile("s_waitcnt vmcnt(" #n ")" ::: "memory")
; #define PG8_WAIT_L(n) asm volatile("s_waitcnt lgkmcnt(" #n ")" ::: "memory")
; #define PG8_BAR __builtin_amdgcn_s_barrier()
; #define PG8_SCHED __builtin_amdgcn_sched_barrier(0)
; template <class EpiT, class Sched>
; __device__ __forceinline__ void gemm_phase(LAS unsigned char* lds, int tid_in, const GemmDesc g, const Sched& S, const EpiT& E) {
;     ...
;             PG8_LDA(At, 1, 1); PG8_STAGE(PG8_SB(1, 0), b3, voffB); PG8_STAGE(PG8_SB(1, 1), b3 + hB, voffB); PG8_STAGE(PG8_SA(1, 0), a3, voffA);
;             PG8_WAIT_V(8); PG8_WAIT_L(0); PG8_BAR; PG8_MMA(1, 0, At, B0); PG8_MMA(1, 1, At, B1); PG8_BAR; PG8_SCHED;
;         }
;         if (wr == 0) PG8_BAR;
	s_add_i32 s4, s11, s17
	v_lshl_add_u64 v[194:195], v[194:195], 0, s[60:61]
	s_mov_b32 m0, s4
	ds_read_b128 v[162:165], v229 offset:49152
	ds_read_b128 v[166:169], v229 offset:50176
	ds_read_b128 v[170:173], v229 offset:51200
	ds_read_b128 v[174:177], v229 offset:52224
	ds_read_b128 v[178:181], v229 offset:53248
	ds_read_b128 v[182:185], v229 offset:54272
	ds_read_b128 v[186:189], v229 offset:55296
	ds_read_b128 v[190:193], v229 offset:56320
	global_load_lds_dwordx4 v[194:195], off
	s_add_i32 m0, s4, 0x2000
	s_add_u32 s4, s88, 0x60080
	v_lshl_add_u64 v[194:195], v[206:207], 0, s[60:61]
	s_addc_u32 s5, s89, 0
	s_add_i32 s11, s28, s17
	global_load_lds_dwordx4 v[194:195], off
	v_lshl_add_u64 v[194:195], s[4:5], 0, v[0:1]
	s_mov_b32 m0, s11
	s_nop 0
	global_load_lds_dwordx4 v[194:195], off
	v_lshl_add_u64 v[194:195], s[4:5], 0, v[200:201]
	s_add_i32 m0, s11, 0x2000
	s_nop 0
	global_load_lds_dwordx4 v[194:195], off
	v_lshl_add_u64 v[194:195], v[208:209], 0, s[60:61]
	s_mov_b32 m0, s91
	s_nop 0
	global_load_lds_dwordx4 v[194:195], off
	v_lshl_add_u64 v[194:195], v[212:213], 0, s[60:61]
	s_mov_b32 m0, s94
	s_nop 0
	global_load_lds_dwordx4 v[194:195], off
	s_waitcnt vmcnt(8)
	s_waitcnt lgkmcnt(0)
	s_barrier
	s_waitcnt lgkmcnt(0)
	v_mfma_f32_16x16x32_bf16 v[62:65], v[130:133], v[162:165], v[62:65]
	v_mfma_f32_16x16x32_bf16 v[58:61], v[138:141], v[162:165], v[58:61]
	v_mfma_f32_16x16x32_bf16 v[46:49], v[130:133], v[170:173], v[46:49]
	v_mfma_f32_16x16x32_bf16 v[42:45], v[138:141], v[170:173], v[42:45]
	v_mfma_f32_16x16x32_bf16 v[30:33], v[130:133], v[178:181], v[30:33]
	v_mfma_f32_16x16x32_bf16 v[26:29], v[138:141], v[178:181], v[26:29]
	v_mfma_f32_16x16x32_bf16 v[14:17], v[130:133], v[186:189], v[14:17]
	v_mfma_f32_16x16x32_bf16 v[10:13], v[138:141], v[186:189], v[10:13]
	v_mfma_f32_16x16x32_bf16 v[62:65], v[134:137], v[166:169], v[62:65]
	v_mfma_f32_16x16x32_bf16 v[58:61], v[142:145], v[166:169], v[58:61]
	v_mfma_f32_16x16x32_bf16 v[46:49], v[134:137], v[174:177], v[46:49]
	v_mfma_f32_16x16x32_bf16 v[42:45], v[142:145], v[174:177], v[42:45]
	v_mfma_f32_16x16x32_bf16 v[30:33], v[134:137], v[182:185], v[30:33]
	v_mfma_f32_16x16x32_bf16 v[26:29], v[142:145], v[182:185], v[26:29]
	v_mfma_f32_16x16x32_bf16 v[14:17], v[134:137], v[190:193], v[14:17]
	v_mfma_f32_16x16x32_bf16 v[10:13], v[142:145], v[190:193], v[10:13]
	v_mfma_f32_16x16x32_bf16 v[54:57], v[146:149], v[162:165], v[54:57]
	v_mfma_f32_16x16x32_bf16 v[50:53], v[154:157], v[162:165], v[50:53]
	v_mfma_f32_16x16x32_bf16 v[38:41], v[146:149], v[170:173], v[38:41]
	v_mfma_f32_16x16x32_bf16 v[34:37], v[154:157], v[170:173], v[34:37]
	v_mfma_f32_16x16x32_bf16 v[22:25], v[146:149], v[178:181], v[22:25]
	v_mfma_f32_16x16x32_bf16 v[18:21], v[154:157], v[178:181], v[18:21]
	v_mfma_f32_16x16x32_bf16 v[6:9], v[146:149], v[186:189], v[6:9]
	v_mfma_f32_16x16x32_bf16 v[2:5], v[154:157], v[186:189], v[2:5]
	v_mfma_f32_16x16x32_bf16 v[54:57], v[150:153], v[166:169], v[54:57]
	v_mfma_f32_16x16x32_bf16 v[50:53], v[158:161], v[166:169], v[50:53]
	v_mfma_f32_16x16x32_bf16 v[38:41], v[150:153], v[174:177], v[38:41]
	v_mfma_f32_16x16x32_bf16 v[34:37], v[158:161], v[174:177], v[34:37]
	v_mfma_f32_16x16x32_bf16 v[22:25], v[150:153], v[182:185], v[22:25]
	v_mfma_f32_16x16x32_bf16 v[18:21], v[158:161], v[182:185], v[18:21]
	v_mfma_f32_16x16x32_bf16 v[6:9], v[150:153], v[190:193], v[6:9]
	v_mfma_f32_16x16x32_bf16 v[2:5], v[158:161], v[190:193], v[2:5]
	s_barrier
	s_add_i32 s10, s10, 2
	s_add_u32 s62, s62, 0x100
	s_addc_u32 s63, s63, 0
	s_cmp_gt_u32 s10, 5
	s_mov_b64 s[4:5], s[86:87]
	s_cbranch_scc0 .LBB0_1025
	s_and_b64 vcc, exec, s[12:13]
	s_cbranch_vccz .LBB0_1028
	s_barrier

; #define PG8_STAGE(bufoff, gbase, voff) do { _Pragma("unroll") for (int _i = 0; _i < 2; ++_i) \
;         __builtin_amdgcn_global_load_lds((const unsigned*)((const char*)(gbase) + (voff)[_i]), (LAS unsigned*)(lds + (bufoff) + ldsw + _i * 8192), 16, 0, 0); } while (0)
; #define PG8_LDA(dst, b, h) do { _Pragma("unroll") for (int m = 0; m < 4; ++m) _Pragma("unroll") for (int k = 0; k < 2; ++k) dst[m][k] = *(const LAS bf16x8*)(lds + PG8_SA(b, h) + aoff + m * 2048 + k * 1024); } while (0)
; #define PG8_LDB(dst, b, h) do { _Pragma("unroll") for (int n = 0; n < 2; ++n) _Pragma("unroll") for (int k = 0; k < 2; ++k) dst[n][k] = *(const LAS bf16x8*)(lds + PG8_SB(b, h) + boff + n * 2048 + k * 1024); } while (0)
; #define PG8_MMA(ai, bj, At, Bt) do { __builtin_amdgcn_s_setprio(1); _Pragma("unroll") for (int m = 0; m < 4; ++m) _Pragma("unroll") for (int n = 0; n < 2; ++n) _Pragma("unroll") for (int k = 0; k < 2; ++k) \
;         acc[ai][bj][m][n] = __builtin_amdgcn_mfma_f32_16x16x32_bf16(Bt[n][k], At[m][k], acc[ai][bj][m][n], 0, 0, 0); __builtin_amdgcn_s_setprio(0); } while (0)
; #define PG8_WAIT_V(n) asm volatile("s_waitcnt vmcnt(" #n ")" ::: "memory")
; #define PG8_WAIT_L(n) asm volatile("s_waitcnt lgkmcnt(" #n ")" ::: "memory")
; #define PG8_BAR __builtin_amdgcn_s_barrier()
; #define PG8_SCHED __builtin_amdgcn_sched_barrier(0)
; template <class EpiT, class Sched>
; __device__ __forceinline__ void gemm_phase(LAS unsigned char* lds, int tid_in, const GemmDesc g, const Sched& S, const EpiT& E) {
;     ...
;             const bool last = (t == nt - 2);
;             const char* a1 = cA + (size_t)(t + 1) * kA;
;             const char* a2 = last ? nA : cA + (size_t)(t + 2) * kA; const char* b2 = last ? nB : cB + (size_t)(t + 2) * kB;
;             const char* a3 = a2 + kA; const char* b3 = b2 + kB;
;             PG8_LDB(B0, 0, 0); PG8_LDB(B1, 0, 1); PG8_SCHED; PG8_LDA(At, 0, 0); PG8_STAGE(PG8_SA(1, 1), a1 + hA, voffA);
;             PG8_WAIT_V(8); PG8_WAIT_L(0); PG8_BAR; PG8_MMA(0, 0, At, B0); PG8_MMA(0, 1, At, B1); PG8_BAR; PG8_SCHED;
;             PG8_LDA(At, 0, 1); PG8_STAGE(PG8_SB(0, 0), b2, voffB); PG8_STAGE(PG8_SB(0, 1), b2 + hB, voffB); PG8_STAGE(PG8_SA(0, 0), a2, voffA);
.LBB0_1135:
	s_add_u32 s10, vcc_lo, 0xfffc0080
	s_addc_u32 s11, vcc_hi, -1
	s_add_i32 s28, 0, 0x10000
	s_cmp_eq_u32 s62, 12
	s_cselect_b32 s89, s2, s11
	s_cselect_b32 s88, s3, s10
	s_cselect_b32 s87, s31, s81
	s_cselect_b32 s86, s35, s59
	s_add_i32 s29, 0, 0x14000
	v_add_u32_e32 v156, s28, v141
	v_add_u32_e32 v172, s29, v141
	ds_read_b128 v[144:147], v156
	ds_read_b128 v[148:151], v156 offset:1024
	ds_read_b128 v[152:155], v156 offset:2048
	ds_read_b128 v[156:159], v156 offset:3072
	ds_read_b128 v[160:163], v172
	ds_read_b128 v[164:167], v172 offset:1024
	ds_read_b128 v[168:171], v172 offset:2048
	ds_read_b128 v[172:175], v172 offset:3072
	v_lshl_add_u64 v[208:209], vcc, 0, v[136:137]
	s_add_i32 m0, s25, 0xc000
	ds_read_b128 v[176:179], v143
	ds_read_b128 v[180:183], v143 offset:1024
	ds_read_b128 v[184:187], v143 offset:2048
	ds_read_b128 v[188:191], v143 offset:3072
	ds_read_b128 v[192:195], v143 offset:4096
	ds_read_b128 v[196:199], v143 offset:5120
	ds_read_b128 v[200:203], v143 offset:6144
	ds_read_b128 v[204:207], v143 offset:7168
	global_load_lds_dwordx4 v[208:209], off
	v_lshl_add_u64 v[208:209], vcc, 0, v[138:139]
	s_add_i32 m0, s25, 0xe000
	s_nop 0
	global_load_lds_dwordx4 v[208:209], off
	s_waitcnt vmcnt(8)
	s_waitcnt lgkmcnt(0)
	s_barrier
	s_waitcnt lgkmcnt(0)
	v_mfma_f32_16x16x32_bf16 v[126:129], v[144:147], v[176:179], v[126:129]
	v_mfma_f32_16x16x32_bf16 v[122:125], v[152:155], v[176:179], v[122:125]
	v_mfma_f32_16x16x32_bf16 v[118:121], v[144:147], v[184:187], v[118:121]
	v_mfma_f32_16x16x32_bf16 v[114:117], v[152:155], v[184:187], v[114:117]
	v_mfma_f32_16x16x32_bf16 v[102:105], v[144:147], v[192:195], v[102:105]
	v_mfma_f32_16x16x32_bf16 v[98:101], v[152:155], v[192:195], v[98:101]
	v_mfma_f32_16x16x32_bf16 v[86:89], v[144:147], v[200:203], v[86:89]
	v_mfma_f32_16x16x32_bf16 v[82:85], v[152:155], v[200:203], v[82:85]
	v_mfma_f32_16x16x32_bf16 v[126:129], v[148:151], v[180:183], v[126:129]
	v_mfma_f32_16x16x32_bf16 v[122:125], v[156:159], v[180:183], v[122:125]
	v_mfma_f32_16x16x32_bf16 v[118:121], v[148:151], v[188:191], v[118:121]
	v_mfma_f32_16x16x32_bf16 v[114:117], v[156:159], v[188:191], v[114:117]
	v_mfma_f32_16x16x32_bf16 v[102:105], v[148:151], v[196:199], v[102:105]
	v_mfma_f32_16x16x32_bf16 v[98:101], v[156:159], v[196:199], v[98:101]
	v_mfma_f32_16x16x32_bf16 v[86:89], v[148:151], v[204:207], v[86:89]
	v_mfma_f32_16x16x32_bf16 v[82:85], v[156:159], v[204:207], v[82:85]
	v_mfma_f32_16x16x32_bf16 v[110:113], v[160:163], v[176:179], v[110:113]
	v_mfma_f32_16x16x32_bf16 v[106:109], v[168:171], v[176:179], v[106:109]
	v_mfma_f32_16x16x32_bf16 v[94:97], v[160:163], v[184:187], v[94:97]
	v_mfma_f32_16x16x32_bf16 v[90:93], v[168:171], v[184:187], v[90:93]
	v_mfma_f32_16x16x32_bf16 v[78:81], v[160:163], v[192:195], v[78:81]
	v_mfma_f32_16x16x32_bf16 v[74:77], v[168:171], v[192:195], v[74:77]
	v_mfma_f32_16x16x32_bf16 v[70:73], v[160:163], v[200:203], v[70:73]
	v_mfma_f32_16x16x32_bf16 v[66:69], v[168:171], v[200:203], v[66:69]
	v_mfma_f32_16x16x32_bf16 v[110:113], v[164:167], v[180:183], v[110:113]
	v_mfma_f32_16x16x32_bf16 v[106:109], v[172:175], v[180:183], v[106:109]
	v_mfma_f32_16x16x32_bf16 v[94:97], v[164:167], v[188:191], v[94:97]
	v_mfma_f32_16x16x32_bf16 v[90:93], v[172:175], v[188:191], v[90:93]
	v_mfma_f32_16x16x32_bf16 v[78:81], v[164:167], v[196:199], v[78:81]
	v_mfma_f32_16x16x32_bf16 v[74:77], v[172:175], v[196:199], v[74:77]
	v_mfma_f32_16x16x32_bf16 v[70:73], v[164:167], v[204:207], v[70:73]
	v_mfma_f32_16x16x32_bf16 v[66:69], v[172:175], v[204:207], v[66:69]
	s_barrier
	s_add_i32 s10, s28, s72
	v_lshl_add_u64 v[208:209], s[86:87], 0, v[0:1]
	s_mov_b32 m0, s10
	ds_read_b128 v[176:179], v143 offset:16384
	ds_read_b128 v[180:183], v143 offset:17408
	ds_read_b128 v[184:187], v143 offset:18432
	ds_read_b128 v[188:191], v143 offset:19456
	ds_read_b128 v[192:195], v143 offset:20480
	ds_read_b128 v[196:199], v143 offset:21504
	ds_read_b128 v[200:203], v143 offset:22528
	ds_read_b128 v[204:207], v143 offset:23552
	global_load_lds_dwordx4 v[208:209], off
	s_add_i32 m0, s10, 0x2000
	s_add_u32 s10, s86, 0x40000
	v_lshl_add_u64 v[210:211], s[86:87], 0, v[134:135]
	s_addc_u32 s11, s87, 0
	s_add_i32 s28, s29, s72
	global_load_lds_dwordx4 v[210:211], off
	v_lshl_add_u64 v[212:213], s[10:11], 0, v[0:1]
	s_mov_b32 m0, s28
	v_lshl_add_u64 v[218:219], s[88:89], 0, v[132:133]
	global_load_lds_dwordx4 v[212:213], off
	v_lshl_add_u64 v[212:213], s[10:11], 0, v[134:135]
	s_add_i32 m0, s28, 0x2000
	s_nop 0
	global_load_lds_dwordx4 v[212:213], off
	v_lshl_add_u64 v[212:213], s[88:89], 0, v[130:131]
	s_mov_b32 m0, s25
	s_nop 0
	global_load_lds_dwordx4 v[212:213], off
	s_mov_b32 m0, s73
	s_nop 0
	global_load_lds_dwordx4 v[218:219], off
	s_waitcnt vmcnt(8)
	s_waitcnt lgkmcnt(0)
	s_barrier
; #define PG8_STAGE(bufoff, gbase, voff) do { _Pragma("unroll") for (int _i = 0; _i < 2; ++_i) \
;         __builtin_amdgcn_global_load_lds((const unsigned*)((const char*)(gbase) + (voff)[_i]), (LAS unsigned*)(lds + (bufoff) + ldsw + _i * 8192), 16, 0, 0); } while (0)
; #define PG8_LDA(dst, b, h) do { _Pragma("unroll") for (int m = 0; m < 4; ++m) _Pragma("unroll") for (int k = 0; k < 2; ++k) dst[m][k] = *(const LAS bf16x8*)(lds + PG8_SA(b, h) + aoff + m * 2048 + k * 1024); } while (0)
; #define PG8_LDB(dst, b, h) do { _Pragma("unroll") for (int n = 0; n < 2; ++n) _Pragma("unroll") for (int k = 0; k < 2; ++k) dst[n][k] = *(const LAS bf16x8*)(lds + PG8_SB(b, h) + boff + n * 2048 + k * 1024); } while (0)
; #define PG8_MMA(ai, bj, At, Bt) do { __builtin_amdgcn_s_setprio(1); _Pragma("unroll") for (int m = 0; m < 4; ++m) _Pragma("unroll") for (int n = 0; n < 2; ++n) _Pragma("unroll") for (int k = 0; k < 2; ++k) \
;         acc[ai][bj][m][n] = __builtin_amdgcn_mfma_f32_16x16x32_bf16(Bt[n][k], At[m][k], acc[ai][bj][m][n], 0, 0, 0); __builtin_amdgcn_s_setprio(0); } while (0)
; #define PG8_WAIT_V(n) asm volatile("s_waitcnt vmcnt(" #n ")" ::: "memory")
; #define PG8_WAIT_L(n) asm volatile("s_waitcnt lgkmcnt(" #n ")" ::: "memory")
; #define PG8_BAR __builtin_amdgcn_s_barrier()
; #define PG8_SCHED __builtin_amdgcn_sched_barrier(0)
; template <class EpiT, class Sched>
; __device__ __forceinline__ void gemm_phase(LAS unsigned char* lds, int tid_in, const GemmDesc g, const Sched& S, const EpiT& E) {
;     ...
;             PG8_WAIT_V(8); PG8_WAIT_L(0); PG8_BAR; PG8_MMA(1, 0, At, B0); PG8_MMA(1, 1, At, B1); PG8_BAR; PG8_SCHED;
;             PG8_LDB(B0, 1, 0); PG8_LDB(B1, 1, 1); PG8_SCHED; PG8_LDA(At, 1, 0); PG8_STAGE(PG8_SA(0, 1), a2 + hA, voffA);
;             PG8_WAIT_V(8); PG8_WAIT_L(0); PG8_BAR; PG8_MMA(0, 0, At, B0); PG8_MMA(0, 1, At, B1); PG8_BAR; PG8_SCHED;
	s_waitcnt lgkmcnt(0)
	v_mfma_f32_16x16x32_bf16 v[62:65], v[144:147], v[176:179], v[62:65]
	v_mfma_f32_16x16x32_bf16 v[58:61], v[152:155], v[176:179], v[58:61]
	v_mfma_f32_16x16x32_bf16 v[54:57], v[144:147], v[184:187], v[54:57]
	v_mfma_f32_16x16x32_bf16 v[50:53], v[152:155], v[184:187], v[50:53]
	v_mfma_f32_16x16x32_bf16 v[38:41], v[144:147], v[192:195], v[38:41]
	v_mfma_f32_16x16x32_bf16 v[34:37], v[152:155], v[192:195], v[34:37]
	v_mfma_f32_16x16x32_bf16 v[22:25], v[144:147], v[200:203], v[22:25]
	v_mfma_f32_16x16x32_bf16 v[18:21], v[152:155], v[200:203], v[18:21]
	v_mfma_f32_16x16x32_bf16 v[62:65], v[148:151], v[180:183], v[62:65]
	v_mfma_f32_16x16x32_bf16 v[58:61], v[156:159], v[180:183], v[58:61]
	v_mfma_f32_16x16x32_bf16 v[54:57], v[148:151], v[188:191], v[54:57]
	v_mfma_f32_16x16x32_bf16 v[50:53], v[156:159], v[188:191], v[50:53]
	v_mfma_f32_16x16x32_bf16 v[38:41], v[148:151], v[196:199], v[38:41]
	v_mfma_f32_16x16x32_bf16 v[34:37], v[156:159], v[196:199], v[34:37]
	v_mfma_f32_16x16x32_bf16 v[22:25], v[148:151], v[204:207], v[22:25]
	v_mfma_f32_16x16x32_bf16 v[18:21], v[156:159], v[204:207], v[18:21]
	v_mfma_f32_16x16x32_bf16 v[46:49], v[160:163], v[176:179], v[46:49]
	v_mfma_f32_16x16x32_bf16 v[42:45], v[168:171], v[176:179], v[42:45]
	v_mfma_f32_16x16x32_bf16 v[30:33], v[160:163], v[184:187], v[30:33]
	v_mfma_f32_16x16x32_bf16 v[26:29], v[168:171], v[184:187], v[26:29]
	v_mfma_f32_16x16x32_bf16 v[14:17], v[160:163], v[192:195], v[14:17]
	v_mfma_f32_16x16x32_bf16 v[10:13], v[168:171], v[192:195], v[10:13]
	v_mfma_f32_16x16x32_bf16 v[6:9], v[160:163], v[200:203], v[6:9]
	v_mfma_f32_16x16x32_bf16 v[2:5], v[168:171], v[200:203], v[2:5]
	v_mfma_f32_16x16x32_bf16 v[46:49], v[164:167], v[180:183], v[46:49]
	v_mfma_f32_16x16x32_bf16 v[42:45], v[172:175], v[180:183], v[42:45]
	v_mfma_f32_16x16x32_bf16 v[30:33], v[164:167], v[188:191], v[30:33]
	v_mfma_f32_16x16x32_bf16 v[26:29], v[172:175], v[188:191], v[26:29]
	v_mfma_f32_16x16x32_bf16 v[14:17], v[164:167], v[196:199], v[14:17]
	v_mfma_f32_16x16x32_bf16 v[10:13], v[172:175], v[196:199], v[10:13]
	v_mfma_f32_16x16x32_bf16 v[6:9], v[164:167], v[204:207], v[6:9]
	v_mfma_f32_16x16x32_bf16 v[2:5], v[172:175], v[204:207], v[2:5]
	s_barrier
	s_add_i32 s28, 0, 0x18000
	s_add_i32 s29, 0, 0x1c000
	v_add_u32_e32 v156, s28, v141
	v_add_u32_e32 v172, s29, v141
	ds_read_b128 v[144:147], v156
	ds_read_b128 v[148:151], v156 offset:1024
	ds_read_b128 v[152:155], v156 offset:2048
	ds_read_b128 v[156:159], v156 offset:3072
	ds_read_b128 v[160:163], v172
	ds_read_b128 v[164:167], v172 offset:1024
	ds_read_b128 v[168:171], v172 offset:2048
	ds_read_b128 v[172:175], v172 offset:3072
	s_add_u32 s10, s88, 0x40000
	s_addc_u32 s11, s89, 0
	s_mov_b32 m0, s74
	v_lshl_add_u64 v[220:221], s[10:11], 0, v[130:131]
	ds_read_b128 v[176:179], v143 offset:32768
	ds_read_b128 v[180:183], v143 offset:33792
	ds_read_b128 v[184:187], v143 offset:34816
	ds_read_b128 v[188:191], v143 offset:35840
	ds_read_b128 v[192:195], v143 offset:36864
	ds_read_b128 v[196:199], v143 offset:37888
	ds_read_b128 v[200:203], v143 offset:38912
	ds_read_b128 v[204:207], v143 offset:39936
	global_load_lds_dwordx4 v[220:221], off
	v_lshl_add_u64 v[220:221], s[10:11], 0, v[132:133]
	s_mov_b32 m0, s75
	s_nop 0
	global_load_lds_dwordx4 v[220:221], off
	s_waitcnt vmcnt(8)
	s_waitcnt lgkmcnt(0)
	s_barrier
	s_waitcnt lgkmcnt(0)
	v_mfma_f32_16x16x32_bf16 v[126:129], v[144:147], v[176:179], v[126:129]
	v_mfma_f32_16x16x32_bf16 v[122:125], v[152:155], v[176:179], v[122:125]
	v_mfma_f32_16x16x32_bf16 v[118:121], v[144:147], v[184:187], v[118:121]
	v_mfma_f32_16x16x32_bf16 v[114:117], v[152:155], v[184:187], v[114:117]
	v_mfma_f32_16x16x32_bf16 v[102:105], v[144:147], v[192:195], v[102:105]
	v_mfma_f32_16x16x32_bf16 v[98:101], v[152:155], v[192:195], v[98:101]
	v_mfma_f32_16x16x32_bf16 v[86:89], v[144:147], v[200:203], v[86:89]
	v_mfma_f32_16x16x32_bf16 v[82:85], v[152:155], v[200:203], v[82:85]
	v_mfma_f32_16x16x32_bf16 v[126:129], v[148:151], v[180:183], v[126:129]
	v_mfma_f32_16x16x32_bf16 v[122:125], v[156:159], v[180:183], v[122:125]
	v_mfma_f32_16x16x32_bf16 v[118:121], v[148:151], v[188:191], v[118:121]
	v_mfma_f32_16x16x32_bf16 v[114:117], v[156:159], v[188:191], v[114:117]
	v_mfma_f32_16x16x32_bf16 v[102:105], v[148:151], v[196:199], v[102:105]
	v_mfma_f32_16x16x32_bf16 v[98:101], v[156:159], v[196:199], v[98:101]
	v_mfma_f32_16x16x32_bf16 v[86:89], v[148:151], v[204:207], v[86:89]
	v_mfma_f32_16x16x32_bf16 v[82:85], v[156:159], v[204:207], v[82:85]
	v_mfma_f32_16x16x32_bf16 v[110:113], v[160:163], v[176:179], v[110:113]
	v_mfma_f32_16x16x32_bf16 v[106:109], v[168:171], v[176:179], v[106:109]
	v_mfma_f32_16x16x32_bf16 v[94:97], v[160:163], v[184:187], v[94:97]
	v_mfma_f32_16x16x32_bf16 v[90:93], v[168:171], v[184:187], v[90:93]
	v_mfma_f32_16x16x32_bf16 v[78:81], v[160:163], v[192:195], v[78:81]
	v_mfma_f32_16x16x32_bf16 v[74:77], v[168:171], v[192:195], v[74:77]
	v_mfma_f32_16x16x32_bf16 v[70:73], v[160:163], v[200:203], v[70:73]
	v_mfma_f32_16x16x32_bf16 v[66:69], v[168:171], v[200:203], v[66:69]
	v_mfma_f32_16x16x32_bf16 v[110:113], v[164:167], v[180:183], v[110:113]
	v_mfma_f32_16x16x32_bf16 v[106:109], v[172:175], v[180:183], v[106:109]
	v_mfma_f32_16x16x32_bf16 v[94:97], v[164:167], v[188:191], v[94:97]
	v_mfma_f32_16x16x32_bf16 v[90:93], v[172:175], v[188:191], v[90:93]
	v_mfma_f32_16x16x32_bf16 v[78:81], v[164:167], v[196:199], v[78:81]
	v_mfma_f32_16x16x32_bf16 v[74:77], v[172:175], v[196:199], v[74:77]
	v_mfma_f32_16x16x32_bf16 v[70:73], v[164:167], v[204:207], v[70:73]
	v_mfma_f32_16x16x32_bf16 v[66:69], v[172:175], v[204:207], v[66:69]
	s_barrier
; #define PG8_STAGE(bufoff, gbase, voff) do { _Pragma("unroll") for (int _i = 0; _i < 2; ++_i) \
;         __builtin_amdgcn_global_load_lds((const unsigned*)((const char*)(gbase) + (voff)[_i]), (LAS unsigned*)(lds + (bufoff) + ldsw + _i * 8192), 16, 0, 0); } while (0)
; #define PG8_LDA(dst, b, h) do { _Pragma("unroll") for (int m = 0; m < 4; ++m) _Pragma("unroll") for (int k = 0; k < 2; ++k) dst[m][k] = *(const LAS bf16x8*)(lds + PG8_SA(b, h) + aoff + m * 2048 + k * 1024); } while (0)
; #define PG8_MMA(ai, bj, At, Bt) do { __builtin_amdgcn_s_setprio(1); _Pragma("unroll") for (int m = 0; m < 4; ++m) _Pragma("unroll") for (int n = 0; n < 2; ++n) _Pragma("unroll") for (int k = 0; k < 2; ++k) \
;         acc[ai][bj][m][n] = __builtin_amdgcn_mfma_f32_16x16x32_bf16(Bt[n][k], At[m][k], acc[ai][bj][m][n], 0, 0, 0); __builtin_amdgcn_s_setprio(0); } while (0)
; #define PG8_WAIT_V(n) asm volatile("s_waitcnt vmcnt(" #n ")" ::: "memory")
; #define PG8_WAIT_L(n) asm volatile("s_waitcnt lgkmcnt(" #n ")" ::: "memory")
; #define PG8_BAR __builtin_amdgcn_s_barrier()
; #define PG8_SCHED __builtin_amdgcn_sched_barrier(0)
; template <class EpiT, class Sched>
; __device__ __forceinline__ void gemm_phase(LAS unsigned char* lds, int tid_in, const GemmDesc g, const Sched& S, const EpiT& E) {
;     ...
;             PG8_LDA(At, 1, 1); PG8_STAGE(PG8_SB(1, 0), b3, voffB); PG8_STAGE(PG8_SB(1, 1), b3 + hB, voffB); PG8_STAGE(PG8_SA(1, 0), a3, voffA);
;             PG8_WAIT_V(8); PG8_WAIT_L(0); PG8_BAR; PG8_MMA(1, 0, At, B0); PG8_MMA(1, 1, At, B1); PG8_BAR; PG8_SCHED;
;         }
;         if (wr == 0) PG8_BAR;
	s_add_i32 s10, s28, s72
	v_lshl_add_u64 v[208:209], v[208:209], 0, s[60:61]
	s_mov_b32 m0, s10
	ds_read_b128 v[176:179], v143 offset:49152
	ds_read_b128 v[180:183], v143 offset:50176
	ds_read_b128 v[184:187], v143 offset:51200
	ds_read_b128 v[188:191], v143 offset:52224
	ds_read_b128 v[192:195], v143 offset:53248
	ds_read_b128 v[196:199], v143 offset:54272
	ds_read_b128 v[200:203], v143 offset:55296
	ds_read_b128 v[204:207], v143 offset:56320
	global_load_lds_dwordx4 v[208:209], off
	s_add_i32 m0, s10, 0x2000
	s_add_u32 s10, s86, 0x40080
	v_lshl_add_u64 v[208:209], v[210:211], 0, s[60:61]
	s_addc_u32 s11, s87, 0
	s_add_i32 s28, s29, s72
	global_load_lds_dwordx4 v[208:209], off
	v_lshl_add_u64 v[208:209], s[10:11], 0, v[0:1]
	s_mov_b32 m0, s28
	s_nop 0
	global_load_lds_dwordx4 v[208:209], off
	v_lshl_add_u64 v[208:209], s[10:11], 0, v[134:135]
	s_add_i32 m0, s28, 0x2000
	s_nop 0
	global_load_lds_dwordx4 v[208:209], off
	v_lshl_add_u64 v[208:209], v[212:213], 0, s[60:61]
	s_mov_b32 m0, s58
	s_nop 0
	global_load_lds_dwordx4 v[208:209], off
	v_lshl_add_u64 v[208:209], v[218:219], 0, s[60:61]
	s_mov_b32 m0, s76
	s_nop 0
	global_load_lds_dwordx4 v[208:209], off
	s_waitcnt vmcnt(8)
	s_waitcnt lgkmcnt(0)
	s_barrier
	s_waitcnt lgkmcnt(0)
	v_mfma_f32_16x16x32_bf16 v[62:65], v[144:147], v[176:179], v[62:65]
	v_mfma_f32_16x16x32_bf16 v[58:61], v[152:155], v[176:179], v[58:61]
	v_mfma_f32_16x16x32_bf16 v[54:57], v[144:147], v[184:187], v[54:57]
	v_mfma_f32_16x16x32_bf16 v[50:53], v[152:155], v[184:187], v[50:53]
	v_mfma_f32_16x16x32_bf16 v[38:41], v[144:147], v[192:195], v[38:41]
	v_mfma_f32_16x16x32_bf16 v[34:37], v[152:155], v[192:195], v[34:37]
	v_mfma_f32_16x16x32_bf16 v[22:25], v[144:147], v[200:203], v[22:25]
	v_mfma_f32_16x16x32_bf16 v[18:21], v[152:155], v[200:203], v[18:21]
	v_mfma_f32_16x16x32_bf16 v[62:65], v[148:151], v[180:183], v[62:65]
	v_mfma_f32_16x16x32_bf16 v[58:61], v[156:159], v[180:183], v[58:61]
	v_mfma_f32_16x16x32_bf16 v[54:57], v[148:151], v[188:191], v[54:57]
	v_mfma_f32_16x16x32_bf16 v[50:53], v[156:159], v[188:191], v[50:53]
	v_mfma_f32_16x16x32_bf16 v[38:41], v[148:151], v[196:199], v[38:41]
	v_mfma_f32_16x16x32_bf16 v[34:37], v[156:159], v[196:199], v[34:37]
	v_mfma_f32_16x16x32_bf16 v[22:25], v[148:151], v[204:207], v[22:25]
	v_mfma_f32_16x16x32_bf16 v[18:21], v[156:159], v[204:207], v[18:21]
	v_mfma_f32_16x16x32_bf16 v[46:49], v[160:163], v[176:179], v[46:49]
	v_mfma_f32_16x16x32_bf16 v[42:45], v[168:171], v[176:179], v[42:45]
	v_mfma_f32_16x16x32_bf16 v[30:33], v[160:163], v[184:187], v[30:33]
	v_mfma_f32_16x16x32_bf16 v[26:29], v[168:171], v[184:187], v[26:29]
	v_mfma_f32_16x16x32_bf16 v[14:17], v[160:163], v[192:195], v[14:17]
	v_mfma_f32_16x16x32_bf16 v[10:13], v[168:171], v[192:195], v[10:13]
	v_mfma_f32_16x16x32_bf16 v[6:9], v[160:163], v[200:203], v[6:9]
	v_mfma_f32_16x16x32_bf16 v[2:5], v[168:171], v[200:203], v[2:5]
	v_mfma_f32_16x16x32_bf16 v[46:49], v[164:167], v[180:183], v[46:49]
	v_mfma_f32_16x16x32_bf16 v[42:45], v[172:175], v[180:183], v[42:45]
	v_mfma_f32_16x16x32_bf16 v[30:33], v[164:167], v[188:191], v[30:33]
	v_mfma_f32_16x16x32_bf16 v[26:29], v[172:175], v[188:191], v[26:29]
	v_mfma_f32_16x16x32_bf16 v[14:17], v[164:167], v[196:199], v[14:17]
	v_mfma_f32_16x16x32_bf16 v[10:13], v[172:175], v[196:199], v[10:13]
	v_mfma_f32_16x16x32_bf16 v[6:9], v[164:167], v[204:207], v[6:9]
	v_mfma_f32_16x16x32_bf16 v[2:5], v[172:175], v[204:207], v[2:5]
	s_barrier
	s_add_i32 s62, s62, 2
	s_add_u32 vcc_lo, vcc_lo, 0x100
	s_addc_u32 vcc_hi, vcc_hi, 0
	s_add_u32 s59, s59, 0x100
	s_addc_u32 s81, s81, 0
	s_cmp_gt_u32 s62, 13
	s_cbranch_scc0 .LBB0_1135
	s_and_b64 vcc, exec, s[22:23]
	s_cbranch_vccz .LBB0_1138
	s_barrier

; #define PG8_STAGE(bufoff, gbase, voff) do { _Pragma("unroll") for (int _i = 0; _i < 2; ++_i) \
;         __builtin_amdgcn_global_load_lds((const unsigned*)((const char*)(gbase) + (voff)[_i]), (LAS unsigned*)(lds + (bufoff) + ldsw + _i * 8192), 16, 0, 0); } while (0)
; #define PG8_LDA(dst, b, h) do { _Pragma("unroll") for (int m = 0; m < 4; ++m) _Pragma("unroll") for (int k = 0; k < 2; ++k) dst[m][k] = *(const LAS bf16x8*)(lds + PG8_SA(b, h) + aoff + m * 2048 + k * 1024); } while (0)
; #define PG8_LDB(dst, b, h) do { _Pragma("unroll") for (int n = 0; n < 2; ++n) _Pragma("unroll") for (int k = 0; k < 2; ++k) dst[n][k] = *(const LAS bf16x8*)(lds + PG8_SB(b, h) + boff + n * 2048 + k * 1024); } while (0)
; #define PG8_MMA(ai, bj, At, Bt) do { __builtin_amdgcn_s_setprio(1); _Pragma("unroll") for (int m = 0; m < 4; ++m) _Pragma("unroll") for (int n = 0; n < 2; ++n) _Pragma("unroll") for (int k = 0; k < 2; ++k) \
;         acc[ai][bj][m][n] = __builtin_amdgcn_mfma_f32_16x16x32_bf16(Bt[n][k], At[m][k], acc[ai][bj][m][n], 0, 0, 0); __builtin_amdgcn_s_setprio(0); } while (0)
; #define PG8_WAIT_V(n) asm volatile("s_waitcnt vmcnt(" #n ")" ::: "memory")
; #define PG8_WAIT_L(n) asm volatile("s_waitcnt lgkmcnt(" #n ")" ::: "memory")
; #define PG8_BAR __builtin_amdgcn_s_barrier()
; #define PG8_SCHED __builtin_amdgcn_sched_barrier(0)
; template <class EpiT, class Sched>
; __device__ __forceinline__ void gemm_phase(LAS unsigned char* lds, int tid_in, const GemmDesc g, const Sched& S, const EpiT& E) {
;     ...
;             const bool last = (t == nt - 2);
;             const char* a1 = cA + (size_t)(t + 1) * kA;
;             const char* a2 = last ? nA : cA + (size_t)(t + 2) * kA; const char* b2 = last ? nB : cB + (size_t)(t + 2) * kB;
;             const char* a3 = a2 + kA; const char* b3 = b2 + kB;
;             PG8_LDB(B0, 0, 0); PG8_LDB(B1, 0, 1); PG8_SCHED; PG8_LDA(At, 0, 0); PG8_STAGE(PG8_SA(1, 1), a1 + hA, voffA);
;             PG8_WAIT_V(8); PG8_WAIT_L(0); PG8_BAR; PG8_MMA(0, 0, At, B0); PG8_MMA(0, 1, At, B1); PG8_BAR; PG8_SCHED;
;             PG8_LDA(At, 0, 1); PG8_STAGE(PG8_SB(0, 0), b2, voffB); PG8_STAGE(PG8_SB(0, 1), b2 + hB, voffB); PG8_STAGE(PG8_SA(0, 0), a2, voffA);
.LBB0_1264:
	s_add_u32 s10, s90, 0xfffc0080
	s_addc_u32 s11, s91, -1
	s_add_i32 s28, 0, 0x10000
	s_cmp_eq_u32 s62, 12
	s_cselect_b32 s95, s2, s11
	s_cselect_b32 s94, s3, s10
	v_add_u32_e32 v140, s28, v143
	s_cselect_b32 s93, s35, s80
	s_cselect_b32 s92, s59, s79
	s_add_i32 s29, 0, 0x14000
	ds_read_b128 v[146:149], v140
	ds_read_b128 v[150:153], v140 offset:1024
	ds_read_b128 v[154:157], v140 offset:2048
	ds_read_b128 v[158:161], v140 offset:3072
	v_add_u32_e32 v140, s29, v143
	ds_read_b128 v[162:165], v140
	ds_read_b128 v[166:169], v140 offset:1024
	ds_read_b128 v[170:173], v140 offset:2048
	ds_read_b128 v[174:177], v140 offset:3072
	v_lshl_add_u64 v[140:141], s[90:91], 0, v[136:137]
	s_add_i32 m0, s76, 0xc000
	ds_read_b128 v[178:181], v145
	ds_read_b128 v[182:185], v145 offset:1024
	ds_read_b128 v[186:189], v145 offset:2048
	ds_read_b128 v[190:193], v145 offset:3072
	ds_read_b128 v[194:197], v145 offset:4096
	ds_read_b128 v[198:201], v145 offset:5120
	ds_read_b128 v[202:205], v145 offset:6144
	ds_read_b128 v[206:209], v145 offset:7168
	global_load_lds_dwordx4 v[140:141], off
	v_lshl_add_u64 v[140:141], s[90:91], 0, v[138:139]
	s_add_i32 m0, s76, 0xe000
	s_nop 0
	global_load_lds_dwordx4 v[140:141], off
	s_waitcnt vmcnt(8)
	s_waitcnt lgkmcnt(0)
	s_barrier
	s_waitcnt lgkmcnt(0)
	v_mfma_f32_16x16x32_bf16 v[126:129], v[146:149], v[178:181], v[126:129]
	v_mfma_f32_16x16x32_bf16 v[118:121], v[154:157], v[178:181], v[118:121]
	v_mfma_f32_16x16x32_bf16 v[110:113], v[146:149], v[186:189], v[110:113]
	v_mfma_f32_16x16x32_bf16 v[102:105], v[154:157], v[186:189], v[102:105]
	v_mfma_f32_16x16x32_bf16 v[94:97], v[146:149], v[194:197], v[94:97]
	v_mfma_f32_16x16x32_bf16 v[86:89], v[154:157], v[194:197], v[86:89]
	v_mfma_f32_16x16x32_bf16 v[78:81], v[146:149], v[202:205], v[78:81]
	v_mfma_f32_16x16x32_bf16 v[70:73], v[154:157], v[202:205], v[70:73]
	v_mfma_f32_16x16x32_bf16 v[126:129], v[150:153], v[182:185], v[126:129]
	v_mfma_f32_16x16x32_bf16 v[118:121], v[158:161], v[182:185], v[118:121]
	v_mfma_f32_16x16x32_bf16 v[110:113], v[150:153], v[190:193], v[110:113]
	v_mfma_f32_16x16x32_bf16 v[102:105], v[158:161], v[190:193], v[102:105]
	v_mfma_f32_16x16x32_bf16 v[94:97], v[150:153], v[198:201], v[94:97]
	v_mfma_f32_16x16x32_bf16 v[86:89], v[158:161], v[198:201], v[86:89]
	v_mfma_f32_16x16x32_bf16 v[78:81], v[150:153], v[206:209], v[78:81]
	v_mfma_f32_16x16x32_bf16 v[70:73], v[158:161], v[206:209], v[70:73]
	v_mfma_f32_16x16x32_bf16 v[122:125], v[162:165], v[178:181], v[122:125]
	v_mfma_f32_16x16x32_bf16 v[114:117], v[170:173], v[178:181], v[114:117]
	v_mfma_f32_16x16x32_bf16 v[106:109], v[162:165], v[186:189], v[106:109]
	v_mfma_f32_16x16x32_bf16 v[98:101], v[170:173], v[186:189], v[98:101]
	v_mfma_f32_16x16x32_bf16 v[90:93], v[162:165], v[194:197], v[90:93]
	v_mfma_f32_16x16x32_bf16 v[82:85], v[170:173], v[194:197], v[82:85]
	v_mfma_f32_16x16x32_bf16 v[74:77], v[162:165], v[202:205], v[74:77]
	v_mfma_f32_16x16x32_bf16 v[66:69], v[170:173], v[202:205], v[66:69]
	v_mfma_f32_16x16x32_bf16 v[122:125], v[166:169], v[182:185], v[122:125]
	v_mfma_f32_16x16x32_bf16 v[114:117], v[174:177], v[182:185], v[114:117]
	v_mfma_f32_16x16x32_bf16 v[106:109], v[166:169], v[190:193], v[106:109]
	v_mfma_f32_16x16x32_bf16 v[98:101], v[174:177], v[190:193], v[98:101]
	v_mfma_f32_16x16x32_bf16 v[90:93], v[166:169], v[198:201], v[90:93]
	v_mfma_f32_16x16x32_bf16 v[82:85], v[174:177], v[198:201], v[82:85]
	v_mfma_f32_16x16x32_bf16 v[74:77], v[166:169], v[206:209], v[74:77]
	v_mfma_f32_16x16x32_bf16 v[66:69], v[174:177], v[206:209], v[66:69]
	s_barrier
	s_add_i32 s10, s28, s74
	v_lshl_add_u64 v[140:141], s[92:93], 0, v[0:1]
	s_mov_b32 m0, s10
	ds_read_b128 v[178:181], v145 offset:16384
	ds_read_b128 v[182:185], v145 offset:17408
	ds_read_b128 v[186:189], v145 offset:18432
	ds_read_b128 v[190:193], v145 offset:19456
	ds_read_b128 v[194:197], v145 offset:20480
	ds_read_b128 v[198:201], v145 offset:21504
	ds_read_b128 v[202:205], v145 offset:22528
	ds_read_b128 v[206:209], v145 offset:23552
	global_load_lds_dwordx4 v[140:141], off
	s_add_i32 m0, s10, 0x2000
	s_add_u32 s10, s92, 0x40000
	v_lshl_add_u64 v[210:211], s[92:93], 0, v[130:131]
	s_addc_u32 s11, s93, 0
	s_add_i32 s28, s29, s74
	global_load_lds_dwordx4 v[210:211], off
	v_lshl_add_u64 v[212:213], s[10:11], 0, v[0:1]
	s_mov_b32 m0, s28
	v_lshl_add_u64 v[218:219], s[94:95], 0, v[132:133]
	global_load_lds_dwordx4 v[212:213], off
	v_lshl_add_u64 v[212:213], s[10:11], 0, v[130:131]
	s_add_i32 m0, s28, 0x2000
	s_nop 0
	global_load_lds_dwordx4 v[212:213], off
	v_lshl_add_u64 v[212:213], s[94:95], 0, v[134:135]
	s_mov_b32 m0, s76
	s_nop 0
	global_load_lds_dwordx4 v[212:213], off
	s_mov_b32 m0, s77
	s_nop 0
	global_load_lds_dwordx4 v[218:219], off
	s_waitcnt vmcnt(8)
	s_waitcnt lgkmcnt(0)
	s_barrier
; #define PG8_STAGE(bufoff, gbase, voff) do { _Pragma("unroll") for (int _i = 0; _i < 2; ++_i) \
;         __builtin_amdgcn_global_load_lds((const unsigned*)((const char*)(gbase) + (voff)[_i]), (LAS unsigned*)(lds + (bufoff) + ldsw + _i * 8192), 16, 0, 0); } while (0)
; #define PG8_LDA(dst, b, h) do { _Pragma("unroll") for (int m = 0; m < 4; ++m) _Pragma("unroll") for (int k = 0; k < 2; ++k) dst[m][k] = *(const LAS bf16x8*)(lds + PG8_SA(b, h) + aoff + m * 2048 + k * 1024); } while (0)
; #define PG8_LDB(dst, b, h) do { _Pragma("unroll") for (int n = 0; n < 2; ++n) _Pragma("unroll") for (int k = 0; k < 2; ++k) dst[n][k] = *(const LAS bf16x8*)(lds + PG8_SB(b, h) + boff + n * 2048 + k * 1024); } while (0)
; #define PG8_MMA(ai, bj, At, Bt) do { __builtin_amdgcn_s_setprio(1); _Pragma("unroll") for (int m = 0; m < 4; ++m) _Pragma("unroll") for (int n = 0; n < 2; ++n) _Pragma("unroll") for (int k = 0; k < 2; ++k) \
;         acc[ai][bj][m][n] = __builtin_amdgcn_mfma_f32_16x16x32_bf16(Bt[n][k], At[m][k], acc[ai][bj][m][n], 0, 0, 0); __builtin_amdgcn_s_setprio(0); } while (0)
; #define PG8_WAIT_V(n) asm volatile("s_waitcnt vmcnt(" #n ")" ::: "memory")
; #define PG8_WAIT_L(n) asm volatile("s_waitcnt lgkmcnt(" #n ")" ::: "memory")
; #define PG8_BAR __builtin_amdgcn_s_barrier()
; #define PG8_SCHED __builtin_amdgcn_sched_barrier(0)
; template <class EpiT, class Sched>
; __device__ __forceinline__ void gemm_phase(LAS unsigned char* lds, int tid_in, const GemmDesc g, const Sched& S, const EpiT& E) {
;     ...
;             PG8_WAIT_V(8); PG8_WAIT_L(0); PG8_BAR; PG8_MMA(1, 0, At, B0); PG8_MMA(1, 1, At, B1); PG8_BAR; PG8_SCHED;
;             PG8_LDB(B0, 1, 0); PG8_LDB(B1, 1, 1); PG8_SCHED; PG8_LDA(At, 1, 0); PG8_STAGE(PG8_SA(0, 1), a2 + hA, voffA);
;             PG8_WAIT_V(8); PG8_WAIT_L(0); PG8_BAR; PG8_MMA(0, 0, At, B0); PG8_MMA(0, 1, At, B1); PG8_BAR; PG8_SCHED;
	s_waitcnt lgkmcnt(0)
	v_mfma_f32_16x16x32_bf16 v[62:65], v[146:149], v[178:181], v[62:65]
	v_mfma_f32_16x16x32_bf16 v[54:57], v[154:157], v[178:181], v[54:57]
	v_mfma_f32_16x16x32_bf16 v[46:49], v[146:149], v[186:189], v[46:49]
	v_mfma_f32_16x16x32_bf16 v[38:41], v[154:157], v[186:189], v[38:41]
	v_mfma_f32_16x16x32_bf16 v[30:33], v[146:149], v[194:197], v[30:33]
	v_mfma_f32_16x16x32_bf16 v[22:25], v[154:157], v[194:197], v[22:25]
	v_mfma_f32_16x16x32_bf16 v[14:17], v[146:149], v[202:205], v[14:17]
	v_mfma_f32_16x16x32_bf16 v[6:9], v[154:157], v[202:205], v[6:9]
	v_mfma_f32_16x16x32_bf16 v[62:65], v[150:153], v[182:185], v[62:65]
	v_mfma_f32_16x16x32_bf16 v[54:57], v[158:161], v[182:185], v[54:57]
	v_mfma_f32_16x16x32_bf16 v[46:49], v[150:153], v[190:193], v[46:49]
	v_mfma_f32_16x16x32_bf16 v[38:41], v[158:161], v[190:193], v[38:41]
	v_mfma_f32_16x16x32_bf16 v[30:33], v[150:153], v[198:201], v[30:33]
	v_mfma_f32_16x16x32_bf16 v[22:25], v[158:161], v[198:201], v[22:25]
	v_mfma_f32_16x16x32_bf16 v[14:17], v[150:153], v[206:209], v[14:17]
	v_mfma_f32_16x16x32_bf16 v[6:9], v[158:161], v[206:209], v[6:9]
	v_mfma_f32_16x16x32_bf16 v[58:61], v[162:165], v[178:181], v[58:61]
	v_mfma_f32_16x16x32_bf16 v[50:53], v[170:173], v[178:181], v[50:53]
	v_mfma_f32_16x16x32_bf16 v[42:45], v[162:165], v[186:189], v[42:45]
	v_mfma_f32_16x16x32_bf16 v[34:37], v[170:173], v[186:189], v[34:37]
	v_mfma_f32_16x16x32_bf16 v[26:29], v[162:165], v[194:197], v[26:29]
	v_mfma_f32_16x16x32_bf16 v[18:21], v[170:173], v[194:197], v[18:21]
	v_mfma_f32_16x16x32_bf16 v[10:13], v[162:165], v[202:205], v[10:13]
	v_mfma_f32_16x16x32_bf16 v[2:5], v[170:173], v[202:205], v[2:5]
	v_mfma_f32_16x16x32_bf16 v[58:61], v[166:169], v[182:185], v[58:61]
	v_mfma_f32_16x16x32_bf16 v[50:53], v[174:177], v[182:185], v[50:53]
	v_mfma_f32_16x16x32_bf16 v[42:45], v[166:169], v[190:193], v[42:45]
	v_mfma_f32_16x16x32_bf16 v[34:37], v[174:177], v[190:193], v[34:37]
	v_mfma_f32_16x16x32_bf16 v[26:29], v[166:169], v[198:201], v[26:29]
	v_mfma_f32_16x16x32_bf16 v[18:21], v[174:177], v[198:201], v[18:21]
	v_mfma_f32_16x16x32_bf16 v[10:13], v[166:169], v[206:209], v[10:13]
	v_mfma_f32_16x16x32_bf16 v[2:5], v[174:177], v[206:209], v[2:5]
	s_barrier
	s_add_i32 s28, 0, 0x18000
	s_add_i32 s29, 0, 0x1c000
	v_add_u32_e32 v158, s28, v143
	v_add_u32_e32 v174, s29, v143
	ds_read_b128 v[146:149], v158
	ds_read_b128 v[150:153], v158 offset:1024
	ds_read_b128 v[154:157], v158 offset:2048
	ds_read_b128 v[158:161], v158 offset:3072
	ds_read_b128 v[162:165], v174
	ds_read_b128 v[166:169], v174 offset:1024
	ds_read_b128 v[170:173], v174 offset:2048
	ds_read_b128 v[174:177], v174 offset:3072
	s_add_u32 s10, s94, 0x40000
	s_addc_u32 s11, s95, 0
	s_mov_b32 m0, s89
	v_lshl_add_u64 v[220:221], s[10:11], 0, v[134:135]
	ds_read_b128 v[178:181], v145 offset:32768
	ds_read_b128 v[182:185], v145 offset:33792
	ds_read_b128 v[186:189], v145 offset:34816
	ds_read_b128 v[190:193], v145 offset:35840
	ds_read_b128 v[194:197], v145 offset:36864
	ds_read_b128 v[198:201], v145 offset:37888
	ds_read_b128 v[202:205], v145 offset:38912
	ds_read_b128 v[206:209], v145 offset:39936
	global_load_lds_dwordx4 v[220:221], off
	v_lshl_add_u64 v[220:221], s[10:11], 0, v[132:133]
	s_mov_b32 m0, s96
	s_nop 0
	global_load_lds_dwordx4 v[220:221], off
	s_waitcnt vmcnt(8)
	s_waitcnt lgkmcnt(0)
	s_barrier
	s_waitcnt lgkmcnt(0)
	v_mfma_f32_16x16x32_bf16 v[126:129], v[146:149], v[178:181], v[126:129]
	v_mfma_f32_16x16x32_bf16 v[118:121], v[154:157], v[178:181], v[118:121]
	v_mfma_f32_16x16x32_bf16 v[110:113], v[146:149], v[186:189], v[110:113]
	v_mfma_f32_16x16x32_bf16 v[102:105], v[154:157], v[186:189], v[102:105]
	v_mfma_f32_16x16x32_bf16 v[94:97], v[146:149], v[194:197], v[94:97]
	v_mfma_f32_16x16x32_bf16 v[86:89], v[154:157], v[194:197], v[86:89]
	v_mfma_f32_16x16x32_bf16 v[78:81], v[146:149], v[202:205], v[78:81]
	v_mfma_f32_16x16x32_bf16 v[70:73], v[154:157], v[202:205], v[70:73]
	v_mfma_f32_16x16x32_bf16 v[126:129], v[150:153], v[182:185], v[126:129]
	v_mfma_f32_16x16x32_bf16 v[118:121], v[158:161], v[182:185], v[118:121]
	v_mfma_f32_16x16x32_bf16 v[110:113], v[150:153], v[190:193], v[110:113]
	v_mfma_f32_16x16x32_bf16 v[102:105], v[158:161], v[190:193], v[102:105]
	v_mfma_f32_16x16x32_bf16 v[94:97], v[150:153], v[198:201], v[94:97]
	v_mfma_f32_16x16x32_bf16 v[86:89], v[158:161], v[198:201], v[86:89]
	v_mfma_f32_16x16x32_bf16 v[78:81], v[150:153], v[206:209], v[78:81]
	v_mfma_f32_16x16x32_bf16 v[70:73], v[158:161], v[206:209], v[70:73]
	v_mfma_f32_16x16x32_bf16 v[122:125], v[162:165], v[178:181], v[122:125]
	v_mfma_f32_16x16x32_bf16 v[114:117], v[170:173], v[178:181], v[114:117]
	v_mfma_f32_16x16x32_bf16 v[106:109], v[162:165], v[186:189], v[106:109]
	v_mfma_f32_16x16x32_bf16 v[98:101], v[170:173], v[186:189], v[98:101]
	v_mfma_f32_16x16x32_bf16 v[90:93], v[162:165], v[194:197], v[90:93]
	v_mfma_f32_16x16x32_bf16 v[82:85], v[170:173], v[194:197], v[82:85]
	v_mfma_f32_16x16x32_bf16 v[74:77], v[162:165], v[202:205], v[74:77]
	v_mfma_f32_16x16x32_bf16 v[66:69], v[170:173], v[202:205], v[66:69]
	v_mfma_f32_16x16x32_bf16 v[122:125], v[166:169], v[182:185], v[122:125]
	v_mfma_f32_16x16x32_bf16 v[114:117], v[174:177], v[182:185], v[114:117]
	v_mfma_f32_16x16x32_bf16 v[106:109], v[166:169], v[190:193], v[106:109]
	v_mfma_f32_16x16x32_bf16 v[98:101], v[174:177], v[190:193], v[98:101]
	v_mfma_f32_16x16x32_bf16 v[90:93], v[166:169], v[198:201], v[90:93]
	v_mfma_f32_16x16x32_bf16 v[82:85], v[174:177], v[198:201], v[82:85]
	v_mfma_f32_16x16x32_bf16 v[74:77], v[166:169], v[206:209], v[74:77]
	v_mfma_f32_16x16x32_bf16 v[66:69], v[174:177], v[206:209], v[66:69]
	s_barrier
; #define PG8_STAGE(bufoff, gbase, voff) do { _Pragma("unroll") for (int _i = 0; _i < 2; ++_i) \
;         __builtin_amdgcn_global_load_lds((const unsigned*)((const char*)(gbase) + (voff)[_i]), (LAS unsigned*)(lds + (bufoff) + ldsw + _i * 8192), 16, 0, 0); } while (0)
; #define PG8_LDA(dst, b, h) do { _Pragma("unroll") for (int m = 0; m < 4; ++m) _Pragma("unroll") for (int k = 0; k < 2; ++k) dst[m][k] = *(const LAS bf16x8*)(lds + PG8_SA(b, h) + aoff + m * 2048 + k * 1024); } while (0)
; #define PG8_MMA(ai, bj, At, Bt) do { __builtin_amdgcn_s_setprio(1); _Pragma("unroll") for (int m = 0; m < 4; ++m) _Pragma("unroll") for (int n = 0; n < 2; ++n) _Pragma("unroll") for (int k = 0; k < 2; ++k) \
;         acc[ai][bj][m][n] = __builtin_amdgcn_mfma_f32_16x16x32_bf16(Bt[n][k], At[m][k], acc[ai][bj][m][n], 0, 0, 0); __builtin_amdgcn_s_setprio(0); } while (0)
; #define PG8_WAIT_V(n) asm volatile("s_waitcnt vmcnt(" #n ")" ::: "memory")
; #define PG8_WAIT_L(n) asm volatile("s_waitcnt lgkmcnt(" #n ")" ::: "memory")
; #define PG8_BAR __builtin_amdgcn_s_barrier()
; #define PG8_SCHED __builtin_amdgcn_sched_barrier(0)
; template <class EpiT, class Sched>
; __device__ __forceinline__ void gemm_phase(LAS unsigned char* lds, int tid_in, const GemmDesc g, const Sched& S, const EpiT& E) {
;     ...
;             PG8_LDA(At, 1, 1); PG8_STAGE(PG8_SB(1, 0), b3, voffB); PG8_STAGE(PG8_SB(1, 1), b3 + hB, voffB); PG8_STAGE(PG8_SA(1, 0), a3, voffA);
;             PG8_WAIT_V(8); PG8_WAIT_L(0); PG8_BAR; PG8_MMA(1, 0, At, B0); PG8_MMA(1, 1, At, B1); PG8_BAR; PG8_SCHED;
;         }
;         if (wr == 0) PG8_BAR;
	s_add_i32 s10, s28, s74
	v_lshl_add_u64 v[140:141], v[140:141], 0, s[60:61]
	s_mov_b32 m0, s10
	ds_read_b128 v[178:181], v145 offset:49152
	ds_read_b128 v[182:185], v145 offset:50176
	ds_read_b128 v[186:189], v145 offset:51200
	ds_read_b128 v[190:193], v145 offset:52224
	ds_read_b128 v[194:197], v145 offset:53248
	ds_read_b128 v[198:201], v145 offset:54272
	ds_read_b128 v[202:205], v145 offset:55296
	ds_read_b128 v[206:209], v145 offset:56320
	global_load_lds_dwordx4 v[140:141], off
	s_add_i32 m0, s10, 0x2000
	s_add_u32 s10, s92, 0x40080
	v_lshl_add_u64 v[140:141], v[210:211], 0, s[60:61]
	s_addc_u32 s11, s93, 0
	s_add_i32 s28, s29, s74
	global_load_lds_dwordx4 v[140:141], off
	v_lshl_add_u64 v[140:141], s[10:11], 0, v[0:1]
	s_mov_b32 m0, s28
	s_nop 0
	global_load_lds_dwordx4 v[140:141], off
	v_lshl_add_u64 v[140:141], s[10:11], 0, v[130:131]
	s_add_i32 m0, s28, 0x2000
	s_nop 0
	global_load_lds_dwordx4 v[140:141], off
	v_lshl_add_u64 v[140:141], v[212:213], 0, s[60:61]
	s_mov_b32 m0, s97
	s_nop 0
	global_load_lds_dwordx4 v[140:141], off
	v_lshl_add_u64 v[140:141], v[218:219], 0, s[60:61]
	s_mov_b32 m0, s17
	s_nop 0
	global_load_lds_dwordx4 v[140:141], off
	s_waitcnt vmcnt(8)
	s_waitcnt lgkmcnt(0)
	s_barrier
	s_waitcnt lgkmcnt(0)
	v_mfma_f32_16x16x32_bf16 v[62:65], v[146:149], v[178:181], v[62:65]
	v_mfma_f32_16x16x32_bf16 v[54:57], v[154:157], v[178:181], v[54:57]
	v_mfma_f32_16x16x32_bf16 v[46:49], v[146:149], v[186:189], v[46:49]
	v_mfma_f32_16x16x32_bf16 v[38:41], v[154:157], v[186:189], v[38:41]
	v_mfma_f32_16x16x32_bf16 v[30:33], v[146:149], v[194:197], v[30:33]
	v_mfma_f32_16x16x32_bf16 v[22:25], v[154:157], v[194:197], v[22:25]
	v_mfma_f32_16x16x32_bf16 v[14:17], v[146:149], v[202:205], v[14:17]
	v_mfma_f32_16x16x32_bf16 v[6:9], v[154:157], v[202:205], v[6:9]
	v_mfma_f32_16x16x32_bf16 v[62:65], v[150:153], v[182:185], v[62:65]
	v_mfma_f32_16x16x32_bf16 v[54:57], v[158:161], v[182:185], v[54:57]
	v_mfma_f32_16x16x32_bf16 v[46:49], v[150:153], v[190:193], v[46:49]
	v_mfma_f32_16x16x32_bf16 v[38:41], v[158:161], v[190:193], v[38:41]
	v_mfma_f32_16x16x32_bf16 v[30:33], v[150:153], v[198:201], v[30:33]
	v_mfma_f32_16x16x32_bf16 v[22:25], v[158:161], v[198:201], v[22:25]
	v_mfma_f32_16x16x32_bf16 v[14:17], v[150:153], v[206:209], v[14:17]
	v_mfma_f32_16x16x32_bf16 v[6:9], v[158:161], v[206:209], v[6:9]
	v_mfma_f32_16x16x32_bf16 v[58:61], v[162:165], v[178:181], v[58:61]
	v_mfma_f32_16x16x32_bf16 v[50:53], v[170:173], v[178:181], v[50:53]
	v_mfma_f32_16x16x32_bf16 v[42:45], v[162:165], v[186:189], v[42:45]
	v_mfma_f32_16x16x32_bf16 v[34:37], v[170:173], v[186:189], v[34:37]
	v_mfma_f32_16x16x32_bf16 v[26:29], v[162:165], v[194:197], v[26:29]
	v_mfma_f32_16x16x32_bf16 v[18:21], v[170:173], v[194:197], v[18:21]
	v_mfma_f32_16x16x32_bf16 v[10:13], v[162:165], v[202:205], v[10:13]
	v_mfma_f32_16x16x32_bf16 v[2:5], v[170:173], v[202:205], v[2:5]
	v_mfma_f32_16x16x32_bf16 v[58:61], v[166:169], v[182:185], v[58:61]
	v_mfma_f32_16x16x32_bf16 v[50:53], v[174:177], v[182:185], v[50:53]
	v_mfma_f32_16x16x32_bf16 v[42:45], v[166:169], v[190:193], v[42:45]
	v_mfma_f32_16x16x32_bf16 v[34:37], v[174:177], v[190:193], v[34:37]
	v_mfma_f32_16x16x32_bf16 v[26:29], v[166:169], v[198:201], v[26:29]
	v_mfma_f32_16x16x32_bf16 v[18:21], v[174:177], v[198:201], v[18:21]
	v_mfma_f32_16x16x32_bf16 v[10:13], v[166:169], v[206:209], v[10:13]
	v_mfma_f32_16x16x32_bf16 v[2:5], v[174:177], v[206:209], v[2:5]
	s_barrier
	s_add_i32 s62, s62, 2
	s_add_u32 s90, s90, 0x100
	s_addc_u32 s91, s91, 0
	s_add_u32 s79, s79, 0x100
	s_addc_u32 s80, s80, 0
	s_cmp_gt_u32 s62, 13
	s_cbranch_scc0 .LBB0_1264
	s_and_b64 vcc, exec, s[30:31]
	s_cbranch_vccz .LBB0_1267
	s_barrier

; #define PG8_STAGE(bufoff, gbase, voff) do { _Pragma("unroll") for (int _i = 0; _i < 2; ++_i) \
;         __builtin_amdgcn_global_load_lds((const unsigned*)((const char*)(gbase) + (voff)[_i]), (LAS unsigned*)(lds + (bufoff) + ldsw + _i * 8192), 16, 0, 0); } while (0)
; #define PG8_LDA(dst, b, h) do { _Pragma("unroll") for (int m = 0; m < 4; ++m) _Pragma("unroll") for (int k = 0; k < 2; ++k) dst[m][k] = *(const LAS bf16x8*)(lds + PG8_SA(b, h) + aoff + m * 2048 + k * 1024); } while (0)
; #define PG8_LDB(dst, b, h) do { _Pragma("unroll") for (int n = 0; n < 2; ++n) _Pragma("unroll") for (int k = 0; k < 2; ++k) dst[n][k] = *(const LAS bf16x8*)(lds + PG8_SB(b, h) + boff + n * 2048 + k * 1024); } while (0)
; #define PG8_MMA(ai, bj, At, Bt) do { __builtin_amdgcn_s_setprio(1); _Pragma("unroll") for (int m = 0; m < 4; ++m) _Pragma("unroll") for (int n = 0; n < 2; ++n) _Pragma("unroll") for (int k = 0; k < 2; ++k) \
;         acc[ai][bj][m][n] = __builtin_amdgcn_mfma_f32_16x16x32_bf16(Bt[n][k], At[m][k], acc[ai][bj][m][n], 0, 0, 0); __builtin_amdgcn_s_setprio(0); } while (0)
; #define PG8_WAIT_V(n) asm volatile("s_waitcnt vmcnt(" #n ")" ::: "memory")
; #define PG8_WAIT_L(n) asm volatile("s_waitcnt lgkmcnt(" #n ")" ::: "memory")
; #define PG8_BAR __builtin_amdgcn_s_barrier()
; #define PG8_SCHED __builtin_amdgcn_sched_barrier(0)
; template <class EpiT, class Sched>
; __device__ __forceinline__ void gemm_phase(LAS unsigned char* lds, int tid_in, const GemmDesc g, const Sched& S, const EpiT& E) {
;     ...
;             const bool last = (t == nt - 2);
;             const char* a1 = cA + (size_t)(t + 1) * kA;
;             const char* a2 = last ? nA : cA + (size_t)(t + 2) * kA; const char* b2 = last ? nB : cB + (size_t)(t + 2) * kB;
;             const char* a3 = a2 + kA; const char* b3 = b2 + kB;
;             PG8_LDB(B0, 0, 0); PG8_LDB(B1, 0, 1); PG8_SCHED; PG8_LDA(At, 0, 0); PG8_STAGE(PG8_SA(1, 1), a1 + hA, voffA);
;             PG8_WAIT_V(8); PG8_WAIT_L(0); PG8_BAR; PG8_MMA(0, 0, At, B0); PG8_MMA(0, 1, At, B1); PG8_BAR; PG8_SCHED;
;             PG8_LDA(At, 0, 1); PG8_STAGE(PG8_SB(0, 0), b2, voffB); PG8_STAGE(PG8_SB(0, 1), b2 + hB, voffB); PG8_STAGE(PG8_SA(0, 0), a2, voffA);
.LBB0_1340:
	s_add_u32 s86, s82, 0x100
	s_addc_u32 s87, s83, 0
	s_add_i32 s11, 0, 0x10000
	s_cmp_eq_u32 s10, 40
	s_cselect_b32 s91, s2, s87
	s_cselect_b32 s90, s3, s86
	s_cselect_b32 s89, s59, s63
	s_cselect_b32 s88, s96, s62
	s_add_i32 s28, 0, 0x14000
	v_add_u32_e32 v156, s11, v141
	v_add_u32_e32 v172, s28, v141
	ds_read_b128 v[144:147], v156
	ds_read_b128 v[148:151], v156 offset:1024
	ds_read_b128 v[152:155], v156 offset:2048
	ds_read_b128 v[156:159], v156 offset:3072
	ds_read_b128 v[160:163], v172
	ds_read_b128 v[164:167], v172 offset:1024
	ds_read_b128 v[168:171], v172 offset:2048
	ds_read_b128 v[172:175], v172 offset:3072
	v_lshl_add_u64 v[208:209], s[82:83], 0, v[136:137]
	s_add_i32 m0, s74, 0xc000
	ds_read_b128 v[176:179], v143
	ds_read_b128 v[180:183], v143 offset:1024
	ds_read_b128 v[184:187], v143 offset:2048
	ds_read_b128 v[188:191], v143 offset:3072
	ds_read_b128 v[192:195], v143 offset:4096
	ds_read_b128 v[196:199], v143 offset:5120
	ds_read_b128 v[200:203], v143 offset:6144
	ds_read_b128 v[204:207], v143 offset:7168
	global_load_lds_dwordx4 v[208:209], off
	v_lshl_add_u64 v[208:209], s[82:83], 0, v[138:139]
	s_add_i32 m0, s74, 0xe000
	s_nop 0
	global_load_lds_dwordx4 v[208:209], off
	s_waitcnt vmcnt(8)
	s_waitcnt lgkmcnt(0)
	s_barrier
	s_waitcnt lgkmcnt(0)
	v_mfma_f32_16x16x32_bf16 v[126:129], v[144:147], v[176:179], v[126:129]
	v_mfma_f32_16x16x32_bf16 v[122:125], v[152:155], v[176:179], v[122:125]
	v_mfma_f32_16x16x32_bf16 v[118:121], v[144:147], v[184:187], v[118:121]
	v_mfma_f32_16x16x32_bf16 v[114:117], v[152:155], v[184:187], v[114:117]
	v_mfma_f32_16x16x32_bf16 v[102:105], v[144:147], v[192:195], v[102:105]
	v_mfma_f32_16x16x32_bf16 v[98:101], v[152:155], v[192:195], v[98:101]
	v_mfma_f32_16x16x32_bf16 v[86:89], v[144:147], v[200:203], v[86:89]
	v_mfma_f32_16x16x32_bf16 v[82:85], v[152:155], v[200:203], v[82:85]
	v_mfma_f32_16x16x32_bf16 v[126:129], v[148:151], v[180:183], v[126:129]
	v_mfma_f32_16x16x32_bf16 v[122:125], v[156:159], v[180:183], v[122:125]
	v_mfma_f32_16x16x32_bf16 v[118:121], v[148:151], v[188:191], v[118:121]
	v_mfma_f32_16x16x32_bf16 v[114:117], v[156:159], v[188:191], v[114:117]
	v_mfma_f32_16x16x32_bf16 v[102:105], v[148:151], v[196:199], v[102:105]
	v_mfma_f32_16x16x32_bf16 v[98:101], v[156:159], v[196:199], v[98:101]
	v_mfma_f32_16x16x32_bf16 v[86:89], v[148:151], v[204:207], v[86:89]
	v_mfma_f32_16x16x32_bf16 v[82:85], v[156:159], v[204:207], v[82:85]
	v_mfma_f32_16x16x32_bf16 v[110:113], v[160:163], v[176:179], v[110:113]
	v_mfma_f32_16x16x32_bf16 v[106:109], v[168:171], v[176:179], v[106:109]
	v_mfma_f32_16x16x32_bf16 v[94:97], v[160:163], v[184:187], v[94:97]
	v_mfma_f32_16x16x32_bf16 v[90:93], v[168:171], v[184:187], v[90:93]
	v_mfma_f32_16x16x32_bf16 v[78:81], v[160:163], v[192:195], v[78:81]
	v_mfma_f32_16x16x32_bf16 v[74:77], v[168:171], v[192:195], v[74:77]
	v_mfma_f32_16x16x32_bf16 v[70:73], v[160:163], v[200:203], v[70:73]
	v_mfma_f32_16x16x32_bf16 v[66:69], v[168:171], v[200:203], v[66:69]
	v_mfma_f32_16x16x32_bf16 v[110:113], v[164:167], v[180:183], v[110:113]
	v_mfma_f32_16x16x32_bf16 v[106:109], v[172:175], v[180:183], v[106:109]
	v_mfma_f32_16x16x32_bf16 v[94:97], v[164:167], v[188:191], v[94:97]
	v_mfma_f32_16x16x32_bf16 v[90:93], v[172:175], v[188:191], v[90:93]
	v_mfma_f32_16x16x32_bf16 v[78:81], v[164:167], v[196:199], v[78:81]
	v_mfma_f32_16x16x32_bf16 v[74:77], v[172:175], v[196:199], v[74:77]
	v_mfma_f32_16x16x32_bf16 v[70:73], v[164:167], v[204:207], v[70:73]
	v_mfma_f32_16x16x32_bf16 v[66:69], v[172:175], v[204:207], v[66:69]
	s_barrier
	s_add_i32 s11, s11, s73
	v_lshl_add_u64 v[208:209], s[88:89], 0, v[0:1]
	s_mov_b32 m0, s11
	ds_read_b128 v[176:179], v143 offset:16384
	ds_read_b128 v[180:183], v143 offset:17408
	ds_read_b128 v[184:187], v143 offset:18432
	ds_read_b128 v[188:191], v143 offset:19456
	ds_read_b128 v[192:195], v143 offset:20480
	ds_read_b128 v[196:199], v143 offset:21504
	ds_read_b128 v[200:203], v143 offset:22528
	ds_read_b128 v[204:207], v143 offset:23552
	global_load_lds_dwordx4 v[208:209], off
	s_add_i32 m0, s11, 0x2000
	s_add_u32 s82, s88, 0xb0000
	v_lshl_add_u64 v[210:211], s[88:89], 0, v[134:135]
	s_addc_u32 s83, s89, 0
	s_add_i32 s11, s28, s73
	global_load_lds_dwordx4 v[210:211], off
	v_lshl_add_u64 v[212:213], s[82:83], 0, v[0:1]
	s_mov_b32 m0, s11
	v_lshl_add_u64 v[218:219], s[90:91], 0, v[132:133]
	global_load_lds_dwordx4 v[212:213], off
	v_lshl_add_u64 v[212:213], s[82:83], 0, v[134:135]
	s_add_i32 m0, s11, 0x2000
	s_nop 0
	global_load_lds_dwordx4 v[212:213], off
	v_lshl_add_u64 v[212:213], s[90:91], 0, v[130:131]
	s_mov_b32 m0, s74
	s_nop 0
	global_load_lds_dwordx4 v[212:213], off
	s_mov_b32 m0, s75
	s_nop 0
	global_load_lds_dwordx4 v[218:219], off
	s_waitcnt vmcnt(8)
	s_waitcnt lgkmcnt(0)
	s_barrier
; #define PG8_STAGE(bufoff, gbase, voff) do { _Pragma("unroll") for (int _i = 0; _i < 2; ++_i) \
;         __builtin_amdgcn_global_load_lds((const unsigned*)((const char*)(gbase) + (voff)[_i]), (LAS unsigned*)(lds + (bufoff) + ldsw + _i * 8192), 16, 0, 0); } while (0)
; #define PG8_LDA(dst, b, h) do { _Pragma("unroll") for (int m = 0; m < 4; ++m) _Pragma("unroll") for (int k = 0; k < 2; ++k) dst[m][k] = *(const LAS bf16x8*)(lds + PG8_SA(b, h) + aoff + m * 2048 + k * 1024); } while (0)
; #define PG8_LDB(dst, b, h) do { _Pragma("unroll") for (int n = 0; n < 2; ++n) _Pragma("unroll") for (int k = 0; k < 2; ++k) dst[n][k] = *(const LAS bf16x8*)(lds + PG8_SB(b, h) + boff + n * 2048 + k * 1024); } while (0)
; #define PG8_MMA(ai, bj, At, Bt) do { __builtin_amdgcn_s_setprio(1); _Pragma("unroll") for (int m = 0; m < 4; ++m) _Pragma("unroll") for (int n = 0; n < 2; ++n) _Pragma("unroll") for (int k = 0; k < 2; ++k) \
;         acc[ai][bj][m][n] = __builtin_amdgcn_mfma_f32_16x16x32_bf16(Bt[n][k], At[m][k], acc[ai][bj][m][n], 0, 0, 0); __builtin_amdgcn_s_setprio(0); } while (0)
; #define PG8_WAIT_V(n) asm volatile("s_waitcnt vmcnt(" #n ")" ::: "memory")
; #define PG8_WAIT_L(n) asm volatile("s_waitcnt lgkmcnt(" #n ")" ::: "memory")
; #define PG8_BAR __builtin_amdgcn_s_barrier()
; #define PG8_SCHED __builtin_amdgcn_sched_barrier(0)
; template <class EpiT, class Sched>
; __device__ __forceinline__ void gemm_phase(LAS unsigned char* lds, int tid_in, const GemmDesc g, const Sched& S, const EpiT& E) {
;     ...
;             PG8_WAIT_V(8); PG8_WAIT_L(0); PG8_BAR; PG8_MMA(1, 0, At, B0); PG8_MMA(1, 1, At, B1); PG8_BAR; PG8_SCHED;
;             PG8_LDB(B0, 1, 0); PG8_LDB(B1, 1, 1); PG8_SCHED; PG8_LDA(At, 1, 0); PG8_STAGE(PG8_SA(0, 1), a2 + hA, voffA);
;             PG8_WAIT_V(8); PG8_WAIT_L(0); PG8_BAR; PG8_MMA(0, 0, At, B0); PG8_MMA(0, 1, At, B1); PG8_BAR; PG8_SCHED;
	s_waitcnt lgkmcnt(0)
	v_mfma_f32_16x16x32_bf16 v[62:65], v[144:147], v[176:179], v[62:65]
	v_mfma_f32_16x16x32_bf16 v[58:61], v[152:155], v[176:179], v[58:61]
	v_mfma_f32_16x16x32_bf16 v[54:57], v[144:147], v[184:187], v[54:57]
	v_mfma_f32_16x16x32_bf16 v[50:53], v[152:155], v[184:187], v[50:53]
	v_mfma_f32_16x16x32_bf16 v[38:41], v[144:147], v[192:195], v[38:41]
	v_mfma_f32_16x16x32_bf16 v[34:37], v[152:155], v[192:195], v[34:37]
	v_mfma_f32_16x16x32_bf16 v[22:25], v[144:147], v[200:203], v[22:25]
	v_mfma_f32_16x16x32_bf16 v[18:21], v[152:155], v[200:203], v[18:21]
	v_mfma_f32_16x16x32_bf16 v[62:65], v[148:151], v[180:183], v[62:65]
	v_mfma_f32_16x16x32_bf16 v[58:61], v[156:159], v[180:183], v[58:61]
	v_mfma_f32_16x16x32_bf16 v[54:57], v[148:151], v[188:191], v[54:57]
	v_mfma_f32_16x16x32_bf16 v[50:53], v[156:159], v[188:191], v[50:53]
	v_mfma_f32_16x16x32_bf16 v[38:41], v[148:151], v[196:199], v[38:41]
	v_mfma_f32_16x16x32_bf16 v[34:37], v[156:159], v[196:199], v[34:37]
	v_mfma_f32_16x16x32_bf16 v[22:25], v[148:151], v[204:207], v[22:25]
	v_mfma_f32_16x16x32_bf16 v[18:21], v[156:159], v[204:207], v[18:21]
	v_mfma_f32_16x16x32_bf16 v[46:49], v[160:163], v[176:179], v[46:49]
	v_mfma_f32_16x16x32_bf16 v[42:45], v[168:171], v[176:179], v[42:45]
	v_mfma_f32_16x16x32_bf16 v[30:33], v[160:163], v[184:187], v[30:33]
	v_mfma_f32_16x16x32_bf16 v[26:29], v[168:171], v[184:187], v[26:29]
	v_mfma_f32_16x16x32_bf16 v[14:17], v[160:163], v[192:195], v[14:17]
	v_mfma_f32_16x16x32_bf16 v[10:13], v[168:171], v[192:195], v[10:13]
	v_mfma_f32_16x16x32_bf16 v[6:9], v[160:163], v[200:203], v[6:9]
	v_mfma_f32_16x16x32_bf16 v[2:5], v[168:171], v[200:203], v[2:5]
	v_mfma_f32_16x16x32_bf16 v[46:49], v[164:167], v[180:183], v[46:49]
	v_mfma_f32_16x16x32_bf16 v[42:45], v[172:175], v[180:183], v[42:45]
	v_mfma_f32_16x16x32_bf16 v[30:33], v[164:167], v[188:191], v[30:33]
	v_mfma_f32_16x16x32_bf16 v[26:29], v[172:175], v[188:191], v[26:29]
	v_mfma_f32_16x16x32_bf16 v[14:17], v[164:167], v[196:199], v[14:17]
	v_mfma_f32_16x16x32_bf16 v[10:13], v[172:175], v[196:199], v[10:13]
	v_mfma_f32_16x16x32_bf16 v[6:9], v[164:167], v[204:207], v[6:9]
	v_mfma_f32_16x16x32_bf16 v[2:5], v[172:175], v[204:207], v[2:5]
	s_barrier
	s_add_i32 s11, 0, 0x18000
	s_add_i32 s28, 0, 0x1c000
	v_add_u32_e32 v156, s11, v141
	v_add_u32_e32 v172, s28, v141
	ds_read_b128 v[144:147], v156
	ds_read_b128 v[148:151], v156 offset:1024
	ds_read_b128 v[152:155], v156 offset:2048
	ds_read_b128 v[156:159], v156 offset:3072
	ds_read_b128 v[160:163], v172
	ds_read_b128 v[164:167], v172 offset:1024
	ds_read_b128 v[168:171], v172 offset:2048
	ds_read_b128 v[172:175], v172 offset:3072
	s_add_u32 s82, s90, 0xb0000
	s_addc_u32 s83, s91, 0
	s_mov_b32 m0, s76
	v_lshl_add_u64 v[220:221], s[82:83], 0, v[130:131]
	ds_read_b128 v[176:179], v143 offset:32768
	ds_read_b128 v[180:183], v143 offset:33792
	ds_read_b128 v[184:187], v143 offset:34816
	ds_read_b128 v[188:191], v143 offset:35840
	ds_read_b128 v[192:195], v143 offset:36864
	ds_read_b128 v[196:199], v143 offset:37888
	ds_read_b128 v[200:203], v143 offset:38912
	ds_read_b128 v[204:207], v143 offset:39936
	global_load_lds_dwordx4 v[220:221], off
	v_lshl_add_u64 v[220:221], s[82:83], 0, v[132:133]
	s_mov_b32 m0, s77
	s_nop 0
	global_load_lds_dwordx4 v[220:221], off
	s_waitcnt vmcnt(8)
	s_waitcnt lgkmcnt(0)
	s_barrier
	s_waitcnt lgkmcnt(0)
	v_mfma_f32_16x16x32_bf16 v[126:129], v[144:147], v[176:179], v[126:129]
	v_mfma_f32_16x16x32_bf16 v[122:125], v[152:155], v[176:179], v[122:125]
	v_mfma_f32_16x16x32_bf16 v[118:121], v[144:147], v[184:187], v[118:121]
	v_mfma_f32_16x16x32_bf16 v[114:117], v[152:155], v[184:187], v[114:117]
	v_mfma_f32_16x16x32_bf16 v[102:105], v[144:147], v[192:195], v[102:105]
	v_mfma_f32_16x16x32_bf16 v[98:101], v[152:155], v[192:195], v[98:101]
	v_mfma_f32_16x16x32_bf16 v[86:89], v[144:147], v[200:203], v[86:89]
	v_mfma_f32_16x16x32_bf16 v[82:85], v[152:155], v[200:203], v[82:85]
	v_mfma_f32_16x16x32_bf16 v[126:129], v[148:151], v[180:183], v[126:129]
	v_mfma_f32_16x16x32_bf16 v[122:125], v[156:159], v[180:183], v[122:125]
	v_mfma_f32_16x16x32_bf16 v[118:121], v[148:151], v[188:191], v[118:121]
	v_mfma_f32_16x16x32_bf16 v[114:117], v[156:159], v[188:191], v[114:117]
	v_mfma_f32_16x16x32_bf16 v[102:105], v[148:151], v[196:199], v[102:105]
	v_mfma_f32_16x16x32_bf16 v[98:101], v[156:159], v[196:199], v[98:101]
	v_mfma_f32_16x16x32_bf16 v[86:89], v[148:151], v[204:207], v[86:89]
	v_mfma_f32_16x16x32_bf16 v[82:85], v[156:159], v[204:207], v[82:85]
	v_mfma_f32_16x16x32_bf16 v[110:113], v[160:163], v[176:179], v[110:113]
	v_mfma_f32_16x16x32_bf16 v[106:109], v[168:171], v[176:179], v[106:109]
	v_mfma_f32_16x16x32_bf16 v[94:97], v[160:163], v[184:187], v[94:97]
	v_mfma_f32_16x16x32_bf16 v[90:93], v[168:171], v[184:187], v[90:93]
	v_mfma_f32_16x16x32_bf16 v[78:81], v[160:163], v[192:195], v[78:81]
	v_mfma_f32_16x16x32_bf16 v[74:77], v[168:171], v[192:195], v[74:77]
	v_mfma_f32_16x16x32_bf16 v[70:73], v[160:163], v[200:203], v[70:73]
	v_mfma_f32_16x16x32_bf16 v[66:69], v[168:171], v[200:203], v[66:69]
	v_mfma_f32_16x16x32_bf16 v[110:113], v[164:167], v[180:183], v[110:113]
	v_mfma_f32_16x16x32_bf16 v[106:109], v[172:175], v[180:183], v[106:109]
	v_mfma_f32_16x16x32_bf16 v[94:97], v[164:167], v[188:191], v[94:97]
	v_mfma_f32_16x16x32_bf16 v[90:93], v[172:175], v[188:191], v[90:93]
	v_mfma_f32_16x16x32_bf16 v[78:81], v[164:167], v[196:199], v[78:81]
	v_mfma_f32_16x16x32_bf16 v[74:77], v[172:175], v[196:199], v[74:77]
	v_mfma_f32_16x16x32_bf16 v[70:73], v[164:167], v[204:207], v[70:73]
	v_mfma_f32_16x16x32_bf16 v[66:69], v[172:175], v[204:207], v[66:69]
	s_barrier
; #define PG8_STAGE(bufoff, gbase, voff) do { _Pragma("unroll") for (int _i = 0; _i < 2; ++_i) \
;         __builtin_amdgcn_global_load_lds((const unsigned*)((const char*)(gbase) + (voff)[_i]), (LAS unsigned*)(lds + (bufoff) + ldsw + _i * 8192), 16, 0, 0); } while (0)
; #define PG8_LDA(dst, b, h) do { _Pragma("unroll") for (int m = 0; m < 4; ++m) _Pragma("unroll") for (int k = 0; k < 2; ++k) dst[m][k] = *(const LAS bf16x8*)(lds + PG8_SA(b, h) + aoff + m * 2048 + k * 1024); } while (0)
; #define PG8_MMA(ai, bj, At, Bt) do { __builtin_amdgcn_s_setprio(1); _Pragma("unroll") for (int m = 0; m < 4; ++m) _Pragma("unroll") for (int n = 0; n < 2; ++n) _Pragma("unroll") for (int k = 0; k < 2; ++k) \
;         acc[ai][bj][m][n] = __builtin_amdgcn_mfma_f32_16x16x32_bf16(Bt[n][k], At[m][k], acc[ai][bj][m][n], 0, 0, 0); __builtin_amdgcn_s_setprio(0); } while (0)
; #define PG8_WAIT_V(n) asm volatile("s_waitcnt vmcnt(" #n ")" ::: "memory")
; #define PG8_WAIT_L(n) asm volatile("s_waitcnt lgkmcnt(" #n ")" ::: "memory")
; #define PG8_BAR __builtin_amdgcn_s_barrier()
; #define PG8_SCHED __builtin_amdgcn_sched_barrier(0)
; template <class EpiT, class Sched>
; __device__ __forceinline__ void gemm_phase(LAS unsigned char* lds, int tid_in, const GemmDesc g, const Sched& S, const EpiT& E) {
;     ...
;             PG8_LDA(At, 1, 1); PG8_STAGE(PG8_SB(1, 0), b3, voffB); PG8_STAGE(PG8_SB(1, 1), b3 + hB, voffB); PG8_STAGE(PG8_SA(1, 0), a3, voffA);
;             PG8_WAIT_V(8); PG8_WAIT_L(0); PG8_BAR; PG8_MMA(1, 0, At, B0); PG8_MMA(1, 1, At, B1); PG8_BAR; PG8_SCHED;
;         }
;         if (wr == 0) PG8_BAR;
	s_add_i32 s11, s11, s73
	v_lshl_add_u64 v[208:209], v[208:209], 0, s[60:61]
	s_mov_b32 m0, s11
	ds_read_b128 v[176:179], v143 offset:49152
	ds_read_b128 v[180:183], v143 offset:50176
	ds_read_b128 v[184:187], v143 offset:51200
	ds_read_b128 v[188:191], v143 offset:52224
	ds_read_b128 v[192:195], v143 offset:53248
	ds_read_b128 v[196:199], v143 offset:54272
	ds_read_b128 v[200:203], v143 offset:55296
	ds_read_b128 v[204:207], v143 offset:56320
	global_load_lds_dwordx4 v[208:209], off
	s_add_i32 m0, s11, 0x2000
	s_add_u32 s82, s88, 0xb0080
	v_lshl_add_u64 v[208:209], v[210:211], 0, s[60:61]
	s_addc_u32 s83, s89, 0
	s_add_i32 s11, s28, s73
	global_load_lds_dwordx4 v[208:209], off
	v_lshl_add_u64 v[208:209], s[82:83], 0, v[0:1]
	s_mov_b32 m0, s11
	s_nop 0
	global_load_lds_dwordx4 v[208:209], off
	v_lshl_add_u64 v[208:209], s[82:83], 0, v[134:135]
	s_add_i32 m0, s11, 0x2000
	s_nop 0
	global_load_lds_dwordx4 v[208:209], off
	v_lshl_add_u64 v[208:209], v[212:213], 0, s[60:61]
	s_mov_b32 m0, s58
	s_nop 0
	global_load_lds_dwordx4 v[208:209], off
	v_lshl_add_u64 v[208:209], v[218:219], 0, s[60:61]
	s_mov_b32 m0, s80
	s_nop 0
	global_load_lds_dwordx4 v[208:209], off
	s_waitcnt vmcnt(8)
	s_waitcnt lgkmcnt(0)
	s_barrier
	s_waitcnt lgkmcnt(0)
	v_mfma_f32_16x16x32_bf16 v[62:65], v[144:147], v[176:179], v[62:65]
	v_mfma_f32_16x16x32_bf16 v[58:61], v[152:155], v[176:179], v[58:61]
	v_mfma_f32_16x16x32_bf16 v[54:57], v[144:147], v[184:187], v[54:57]
	v_mfma_f32_16x16x32_bf16 v[50:53], v[152:155], v[184:187], v[50:53]
	v_mfma_f32_16x16x32_bf16 v[38:41], v[144:147], v[192:195], v[38:41]
	v_mfma_f32_16x16x32_bf16 v[34:37], v[152:155], v[192:195], v[34:37]
	v_mfma_f32_16x16x32_bf16 v[22:25], v[144:147], v[200:203], v[22:25]
	v_mfma_f32_16x16x32_bf16 v[18:21], v[152:155], v[200:203], v[18:21]
	v_mfma_f32_16x16x32_bf16 v[62:65], v[148:151], v[180:183], v[62:65]
	v_mfma_f32_16x16x32_bf16 v[58:61], v[156:159], v[180:183], v[58:61]
	v_mfma_f32_16x16x32_bf16 v[54:57], v[148:151], v[188:191], v[54:57]
	v_mfma_f32_16x16x32_bf16 v[50:53], v[156:159], v[188:191], v[50:53]
	v_mfma_f32_16x16x32_bf16 v[38:41], v[148:151], v[196:199], v[38:41]
	v_mfma_f32_16x16x32_bf16 v[34:37], v[156:159], v[196:199], v[34:37]
	v_mfma_f32_16x16x32_bf16 v[22:25], v[148:151], v[204:207], v[22:25]
	v_mfma_f32_16x16x32_bf16 v[18:21], v[156:159], v[204:207], v[18:21]
	v_mfma_f32_16x16x32_bf16 v[46:49], v[160:163], v[176:179], v[46:49]
	v_mfma_f32_16x16x32_bf16 v[42:45], v[168:171], v[176:179], v[42:45]
	v_mfma_f32_16x16x32_bf16 v[30:33], v[160:163], v[184:187], v[30:33]
	v_mfma_f32_16x16x32_bf16 v[26:29], v[168:171], v[184:187], v[26:29]
	v_mfma_f32_16x16x32_bf16 v[14:17], v[160:163], v[192:195], v[14:17]
	v_mfma_f32_16x16x32_bf16 v[10:13], v[168:171], v[192:195], v[10:13]
	v_mfma_f32_16x16x32_bf16 v[6:9], v[160:163], v[200:203], v[6:9]
	v_mfma_f32_16x16x32_bf16 v[2:5], v[168:171], v[200:203], v[2:5]
	v_mfma_f32_16x16x32_bf16 v[46:49], v[164:167], v[180:183], v[46:49]
	v_mfma_f32_16x16x32_bf16 v[42:45], v[172:175], v[180:183], v[42:45]
	v_mfma_f32_16x16x32_bf16 v[30:33], v[164:167], v[188:191], v[30:33]
	v_mfma_f32_16x16x32_bf16 v[26:29], v[172:175], v[188:191], v[26:29]
	v_mfma_f32_16x16x32_bf16 v[14:17], v[164:167], v[196:199], v[14:17]
	v_mfma_f32_16x16x32_bf16 v[10:13], v[172:175], v[196:199], v[10:13]
	v_mfma_f32_16x16x32_bf16 v[6:9], v[164:167], v[204:207], v[6:9]
	v_mfma_f32_16x16x32_bf16 v[2:5], v[172:175], v[204:207], v[2:5]
	s_barrier
	s_add_i32 s10, s10, 2
	s_add_u32 s62, s62, 0x100
	s_addc_u32 s63, s63, 0
	s_cmp_gt_u32 s10, 41
	s_mov_b64 s[82:83], s[86:87]
	s_cbranch_scc0 .LBB0_1340
	s_and_b64 vcc, exec, s[22:23]
	s_cbranch_vccz .LBB0_1343
	s_barrier
